# k11: k8 + lgkmcnt(0) moved before the barrier in GEMM MMA phases
# baseline (speedup 1.0000x reference)
; #define PG8_STAGE(bufoff, gbase, voff) do { _Pragma("unroll") for (int _i = 0; _i < 2; ++_i) \
;         __builtin_amdgcn_global_load_lds((const unsigned*)((const char*)(gbase) + (voff)[_i]), (LAS unsigned*)(lds + (bufoff) + ldsw + _i * 8192), 16, 0, 0); } while (0)
; #define PG8_LDA(dst, b, h) do { _Pragma("unroll") for (int m = 0; m < 4; ++m) _Pragma("unroll") for (int k = 0; k < 2; ++k) dst[m][k] = *(const LAS bf16x8*)(lds + PG8_SA(b, h) + aoff + m * 2048 + k * 1024); } while (0)
; #define PG8_LDB(dst, b, h) do { _Pragma("unroll") for (int n = 0; n < 2; ++n) _Pragma("unroll") for (int k = 0; k < 2; ++k) dst[n][k] = *(const LAS bf16x8*)(lds + PG8_SB(b, h) + boff + n * 2048 + k * 1024); } while (0)
; #define PG8_MMA(ai, bj, At, Bt) do { __builtin_amdgcn_s_setprio(1); _Pragma("unroll") for (int m = 0; m < 4; ++m) _Pragma("unroll") for (int n = 0; n < 2; ++n) _Pragma("unroll") for (int k = 0; k < 2; ++k) \
;         acc[ai][bj][m][n] = __builtin_amdgcn_mfma_f32_16x16x32_bf16(Bt[n][k], At[m][k], acc[ai][bj][m][n], 0, 0, 0); __builtin_amdgcn_s_setprio(0); } while (0)
; #define PG8_WAIT_L(n) asm volatile("s_waitcnt lgkmcnt(" #n ")" ::: "memory")
; #define PG8_BAR __builtin_amdgcn_s_barrier()
; #define PG8_SCHED __builtin_amdgcn_sched_barrier(0)
; template <class Epi>
; __device__ __forceinline__ void gemm_phase(LAS unsigned char* lds, const Gemm g, const Epi& E) {
;     ...
;         for (int t = 0; t < nt; t += 2) {
;             const bool last = (t == nt - 2);
;             const char* a1 = cA + (size_t)(t + 1) * kstep;
;             const char* a2 = last ? nA : cA + (size_t)(t + 2) * kstep; const char* b2 = last ? nB : cB + (size_t)(t + 2) * kstep;
;             const char* a3 = a2 + kstep; const char* b3 = b2 + kstep;
;             PG8_LDB(B0, 0, 0); PG8_SCHED; PG8_LDA(At, 0, 0); PG8_STAGE(PG8_SA(1, 1), a1 + hstepA, voffA);
;             PG8_WAIT_L(8); PG8_BAR; PG8_WAIT_L(0); PG8_MMA(0, 0, At, B0); PG8_BAR; PG8_SCHED;
;             PG8_LDB(B1, 0, 1); PG8_STAGE(PG8_SB(0, 0), b2, voffB);
;             PG8_BAR; PG8_WAIT_L(0); PG8_MMA(0, 1, At, B1); PG8_BAR;
;             PG8_LDA(At, 0, 1); PG8_STAGE(PG8_SA(0, 0), a2, voffA);
;             PG8_BAR; PG8_WAIT_L(0); PG8_MMA(1, 0, At, B0); PG8_BAR; PG8_SCHED;
.LBB0_296:
	s_add_u32 s9, s16, s5
	s_addc_u32 s18, s17, 0
	s_add_u32 s36, s9, 0x100
	s_addc_u32 s60, s18, 0
	s_and_b64 s[0:1], s[58:59], exec
	s_cselect_b32 s67, s11, s60
	s_cselect_b32 s66, s10, s36
	s_add_u32 s0, s14, s5
	s_addc_u32 s1, s15, 0
	s_add_u32 s5, s0, 0x100
	s_addc_u32 s36, s1, 0
	s_add_i32 s73, 0, 0x10000
	s_and_b64 s[0:1], s[58:59], exec
	s_cselect_b32 s75, s13, s36
	s_cselect_b32 s74, s12, s5
	s_add_u32 s78, s9, 0x40080
	s_addc_u32 s79, s18, 0
	s_add_i32 s72, s73, s30
	s_add_i32 m0, s26, 0xc000
	s_add_i32 s50, s26, 0xe000
	s_add_i32 s27, 0, 0x14000
	s_add_i32 s24, s72, 0x2000
	s_add_u32 s64, s74, 0x10000
	v_add_u32_e32 v142, s73, v159
	s_addc_u32 s65, s75, 0
	s_add_i32 s18, s27, s30
	ds_read_b128 v[130:133], v142
	ds_read_b128 v[134:137], v142 offset:1024
	ds_read_b128 v[138:141], v142 offset:2048
	ds_read_b128 v[142:145], v142 offset:3072
	s_add_i32 s36, s18, 0x2000
	s_add_i32 vcc_hi, 0, 0x18000
	s_add_u32 s60, s66, 0x40000
	s_addc_u32 s61, s67, 0
	s_add_i32 vcc_lo, vcc_hi, s30
	s_add_i32 s9, 0, 0x1c000
	s_add_i32 s5, vcc_lo, 0x2000
	s_add_u32 s58, s74, 0x10080
	s_addc_u32 s59, s75, 0
	s_add_i32 s0, s9, s30
	s_add_i32 s1, s0, 0x2000
	v_lshl_add_u64 v[192:193], s[78:79], 0, v[152:153]
	ds_read_b128 v[154:157], v160
	ds_read_b128 v[162:165], v160 offset:1024
	ds_read_b128 v[166:169], v160 offset:2048
	ds_read_b128 v[170:173], v160 offset:3072
	ds_read_b128 v[174:177], v160 offset:4096
	ds_read_b128 v[180:183], v160 offset:5120
	ds_read_b128 v[184:187], v160 offset:6144
	ds_read_b128 v[188:191], v160 offset:7168
	global_load_lds_dwordx4 v[192:193], off
	v_lshl_add_u64 v[192:193], s[78:79], 0, v[148:149]
	s_mov_b32 m0, s50
	s_nop 0
	global_load_lds_dwordx4 v[192:193], off
	s_waitcnt lgkmcnt(0)
	s_barrier
	s_setprio 1
	v_mfma_f32_16x16x32_bf16 v[126:129], v[130:133], v[154:157], v[126:129]
	v_mfma_f32_16x16x32_bf16 v[122:125], v[138:141], v[154:157], v[122:125]
	v_mfma_f32_16x16x32_bf16 v[114:117], v[130:133], v[166:169], v[114:117]
	v_mfma_f32_16x16x32_bf16 v[110:113], v[138:141], v[166:169], v[110:113]
	v_mfma_f32_16x16x32_bf16 v[102:105], v[130:133], v[174:177], v[102:105]
	v_mfma_f32_16x16x32_bf16 v[94:97], v[138:141], v[174:177], v[94:97]
	v_mfma_f32_16x16x32_bf16 v[86:89], v[130:133], v[184:187], v[86:89]
	v_mfma_f32_16x16x32_bf16 v[78:81], v[138:141], v[184:187], v[78:81]
	v_mfma_f32_16x16x32_bf16 v[126:129], v[134:137], v[162:165], v[126:129]
	v_mfma_f32_16x16x32_bf16 v[122:125], v[142:145], v[162:165], v[122:125]
	v_mfma_f32_16x16x32_bf16 v[114:117], v[134:137], v[170:173], v[114:117]
	v_mfma_f32_16x16x32_bf16 v[110:113], v[142:145], v[170:173], v[110:113]
	v_mfma_f32_16x16x32_bf16 v[102:105], v[134:137], v[180:183], v[102:105]
	v_mfma_f32_16x16x32_bf16 v[94:97], v[142:145], v[180:183], v[94:97]
	v_mfma_f32_16x16x32_bf16 v[86:89], v[134:137], v[188:191], v[86:89]
	v_mfma_f32_16x16x32_bf16 v[78:81], v[142:145], v[188:191], v[78:81]
	s_setprio 0
	s_barrier
	s_mov_b32 m0, s72
	v_add_u32_e32 v161, s27, v159
	v_lshl_add_u64 v[208:209], s[74:75], 0, v[150:151]
	ds_read_b128 v[192:195], v161
	ds_read_b128 v[196:199], v161 offset:1024
	ds_read_b128 v[200:203], v161 offset:2048
	ds_read_b128 v[204:207], v161 offset:3072
	global_load_lds_dwordx4 v[208:209], off
	v_lshl_add_u64 v[226:227], s[74:75], 0, v[146:147]
	s_mov_b32 m0, s24
	s_nop 0
	global_load_lds_dwordx4 v[226:227], off
	s_waitcnt lgkmcnt(0)
	s_barrier
	s_setprio 1
	v_mfma_f32_16x16x32_bf16 v[118:121], v[192:195], v[154:157], v[118:121]
	v_mfma_f32_16x16x32_bf16 v[106:109], v[200:203], v[154:157], v[106:109]
	v_mfma_f32_16x16x32_bf16 v[98:101], v[192:195], v[166:169], v[98:101]
	v_mfma_f32_16x16x32_bf16 v[90:93], v[200:203], v[166:169], v[90:93]
	v_mfma_f32_16x16x32_bf16 v[82:85], v[192:195], v[174:177], v[82:85]
	v_mfma_f32_16x16x32_bf16 v[74:77], v[200:203], v[174:177], v[74:77]
	v_mfma_f32_16x16x32_bf16 v[70:73], v[192:195], v[184:187], v[70:73]
	v_mfma_f32_16x16x32_bf16 v[66:69], v[200:203], v[184:187], v[66:69]
	v_mfma_f32_16x16x32_bf16 v[118:121], v[196:199], v[162:165], v[118:121]
	v_mfma_f32_16x16x32_bf16 v[106:109], v[204:207], v[162:165], v[106:109]
	v_mfma_f32_16x16x32_bf16 v[98:101], v[196:199], v[170:173], v[98:101]
	v_mfma_f32_16x16x32_bf16 v[90:93], v[204:207], v[170:173], v[90:93]
	v_mfma_f32_16x16x32_bf16 v[82:85], v[196:199], v[180:183], v[82:85]
	v_mfma_f32_16x16x32_bf16 v[74:77], v[204:207], v[180:183], v[74:77]
	v_mfma_f32_16x16x32_bf16 v[70:73], v[196:199], v[188:191], v[70:73]
	v_mfma_f32_16x16x32_bf16 v[66:69], v[204:207], v[188:191], v[66:69]
	s_setprio 0
	s_mov_b32 m0, s26
	v_lshl_add_u64 v[228:229], s[66:67], 0, v[152:153]
	s_barrier
	ds_read_b128 v[154:157], v160 offset:16384
	ds_read_b128 v[162:165], v160 offset:17408
	ds_read_b128 v[166:169], v160 offset:18432
	ds_read_b128 v[170:173], v160 offset:19456
	ds_read_b128 v[174:177], v160 offset:20480
	ds_read_b128 v[180:183], v160 offset:21504
	ds_read_b128 v[184:187], v160 offset:22528
	ds_read_b128 v[188:191], v160 offset:23552
	global_load_lds_dwordx4 v[228:229], off
	v_lshl_add_u64 v[230:231], s[66:67], 0, v[148:149]
	s_mov_b32 m0, s52
	s_nop 0
	global_load_lds_dwordx4 v[230:231], off
	s_waitcnt lgkmcnt(0)
	s_barrier
; #define PG8_STAGE(bufoff, gbase, voff) do { _Pragma("unroll") for (int _i = 0; _i < 2; ++_i) \
;         __builtin_amdgcn_global_load_lds((const unsigned*)((const char*)(gbase) + (voff)[_i]), (LAS unsigned*)(lds + (bufoff) + ldsw + _i * 8192), 16, 0, 0); } while (0)
; #define PG8_LDA(dst, b, h) do { _Pragma("unroll") for (int m = 0; m < 4; ++m) _Pragma("unroll") for (int k = 0; k < 2; ++k) dst[m][k] = *(const LAS bf16x8*)(lds + PG8_SA(b, h) + aoff + m * 2048 + k * 1024); } while (0)
; #define PG8_LDB(dst, b, h) do { _Pragma("unroll") for (int n = 0; n < 2; ++n) _Pragma("unroll") for (int k = 0; k < 2; ++k) dst[n][k] = *(const LAS bf16x8*)(lds + PG8_SB(b, h) + boff + n * 2048 + k * 1024); } while (0)
; #define PG8_MMA(ai, bj, At, Bt) do { __builtin_amdgcn_s_setprio(1); _Pragma("unroll") for (int m = 0; m < 4; ++m) _Pragma("unroll") for (int n = 0; n < 2; ++n) _Pragma("unroll") for (int k = 0; k < 2; ++k) \
;         acc[ai][bj][m][n] = __builtin_amdgcn_mfma_f32_16x16x32_bf16(Bt[n][k], At[m][k], acc[ai][bj][m][n], 0, 0, 0); __builtin_amdgcn_s_setprio(0); } while (0)
; #define PG8_WAIT_V(n) asm volatile("s_waitcnt vmcnt(" #n ")" ::: "memory")
; #define PG8_WAIT_L(n) asm volatile("s_waitcnt lgkmcnt(" #n ")" ::: "memory")
; #define PG8_BAR __builtin_amdgcn_s_barrier()
; #define PG8_SCHED __builtin_amdgcn_sched_barrier(0)
; template <class Epi>
; __device__ __forceinline__ void gemm_phase(LAS unsigned char* lds, const Gemm g, const Epi& E) {
;     ...
;             PG8_BAR; PG8_WAIT_L(0); PG8_MMA(1, 0, At, B0); PG8_BAR; PG8_SCHED;
;             PG8_STAGE(PG8_SB(0, 1), b2 + hstepB, voffB);
;             PG8_WAIT_V(6); PG8_BAR; PG8_MMA(1, 1, At, B1); PG8_BAR;
;             PG8_LDB(B0, 1, 0); PG8_SCHED; PG8_LDA(At, 1, 0); PG8_STAGE(PG8_SA(0, 1), a2 + hstepA, voffA);
;             PG8_WAIT_L(8); PG8_BAR; PG8_WAIT_L(0); PG8_MMA(0, 0, At, B0); PG8_BAR; PG8_SCHED;
;             PG8_LDB(B1, 1, 1); PG8_STAGE(PG8_SB(1, 0), b3, voffB);
;             PG8_BAR; PG8_WAIT_L(0); PG8_MMA(0, 1, At, B1); PG8_BAR;
	s_setprio 1
	v_mfma_f32_16x16x32_bf16 v[62:65], v[130:133], v[154:157], v[62:65]
	v_mfma_f32_16x16x32_bf16 v[58:61], v[138:141], v[154:157], v[58:61]
	v_mfma_f32_16x16x32_bf16 v[54:57], v[130:133], v[166:169], v[54:57]
	v_mfma_f32_16x16x32_bf16 v[46:49], v[138:141], v[166:169], v[46:49]
	v_mfma_f32_16x16x32_bf16 v[38:41], v[130:133], v[174:177], v[38:41]
	v_mfma_f32_16x16x32_bf16 v[30:33], v[138:141], v[174:177], v[30:33]
	v_mfma_f32_16x16x32_bf16 v[22:25], v[130:133], v[184:187], v[22:25]
	v_mfma_f32_16x16x32_bf16 v[14:17], v[138:141], v[184:187], v[14:17]
	v_mfma_f32_16x16x32_bf16 v[62:65], v[134:137], v[162:165], v[62:65]
	v_mfma_f32_16x16x32_bf16 v[58:61], v[142:145], v[162:165], v[58:61]
	v_mfma_f32_16x16x32_bf16 v[54:57], v[134:137], v[170:173], v[54:57]
	v_mfma_f32_16x16x32_bf16 v[46:49], v[142:145], v[170:173], v[46:49]
	v_mfma_f32_16x16x32_bf16 v[38:41], v[134:137], v[180:183], v[38:41]
	v_mfma_f32_16x16x32_bf16 v[30:33], v[142:145], v[180:183], v[30:33]
	v_mfma_f32_16x16x32_bf16 v[22:25], v[134:137], v[188:191], v[22:25]
	v_mfma_f32_16x16x32_bf16 v[14:17], v[142:145], v[188:191], v[14:17]
	s_setprio 0
	s_barrier
	s_mov_b32 m0, s18
	v_lshl_add_u64 v[130:131], s[64:65], 0, v[150:151]
	global_load_lds_dwordx4 v[130:131], off
	v_lshl_add_u64 v[130:131], s[64:65], 0, v[146:147]
	s_mov_b32 m0, s36
	s_nop 0
	global_load_lds_dwordx4 v[130:131], off
	s_waitcnt vmcnt(6)
	s_barrier
	s_setprio 1
	v_mfma_f32_16x16x32_bf16 v[50:53], v[192:195], v[154:157], v[50:53]
	v_mfma_f32_16x16x32_bf16 v[42:45], v[200:203], v[154:157], v[42:45]
	v_mfma_f32_16x16x32_bf16 v[34:37], v[192:195], v[166:169], v[34:37]
	v_mfma_f32_16x16x32_bf16 v[26:29], v[200:203], v[166:169], v[26:29]
	v_mfma_f32_16x16x32_bf16 v[18:21], v[192:195], v[174:177], v[18:21]
	v_mfma_f32_16x16x32_bf16 v[10:13], v[200:203], v[174:177], v[10:13]
	v_mfma_f32_16x16x32_bf16 v[6:9], v[192:195], v[184:187], v[6:9]
	v_mfma_f32_16x16x32_bf16 v[2:5], v[200:203], v[184:187], v[2:5]
	v_mfma_f32_16x16x32_bf16 v[50:53], v[196:199], v[162:165], v[50:53]
	v_mfma_f32_16x16x32_bf16 v[42:45], v[204:207], v[162:165], v[42:45]
	v_mfma_f32_16x16x32_bf16 v[34:37], v[196:199], v[170:173], v[34:37]
	v_mfma_f32_16x16x32_bf16 v[26:29], v[204:207], v[170:173], v[26:29]
	v_mfma_f32_16x16x32_bf16 v[18:21], v[196:199], v[180:183], v[18:21]
	v_mfma_f32_16x16x32_bf16 v[10:13], v[204:207], v[180:183], v[10:13]
	v_mfma_f32_16x16x32_bf16 v[6:9], v[196:199], v[188:191], v[6:9]
	v_mfma_f32_16x16x32_bf16 v[2:5], v[204:207], v[188:191], v[2:5]
	s_setprio 0
	v_add_u32_e32 v142, vcc_hi, v159
	s_barrier
	ds_read_b128 v[130:133], v142
	ds_read_b128 v[134:137], v142 offset:1024
	ds_read_b128 v[138:141], v142 offset:2048
	ds_read_b128 v[142:145], v142 offset:3072
	s_mov_b32 m0, s53
	v_lshl_add_u64 v[192:193], s[60:61], 0, v[152:153]
	ds_read_b128 v[154:157], v160 offset:32768
	ds_read_b128 v[162:165], v160 offset:33792
	ds_read_b128 v[166:169], v160 offset:34816
	ds_read_b128 v[170:173], v160 offset:35840
	ds_read_b128 v[174:177], v160 offset:36864
	ds_read_b128 v[180:183], v160 offset:37888
	ds_read_b128 v[184:187], v160 offset:38912
	ds_read_b128 v[188:191], v160 offset:39936
	global_load_lds_dwordx4 v[192:193], off
	v_lshl_add_u64 v[192:193], s[60:61], 0, v[148:149]
	s_mov_b32 m0, s68
	s_nop 0
	global_load_lds_dwordx4 v[192:193], off
	s_waitcnt lgkmcnt(0)
	s_barrier
	s_setprio 1
	v_mfma_f32_16x16x32_bf16 v[126:129], v[130:133], v[154:157], v[126:129]
	v_mfma_f32_16x16x32_bf16 v[122:125], v[138:141], v[154:157], v[122:125]
	v_mfma_f32_16x16x32_bf16 v[114:117], v[130:133], v[166:169], v[114:117]
	v_mfma_f32_16x16x32_bf16 v[110:113], v[138:141], v[166:169], v[110:113]
	v_mfma_f32_16x16x32_bf16 v[102:105], v[130:133], v[174:177], v[102:105]
	v_mfma_f32_16x16x32_bf16 v[94:97], v[138:141], v[174:177], v[94:97]
	v_mfma_f32_16x16x32_bf16 v[86:89], v[130:133], v[184:187], v[86:89]
	v_mfma_f32_16x16x32_bf16 v[78:81], v[138:141], v[184:187], v[78:81]
	v_mfma_f32_16x16x32_bf16 v[126:129], v[134:137], v[162:165], v[126:129]
	v_mfma_f32_16x16x32_bf16 v[122:125], v[142:145], v[162:165], v[122:125]
	v_mfma_f32_16x16x32_bf16 v[114:117], v[134:137], v[170:173], v[114:117]
	v_mfma_f32_16x16x32_bf16 v[110:113], v[142:145], v[170:173], v[110:113]
	v_mfma_f32_16x16x32_bf16 v[102:105], v[134:137], v[180:183], v[102:105]
	v_mfma_f32_16x16x32_bf16 v[94:97], v[142:145], v[180:183], v[94:97]
	v_mfma_f32_16x16x32_bf16 v[86:89], v[134:137], v[188:191], v[86:89]
	v_mfma_f32_16x16x32_bf16 v[78:81], v[142:145], v[188:191], v[78:81]
	s_setprio 0
	s_barrier
	s_mov_b32 m0, vcc_lo
	v_add_u32_e32 v161, s9, v159
	v_lshl_add_u64 v[208:209], v[208:209], 0, s[86:87]
	ds_read_b128 v[192:195], v161
	ds_read_b128 v[196:199], v161 offset:1024
	ds_read_b128 v[200:203], v161 offset:2048
	ds_read_b128 v[204:207], v161 offset:3072
	global_load_lds_dwordx4 v[208:209], off
	v_lshl_add_u64 v[208:209], v[226:227], 0, s[86:87]
	s_mov_b32 m0, s5
	s_nop 0
	global_load_lds_dwordx4 v[208:209], off
	s_waitcnt lgkmcnt(0)
	s_barrier
; #define PG8_STAGE(bufoff, gbase, voff) do { _Pragma("unroll") for (int _i = 0; _i < 2; ++_i) \
;         __builtin_amdgcn_global_load_lds((const unsigned*)((const char*)(gbase) + (voff)[_i]), (LAS unsigned*)(lds + (bufoff) + ldsw + _i * 8192), 16, 0, 0); } while (0)
; #define PG8_LDA(dst, b, h) do { _Pragma("unroll") for (int m = 0; m < 4; ++m) _Pragma("unroll") for (int k = 0; k < 2; ++k) dst[m][k] = *(const LAS bf16x8*)(lds + PG8_SA(b, h) + aoff + m * 2048 + k * 1024); } while (0)
; #define PG8_MMA(ai, bj, At, Bt) do { __builtin_amdgcn_s_setprio(1); _Pragma("unroll") for (int m = 0; m < 4; ++m) _Pragma("unroll") for (int n = 0; n < 2; ++n) _Pragma("unroll") for (int k = 0; k < 2; ++k) \
;         acc[ai][bj][m][n] = __builtin_amdgcn_mfma_f32_16x16x32_bf16(Bt[n][k], At[m][k], acc[ai][bj][m][n], 0, 0, 0); __builtin_amdgcn_s_setprio(0); } while (0)
; #define PG8_WAIT_V(n) asm volatile("s_waitcnt vmcnt(" #n ")" ::: "memory")
; #define PG8_WAIT_L(n) asm volatile("s_waitcnt lgkmcnt(" #n ")" ::: "memory")
; #define PG8_BAR __builtin_amdgcn_s_barrier()
; #define PG8_SCHED __builtin_amdgcn_sched_barrier(0)
; template <class Epi>
; __device__ __forceinline__ void gemm_phase(LAS unsigned char* lds, const Gemm g, const Epi& E) {
;     ...
;             PG8_BAR; PG8_WAIT_L(0); PG8_MMA(0, 1, At, B1); PG8_BAR;
;             PG8_LDA(At, 1, 1); PG8_STAGE(PG8_SA(1, 0), a3, voffA);
;             PG8_BAR; PG8_WAIT_L(0); PG8_MMA(1, 0, At, B0); PG8_BAR; PG8_SCHED;
;             PG8_STAGE(PG8_SB(1, 1), b3 + hstepB, voffB);
;             PG8_WAIT_V(6); PG8_BAR; PG8_MMA(1, 1, At, B1); PG8_BAR;
;         }
;     __device__ __forceinline__ void operator()(const AccT& acc, const Unit& u, int wr, int wc, int fr, int fq) const {
;     ...
;         const int gpm = mapA.src(u.pm);
;         const int mb = gpm < 32 ? 32 : (gpm - 32) >> 3;
;         const int row0 = gpm * 256 + wr * 64 + fr, col0 = u.pn * 256 + wc * 32 + 4 * fq;
;         const float* gp = modl + ((size_t)mb * 6 + gi) * 1024;
;         f32x4 gv[2][2];
; #pragma unroll
;         for (int bj = 0; bj < 2; ++bj)
; #pragma unroll
;             for (int n = 0; n < 2; ++n) { gv[bj][n] = *(const f32x4*)(gp + col0 + bj * 128 + n * 16); if (scale) gv[bj][n] = gv[bj][n] * *(const f32x4*)(scale + col0 + bj * 128 + n * 16); }
	s_setprio 1
	v_mfma_f32_16x16x32_bf16 v[118:121], v[192:195], v[154:157], v[118:121]
	v_mfma_f32_16x16x32_bf16 v[106:109], v[200:203], v[154:157], v[106:109]
	v_mfma_f32_16x16x32_bf16 v[98:101], v[192:195], v[166:169], v[98:101]
	v_mfma_f32_16x16x32_bf16 v[90:93], v[200:203], v[166:169], v[90:93]
	v_mfma_f32_16x16x32_bf16 v[82:85], v[192:195], v[174:177], v[82:85]
	v_mfma_f32_16x16x32_bf16 v[74:77], v[200:203], v[174:177], v[74:77]
	v_mfma_f32_16x16x32_bf16 v[70:73], v[192:195], v[184:187], v[70:73]
	v_mfma_f32_16x16x32_bf16 v[66:69], v[200:203], v[184:187], v[66:69]
	v_mfma_f32_16x16x32_bf16 v[118:121], v[196:199], v[162:165], v[118:121]
	v_mfma_f32_16x16x32_bf16 v[106:109], v[204:207], v[162:165], v[106:109]
	v_mfma_f32_16x16x32_bf16 v[98:101], v[196:199], v[170:173], v[98:101]
	v_mfma_f32_16x16x32_bf16 v[90:93], v[204:207], v[170:173], v[90:93]
	v_mfma_f32_16x16x32_bf16 v[82:85], v[196:199], v[180:183], v[82:85]
	v_mfma_f32_16x16x32_bf16 v[74:77], v[204:207], v[180:183], v[74:77]
	v_mfma_f32_16x16x32_bf16 v[70:73], v[196:199], v[188:191], v[70:73]
	v_mfma_f32_16x16x32_bf16 v[66:69], v[204:207], v[188:191], v[66:69]
	s_setprio 0
	s_mov_b32 m0, s71
	v_lshl_add_u64 v[208:209], v[228:229], 0, s[86:87]
	s_barrier
	ds_read_b128 v[154:157], v160 offset:49152
	ds_read_b128 v[162:165], v160 offset:50176
	ds_read_b128 v[166:169], v160 offset:51200
	ds_read_b128 v[170:173], v160 offset:52224
	ds_read_b128 v[174:177], v160 offset:53248
	ds_read_b128 v[180:183], v160 offset:54272
	ds_read_b128 v[184:187], v160 offset:55296
	ds_read_b128 v[188:191], v160 offset:56320
	global_load_lds_dwordx4 v[208:209], off
	v_lshl_add_u64 v[208:209], v[230:231], 0, s[86:87]
	s_mov_b32 m0, s80
	s_nop 0
	global_load_lds_dwordx4 v[208:209], off
	s_waitcnt lgkmcnt(0)
	s_barrier
	s_setprio 1
	v_mfma_f32_16x16x32_bf16 v[62:65], v[130:133], v[154:157], v[62:65]
	v_mfma_f32_16x16x32_bf16 v[58:61], v[138:141], v[154:157], v[58:61]
	v_mfma_f32_16x16x32_bf16 v[54:57], v[130:133], v[166:169], v[54:57]
	v_mfma_f32_16x16x32_bf16 v[46:49], v[138:141], v[166:169], v[46:49]
	v_mfma_f32_16x16x32_bf16 v[38:41], v[130:133], v[174:177], v[38:41]
	v_mfma_f32_16x16x32_bf16 v[30:33], v[138:141], v[174:177], v[30:33]
	v_mfma_f32_16x16x32_bf16 v[22:25], v[130:133], v[184:187], v[22:25]
	v_mfma_f32_16x16x32_bf16 v[14:17], v[138:141], v[184:187], v[14:17]
	v_mfma_f32_16x16x32_bf16 v[62:65], v[134:137], v[162:165], v[62:65]
	v_mfma_f32_16x16x32_bf16 v[58:61], v[142:145], v[162:165], v[58:61]
	v_mfma_f32_16x16x32_bf16 v[54:57], v[134:137], v[170:173], v[54:57]
	v_mfma_f32_16x16x32_bf16 v[46:49], v[142:145], v[170:173], v[46:49]
	v_mfma_f32_16x16x32_bf16 v[38:41], v[134:137], v[180:183], v[38:41]
	v_mfma_f32_16x16x32_bf16 v[30:33], v[142:145], v[180:183], v[30:33]
	v_mfma_f32_16x16x32_bf16 v[22:25], v[134:137], v[188:191], v[22:25]
	v_mfma_f32_16x16x32_bf16 v[14:17], v[142:145], v[188:191], v[14:17]
	s_setprio 0
	s_barrier
	s_mov_b32 m0, s0
	v_lshl_add_u64 v[130:131], s[58:59], 0, v[150:151]
	global_load_lds_dwordx4 v[130:131], off
	v_lshl_add_u64 v[130:131], s[58:59], 0, v[146:147]
	s_mov_b32 m0, s1
	s_nop 0
	global_load_lds_dwordx4 v[130:131], off
	s_waitcnt vmcnt(6)
	s_barrier
	s_setprio 1
	v_mfma_f32_16x16x32_bf16 v[50:53], v[192:195], v[154:157], v[50:53]
	v_mfma_f32_16x16x32_bf16 v[42:45], v[200:203], v[154:157], v[42:45]
	v_mfma_f32_16x16x32_bf16 v[34:37], v[192:195], v[166:169], v[34:37]
	v_mfma_f32_16x16x32_bf16 v[26:29], v[200:203], v[166:169], v[26:29]
	v_mfma_f32_16x16x32_bf16 v[18:21], v[192:195], v[174:177], v[18:21]
	v_mfma_f32_16x16x32_bf16 v[10:13], v[200:203], v[174:177], v[10:13]
	v_mfma_f32_16x16x32_bf16 v[6:9], v[192:195], v[184:187], v[6:9]
	v_mfma_f32_16x16x32_bf16 v[2:5], v[200:203], v[184:187], v[2:5]
	v_mfma_f32_16x16x32_bf16 v[50:53], v[196:199], v[162:165], v[50:53]
	v_mfma_f32_16x16x32_bf16 v[42:45], v[204:207], v[162:165], v[42:45]
	v_mfma_f32_16x16x32_bf16 v[34:37], v[196:199], v[170:173], v[34:37]
	v_mfma_f32_16x16x32_bf16 v[26:29], v[204:207], v[170:173], v[26:29]
	v_mfma_f32_16x16x32_bf16 v[18:21], v[196:199], v[180:183], v[18:21]
	v_mfma_f32_16x16x32_bf16 v[10:13], v[204:207], v[180:183], v[10:13]
	v_mfma_f32_16x16x32_bf16 v[6:9], v[196:199], v[188:191], v[6:9]
	v_mfma_f32_16x16x32_bf16 v[2:5], v[204:207], v[188:191], v[2:5]
	s_setprio 0
	s_movk_i32 s5, 0x100
	s_andn2_b64 vcc, exec, s[28:29]
	s_mov_b64 s[58:59], -1
	s_mov_b64 s[28:29], 0
	s_barrier
	s_cbranch_vccz .LBB0_296
	s_cmp_ge_i32 s93, s31
	s_cselect_b32 s0, s44, 0
	s_add_i32 s0, s93, s0
	s_sub_i32 s1, s0, 32
	s_lshl_b32 s4, s4, 8
	s_ashr_i32 s1, s1, 3
	s_or_b32 s4, s4, s70
	v_mov_b32_e32 v130, v1
	v_mov_b32_e32 v161, v158
	s_mul_i32 s1, s1, 6
	s_cmp_gt_i32 s0, 31
	v_readlane_b32 s14, v255, 14
	v_lshl_add_u32 v154, v130, 2, s4
	s_cselect_b32 s4, s1, 0xc0
	s_ashr_i32 s5, s4, 31
	s_lshl_b64 s[4:5], s[4:5], 12
	v_readlane_b32 s15, v255, 15
	s_add_u32 s4, s14, s4
	v_ashrrev_i32_e32 v155, 31, v154
	s_addc_u32 s5, s15, s5
	v_lshlrev_b64 v[136:137], 2, v[154:155]
	v_lshl_add_u64 v[134:135], s[4:5], 0, v[136:137]
	v_add_co_u32_e32 v130, vcc, 0x2000, v134
	v_readlane_b32 s14, v254, 30
	s_nop 0
	v_addc_co_u32_e32 v131, vcc, 0, v135, vcc
	global_load_dwordx4 v[130:133], v[130:131], off
	v_readlane_b32 s15, v254, 31
	s_andn2_b64 vcc, exec, s[14:15]
	v_lshl_add_u64 v[156:157], s[6:7], 0, v[136:137]
	v_cndmask_b32_e64 v138, 0, 1, s[14:15]
	v_cmp_ne_u32_e64 s[4:5], 1, v138
	s_cbranch_vccnz .LBB0_299
	global_load_dwordx4 v[136:139], v[156:157], off
	s_waitcnt vmcnt(0)
	v_pk_mul_f32 v[132:133], v[132:133], v[138:139]
	v_pk_mul_f32 v[130:131], v[130:131], v[136:137]

; #define PG8_STAGE(bufoff, gbase, voff) do { _Pragma("unroll") for (int _i = 0; _i < 2; ++_i) \
;         __builtin_amdgcn_global_load_lds((const unsigned*)((const char*)(gbase) + (voff)[_i]), (LAS unsigned*)(lds + (bufoff) + ldsw + _i * 8192), 16, 0, 0); } while (0)
; #define PG8_LDA(dst, b, h) do { _Pragma("unroll") for (int m = 0; m < 4; ++m) _Pragma("unroll") for (int k = 0; k < 2; ++k) dst[m][k] = *(const LAS bf16x8*)(lds + PG8_SA(b, h) + aoff + m * 2048 + k * 1024); } while (0)
; #define PG8_LDB(dst, b, h) do { _Pragma("unroll") for (int n = 0; n < 2; ++n) _Pragma("unroll") for (int k = 0; k < 2; ++k) dst[n][k] = *(const LAS bf16x8*)(lds + PG8_SB(b, h) + boff + n * 2048 + k * 1024); } while (0)
; #define PG8_MMA(ai, bj, At, Bt) do { __builtin_amdgcn_s_setprio(1); _Pragma("unroll") for (int m = 0; m < 4; ++m) _Pragma("unroll") for (int n = 0; n < 2; ++n) _Pragma("unroll") for (int k = 0; k < 2; ++k) \
;         acc[ai][bj][m][n] = __builtin_amdgcn_mfma_f32_16x16x32_bf16(Bt[n][k], At[m][k], acc[ai][bj][m][n], 0, 0, 0); __builtin_amdgcn_s_setprio(0); } while (0)
; #define PG8_WAIT_L(n) asm volatile("s_waitcnt lgkmcnt(" #n ")" ::: "memory")
; #define PG8_BAR __builtin_amdgcn_s_barrier()
; #define PG8_SCHED __builtin_amdgcn_sched_barrier(0)
; template <class Epi>
; __device__ __forceinline__ void gemm_phase(LAS unsigned char* lds, const Gemm g, const Epi& E) {
;     ...
;         for (int t = 0; t < nt; t += 2) {
;             const bool last = (t == nt - 2);
;             const char* a1 = cA + (size_t)(t + 1) * kstep;
;             const char* a2 = last ? nA : cA + (size_t)(t + 2) * kstep; const char* b2 = last ? nB : cB + (size_t)(t + 2) * kstep;
;             const char* a3 = a2 + kstep; const char* b3 = b2 + kstep;
;             PG8_LDB(B0, 0, 0); PG8_SCHED; PG8_LDA(At, 0, 0); PG8_STAGE(PG8_SA(1, 1), a1 + hstepA, voffA);
;             PG8_WAIT_L(8); PG8_BAR; PG8_WAIT_L(0); PG8_MMA(0, 0, At, B0); PG8_BAR; PG8_SCHED;
;             PG8_LDB(B1, 0, 1); PG8_STAGE(PG8_SB(0, 0), b2, voffB);
;             PG8_BAR; PG8_WAIT_L(0); PG8_MMA(0, 1, At, B1); PG8_BAR;
;             PG8_LDA(At, 0, 1); PG8_STAGE(PG8_SA(0, 0), a2, voffA);
;             PG8_BAR; PG8_WAIT_L(0); PG8_MMA(1, 0, At, B0); PG8_BAR; PG8_SCHED;
.LBB0_331:
	s_add_u32 s60, s4, 0xfffc0080
	s_addc_u32 s61, s5, -1
	s_add_i32 s72, 0, 0x10000
	s_waitcnt vmcnt(0)
	v_add_u32_e32 v94, s72, v201
	ds_read_b128 v[74:77], v94
	ds_read_b128 v[82:85], v94 offset:1024
	ds_read_b128 v[86:89], v94 offset:2048
	ds_read_b128 v[94:97], v94 offset:3072
	s_cmp_eq_u32 s53, 12
	s_cselect_b32 s65, s29, s61
	s_cselect_b32 s64, s28, s60
	s_cselect_b32 s61, s59, s52
	s_cselect_b32 s60, s58, s15
	v_lshl_add_u64 v[192:193], s[4:5], 0, v[188:189]
	s_add_i32 m0, s24, 0xc000
	ds_read_b128 v[106:109], v202
	ds_read_b128 v[110:113], v202 offset:1024
	ds_read_b128 v[130:133], v202 offset:2048
	ds_read_b128 v[134:137], v202 offset:3072
	ds_read_b128 v[154:157], v202 offset:4096
	ds_read_b128 v[158:161], v202 offset:5120
	ds_read_b128 v[170:173], v202 offset:6144
	ds_read_b128 v[174:177], v202 offset:7168
	global_load_lds_dwordx4 v[192:193], off
	v_lshl_add_u64 v[192:193], s[4:5], 0, v[190:191]
	s_add_i32 m0, s24, 0xe000
	s_nop 0
	global_load_lds_dwordx4 v[192:193], off
	s_waitcnt lgkmcnt(0)
	s_barrier
	s_setprio 1
	v_mfma_f32_16x16x32_bf16 v[166:169], v[74:77], v[106:109], v[166:169]
	v_mfma_f32_16x16x32_bf16 v[162:165], v[86:89], v[106:109], v[162:165]
	v_mfma_f32_16x16x32_bf16 v[142:145], v[74:77], v[130:133], v[142:145]
	v_mfma_f32_16x16x32_bf16 v[138:141], v[86:89], v[130:133], v[138:141]
	v_mfma_f32_16x16x32_bf16 v[118:121], v[74:77], v[154:157], v[118:121]
	v_mfma_f32_16x16x32_bf16 v[114:117], v[86:89], v[154:157], v[114:117]
	v_mfma_f32_16x16x32_bf16 v[90:93], v[74:77], v[170:173], v[90:93]
	v_mfma_f32_16x16x32_bf16 v[78:81], v[86:89], v[170:173], v[78:81]
	v_mfma_f32_16x16x32_bf16 v[166:169], v[82:85], v[110:113], v[166:169]
	v_mfma_f32_16x16x32_bf16 v[162:165], v[94:97], v[110:113], v[162:165]
	v_mfma_f32_16x16x32_bf16 v[142:145], v[82:85], v[134:137], v[142:145]
	v_mfma_f32_16x16x32_bf16 v[138:141], v[94:97], v[134:137], v[138:141]
	v_mfma_f32_16x16x32_bf16 v[118:121], v[82:85], v[158:161], v[118:121]
	v_mfma_f32_16x16x32_bf16 v[114:117], v[94:97], v[158:161], v[114:117]
	v_mfma_f32_16x16x32_bf16 v[90:93], v[82:85], v[174:177], v[90:93]
	v_mfma_f32_16x16x32_bf16 v[78:81], v[94:97], v[174:177], v[78:81]
	s_setprio 0
	s_barrier
	s_add_i32 s74, 0, 0x14000
	s_add_i32 s72, s72, s1
	v_add_u32_e32 v203, s74, v201
	v_lshl_add_u64 v[208:209], s[60:61], 0, v[184:185]
	s_mov_b32 m0, s72
	ds_read_b128 v[192:195], v203
	ds_read_b128 v[196:199], v203 offset:1024
	ds_read_b128 v[204:207], v203 offset:2048
	ds_read_b128 v[226:229], v203 offset:3072
	global_load_lds_dwordx4 v[208:209], off
	v_lshl_add_u64 v[234:235], s[60:61], 0, v[180:181]
	s_add_i32 m0, s72, 0x2000
	s_nop 0
	global_load_lds_dwordx4 v[234:235], off
	s_waitcnt lgkmcnt(0)
	s_barrier
	s_setprio 1
	v_mfma_f32_16x16x32_bf16 v[150:153], v[192:195], v[106:109], v[150:153]
	v_mfma_f32_16x16x32_bf16 v[106:109], v[204:207], v[106:109], v[146:149]
	v_mfma_f32_16x16x32_bf16 v[122:125], v[204:207], v[130:133], v[122:125]
	v_mfma_f32_16x16x32_bf16 v[102:105], v[192:195], v[154:157], v[102:105]
	v_mfma_f32_16x16x32_bf16 v[98:101], v[204:207], v[154:157], v[98:101]
	v_mfma_f32_16x16x32_bf16 v[70:73], v[192:195], v[170:173], v[70:73]
	v_mfma_f32_16x16x32_bf16 v[66:69], v[204:207], v[170:173], v[66:69]
	v_mfma_f32_16x16x32_bf16 v[150:153], v[196:199], v[110:113], v[150:153]
	v_mfma_f32_16x16x32_bf16 v[106:109], v[226:229], v[110:113], v[106:109]
	v_mfma_f32_16x16x32_bf16 v[110:113], v[192:195], v[130:133], v[126:129]
	v_mfma_f32_16x16x32_bf16 v[122:125], v[226:229], v[134:137], v[122:125]
	v_mfma_f32_16x16x32_bf16 v[102:105], v[196:199], v[158:161], v[102:105]
	v_mfma_f32_16x16x32_bf16 v[98:101], v[226:229], v[158:161], v[98:101]
	v_mfma_f32_16x16x32_bf16 v[70:73], v[196:199], v[174:177], v[70:73]
	v_mfma_f32_16x16x32_bf16 v[66:69], v[226:229], v[174:177], v[66:69]
	v_mfma_f32_16x16x32_bf16 v[110:113], v[196:199], v[134:137], v[110:113]
	s_setprio 0
	s_mov_b32 m0, s24
	v_lshl_add_u64 v[236:237], s[64:65], 0, v[186:187]
	s_barrier
	ds_read_b128 v[126:129], v202 offset:16384
	ds_read_b128 v[130:133], v202 offset:17408
	ds_read_b128 v[134:137], v202 offset:18432
	ds_read_b128 v[146:149], v202 offset:19456
	ds_read_b128 v[154:157], v202 offset:20480
	ds_read_b128 v[158:161], v202 offset:21504
	ds_read_b128 v[170:173], v202 offset:22528
	ds_read_b128 v[174:177], v202 offset:23552
	global_load_lds_dwordx4 v[236:237], off
	v_lshl_add_u64 v[238:239], s[64:65], 0, v[182:183]
	s_mov_b32 m0, s25
	s_nop 0
	global_load_lds_dwordx4 v[238:239], off
	s_waitcnt lgkmcnt(0)
	s_barrier
	s_setprio 1
	v_mfma_f32_16x16x32_bf16 v[62:65], v[74:77], v[126:129], v[62:65]
	v_mfma_f32_16x16x32_bf16 v[58:61], v[86:89], v[126:129], v[58:61]
	v_mfma_f32_16x16x32_bf16 v[46:49], v[74:77], v[134:137], v[46:49]
	v_mfma_f32_16x16x32_bf16 v[42:45], v[86:89], v[134:137], v[42:45]
	v_mfma_f32_16x16x32_bf16 v[30:33], v[74:77], v[154:157], v[30:33]
	v_mfma_f32_16x16x32_bf16 v[26:29], v[86:89], v[154:157], v[26:29]
	v_mfma_f32_16x16x32_bf16 v[14:17], v[74:77], v[170:173], v[14:17]
	v_mfma_f32_16x16x32_bf16 v[10:13], v[86:89], v[170:173], v[10:13]
	v_mfma_f32_16x16x32_bf16 v[62:65], v[82:85], v[130:133], v[62:65]
	v_mfma_f32_16x16x32_bf16 v[58:61], v[94:97], v[130:133], v[58:61]
	v_mfma_f32_16x16x32_bf16 v[46:49], v[82:85], v[146:149], v[46:49]
	v_mfma_f32_16x16x32_bf16 v[42:45], v[94:97], v[146:149], v[42:45]
	v_mfma_f32_16x16x32_bf16 v[30:33], v[82:85], v[158:161], v[30:33]
	v_mfma_f32_16x16x32_bf16 v[26:29], v[94:97], v[158:161], v[26:29]
	v_mfma_f32_16x16x32_bf16 v[14:17], v[82:85], v[174:177], v[14:17]
	v_mfma_f32_16x16x32_bf16 v[10:13], v[94:97], v[174:177], v[10:13]
	s_setprio 0
	s_barrier
; #define PG8_STAGE(bufoff, gbase, voff) do { _Pragma("unroll") for (int _i = 0; _i < 2; ++_i) \
;         __builtin_amdgcn_global_load_lds((const unsigned*)((const char*)(gbase) + (voff)[_i]), (LAS unsigned*)(lds + (bufoff) + ldsw + _i * 8192), 16, 0, 0); } while (0)
; #define PG8_LDA(dst, b, h) do { _Pragma("unroll") for (int m = 0; m < 4; ++m) _Pragma("unroll") for (int k = 0; k < 2; ++k) dst[m][k] = *(const LAS bf16x8*)(lds + PG8_SA(b, h) + aoff + m * 2048 + k * 1024); } while (0)
; #define PG8_LDB(dst, b, h) do { _Pragma("unroll") for (int n = 0; n < 2; ++n) _Pragma("unroll") for (int k = 0; k < 2; ++k) dst[n][k] = *(const LAS bf16x8*)(lds + PG8_SB(b, h) + boff + n * 2048 + k * 1024); } while (0)
; #define PG8_MMA(ai, bj, At, Bt) do { __builtin_amdgcn_s_setprio(1); _Pragma("unroll") for (int m = 0; m < 4; ++m) _Pragma("unroll") for (int n = 0; n < 2; ++n) _Pragma("unroll") for (int k = 0; k < 2; ++k) \
;         acc[ai][bj][m][n] = __builtin_amdgcn_mfma_f32_16x16x32_bf16(Bt[n][k], At[m][k], acc[ai][bj][m][n], 0, 0, 0); __builtin_amdgcn_s_setprio(0); } while (0)
; #define PG8_WAIT_V(n) asm volatile("s_waitcnt vmcnt(" #n ")" ::: "memory")
; #define PG8_WAIT_L(n) asm volatile("s_waitcnt lgkmcnt(" #n ")" ::: "memory")
; #define PG8_BAR __builtin_amdgcn_s_barrier()
; #define PG8_SCHED __builtin_amdgcn_sched_barrier(0)
; template <class Epi>
; __device__ __forceinline__ void gemm_phase(LAS unsigned char* lds, const Gemm g, const Epi& E) {
;     ...
;             PG8_STAGE(PG8_SB(0, 1), b2 + hstepB, voffB);
;             PG8_WAIT_V(6); PG8_BAR; PG8_MMA(1, 1, At, B1); PG8_BAR;
;             PG8_LDB(B0, 1, 0); PG8_SCHED; PG8_LDA(At, 1, 0); PG8_STAGE(PG8_SA(0, 1), a2 + hstepA, voffA);
;             PG8_WAIT_L(8); PG8_BAR; PG8_WAIT_L(0); PG8_MMA(0, 0, At, B0); PG8_BAR; PG8_SCHED;
;             PG8_LDB(B1, 1, 1); PG8_STAGE(PG8_SB(1, 0), b3, voffB);
;             PG8_BAR; PG8_WAIT_L(0); PG8_MMA(0, 1, At, B1); PG8_BAR;
;             PG8_LDA(At, 1, 1); PG8_STAGE(PG8_SA(1, 0), a3, voffA);
	s_add_u32 s72, s60, 0x40000
	s_addc_u32 s73, s61, 0
	s_add_i32 s74, s74, s1
	v_lshl_add_u64 v[74:75], s[72:73], 0, v[184:185]
	s_mov_b32 m0, s74
	s_nop 0
	global_load_lds_dwordx4 v[74:75], off
	v_lshl_add_u64 v[74:75], s[72:73], 0, v[180:181]
	s_add_i32 m0, s74, 0x2000
	s_nop 0
	global_load_lds_dwordx4 v[74:75], off
	s_waitcnt vmcnt(6)
	s_barrier
	s_setprio 1
	v_mfma_f32_16x16x32_bf16 v[54:57], v[192:195], v[126:129], v[54:57]
	v_mfma_f32_16x16x32_bf16 v[50:53], v[204:207], v[126:129], v[50:53]
	v_mfma_f32_16x16x32_bf16 v[38:41], v[192:195], v[134:137], v[38:41]
	v_mfma_f32_16x16x32_bf16 v[34:37], v[204:207], v[134:137], v[34:37]
	v_mfma_f32_16x16x32_bf16 v[22:25], v[192:195], v[154:157], v[22:25]
	v_mfma_f32_16x16x32_bf16 v[18:21], v[204:207], v[154:157], v[18:21]
	v_mfma_f32_16x16x32_bf16 v[6:9], v[192:195], v[170:173], v[6:9]
	v_mfma_f32_16x16x32_bf16 v[2:5], v[204:207], v[170:173], v[2:5]
	v_mfma_f32_16x16x32_bf16 v[54:57], v[196:199], v[130:133], v[54:57]
	v_mfma_f32_16x16x32_bf16 v[50:53], v[226:229], v[130:133], v[50:53]
	v_mfma_f32_16x16x32_bf16 v[38:41], v[196:199], v[146:149], v[38:41]
	v_mfma_f32_16x16x32_bf16 v[34:37], v[226:229], v[146:149], v[34:37]
	v_mfma_f32_16x16x32_bf16 v[22:25], v[196:199], v[158:161], v[22:25]
	v_mfma_f32_16x16x32_bf16 v[18:21], v[226:229], v[158:161], v[18:21]
	v_mfma_f32_16x16x32_bf16 v[6:9], v[196:199], v[174:177], v[6:9]
	v_mfma_f32_16x16x32_bf16 v[2:5], v[226:229], v[174:177], v[2:5]
	s_setprio 0
	s_add_i32 s72, 0, 0x18000
	v_add_u32_e32 v94, s72, v201
	s_barrier
	ds_read_b128 v[74:77], v94
	ds_read_b128 v[82:85], v94 offset:1024
	ds_read_b128 v[86:89], v94 offset:2048
	ds_read_b128 v[94:97], v94 offset:3072
	s_add_u32 s64, s64, 0x40000
	s_addc_u32 s65, s65, 0
	s_mov_b32 m0, s31
	v_lshl_add_u64 v[146:147], s[64:65], 0, v[186:187]
	ds_read_b128 v[126:129], v202 offset:32768
	ds_read_b128 v[130:133], v202 offset:33792
	ds_read_b128 v[134:137], v202 offset:34816
	ds_read_b128 v[154:157], v202 offset:35840
	ds_read_b128 v[158:161], v202 offset:36864
	ds_read_b128 v[170:173], v202 offset:37888
	ds_read_b128 v[174:177], v202 offset:38912
	ds_read_b128 v[192:195], v202 offset:39936
	global_load_lds_dwordx4 v[146:147], off
	v_lshl_add_u64 v[146:147], s[64:65], 0, v[182:183]
	s_mov_b32 m0, s36
	s_nop 0
	global_load_lds_dwordx4 v[146:147], off
	s_waitcnt lgkmcnt(0)
	s_barrier
	s_setprio 1
	v_mfma_f32_16x16x32_bf16 v[146:149], v[74:77], v[126:129], v[166:169]
	v_mfma_f32_16x16x32_bf16 v[166:169], v[82:85], v[130:133], v[146:149]
	v_mfma_f32_16x16x32_bf16 v[146:149], v[86:89], v[126:129], v[162:165]
	v_mfma_f32_16x16x32_bf16 v[142:145], v[74:77], v[134:137], v[142:145]
	v_mfma_f32_16x16x32_bf16 v[138:141], v[86:89], v[134:137], v[138:141]
	v_mfma_f32_16x16x32_bf16 v[118:121], v[74:77], v[158:161], v[118:121]
	v_mfma_f32_16x16x32_bf16 v[114:117], v[86:89], v[158:161], v[114:117]
	v_mfma_f32_16x16x32_bf16 v[90:93], v[74:77], v[174:177], v[90:93]
	v_mfma_f32_16x16x32_bf16 v[78:81], v[86:89], v[174:177], v[78:81]
	v_mfma_f32_16x16x32_bf16 v[162:165], v[94:97], v[130:133], v[146:149]
	v_mfma_f32_16x16x32_bf16 v[142:145], v[82:85], v[154:157], v[142:145]
	v_mfma_f32_16x16x32_bf16 v[138:141], v[94:97], v[154:157], v[138:141]
	v_mfma_f32_16x16x32_bf16 v[118:121], v[82:85], v[170:173], v[118:121]
	v_mfma_f32_16x16x32_bf16 v[114:117], v[94:97], v[170:173], v[114:117]
	v_mfma_f32_16x16x32_bf16 v[90:93], v[82:85], v[192:195], v[90:93]
	v_mfma_f32_16x16x32_bf16 v[78:81], v[94:97], v[192:195], v[78:81]
	s_setprio 0
	s_barrier
	s_add_i32 s64, 0, 0x1c000
	v_add_u32_e32 v146, s64, v201
	s_add_i32 s65, s72, s1
	ds_read_b128 v[196:199], v146
	ds_read_b128 v[204:207], v146 offset:1024
	ds_read_b128 v[226:229], v146 offset:2048
	ds_read_b128 v[230:233], v146 offset:3072
	v_lshl_add_u64 v[146:147], v[208:209], 0, s[86:87]
	s_mov_b32 m0, s65
	s_nop 0
	global_load_lds_dwordx4 v[146:147], off
	v_lshl_add_u64 v[146:147], v[234:235], 0, s[86:87]
	s_add_i32 m0, s65, 0x2000
	s_nop 0
	global_load_lds_dwordx4 v[146:147], off
	s_waitcnt lgkmcnt(0)
	s_barrier
	s_setprio 1
	v_mfma_f32_16x16x32_bf16 v[146:149], v[196:199], v[126:129], v[150:153]
	v_mfma_f32_16x16x32_bf16 v[106:109], v[226:229], v[126:129], v[106:109]
	v_mfma_f32_16x16x32_bf16 v[150:153], v[204:207], v[130:133], v[146:149]
	v_mfma_f32_16x16x32_bf16 v[146:149], v[230:233], v[130:133], v[106:109]
	v_mfma_f32_16x16x32_bf16 v[106:109], v[196:199], v[134:137], v[110:113]
	v_mfma_f32_16x16x32_bf16 v[126:129], v[204:207], v[154:157], v[106:109]
	v_mfma_f32_16x16x32_bf16 v[106:109], v[226:229], v[134:137], v[122:125]
	v_mfma_f32_16x16x32_bf16 v[102:105], v[196:199], v[158:161], v[102:105]
	v_mfma_f32_16x16x32_bf16 v[98:101], v[226:229], v[158:161], v[98:101]
	v_mfma_f32_16x16x32_bf16 v[70:73], v[196:199], v[174:177], v[70:73]
	v_mfma_f32_16x16x32_bf16 v[66:69], v[226:229], v[174:177], v[66:69]
	v_mfma_f32_16x16x32_bf16 v[122:125], v[230:233], v[154:157], v[106:109]
	v_mfma_f32_16x16x32_bf16 v[102:105], v[204:207], v[170:173], v[102:105]
	v_mfma_f32_16x16x32_bf16 v[98:101], v[230:233], v[170:173], v[98:101]
	v_mfma_f32_16x16x32_bf16 v[70:73], v[204:207], v[192:195], v[70:73]
	v_mfma_f32_16x16x32_bf16 v[66:69], v[230:233], v[192:195], v[66:69]
	s_setprio 0
	s_mov_b32 m0, s50
	v_lshl_add_u64 v[192:193], v[236:237], 0, s[86:87]
	s_barrier
; #define PG8_STAGE(bufoff, gbase, voff) do { _Pragma("unroll") for (int _i = 0; _i < 2; ++_i) \
;         __builtin_amdgcn_global_load_lds((const unsigned*)((const char*)(gbase) + (voff)[_i]), (LAS unsigned*)(lds + (bufoff) + ldsw + _i * 8192), 16, 0, 0); } while (0)
; #define PG8_MMA(ai, bj, At, Bt) do { __builtin_amdgcn_s_setprio(1); _Pragma("unroll") for (int m = 0; m < 4; ++m) _Pragma("unroll") for (int n = 0; n < 2; ++n) _Pragma("unroll") for (int k = 0; k < 2; ++k) \
;         acc[ai][bj][m][n] = __builtin_amdgcn_mfma_f32_16x16x32_bf16(Bt[n][k], At[m][k], acc[ai][bj][m][n], 0, 0, 0); __builtin_amdgcn_s_setprio(0); } while (0)
; #define PG8_WAIT_V(n) asm volatile("s_waitcnt vmcnt(" #n ")" ::: "memory")
; #define PG8_WAIT_L(n) asm volatile("s_waitcnt lgkmcnt(" #n ")" ::: "memory")
; #define PG8_BAR __builtin_amdgcn_s_barrier()
; #define PG8_SCHED __builtin_amdgcn_sched_barrier(0)
; template <class Epi>
; __device__ __forceinline__ void gemm_phase(LAS unsigned char* lds, const Gemm g, const Epi& E) {
;     ...
;             PG8_BAR; PG8_WAIT_L(0); PG8_MMA(1, 0, At, B0); PG8_BAR; PG8_SCHED;
;             PG8_STAGE(PG8_SB(1, 1), b3 + hstepB, voffB);
;             PG8_WAIT_V(6); PG8_BAR; PG8_MMA(1, 1, At, B1); PG8_BAR;
;         }
;     __device__ __forceinline__ void operator()(const AccT& acc, const Unit& u, int wr, int wc, int fr, int fq) const {
;     ...
;         const int gpm = mapA.src(u.pm);
;         const bool isq = u.pn < 4, isv = u.pn >= 8;
;         const bool lat = gpm >= 32 && !isv;
;         bf16_t* base = isq ? Q : (isv ? Vv + (size_t)(u.pn - 8) * 256 : Kk);
;         const int hh = isv ? 0 : (u.pn & 3);
;         const int ldo = isv ? 2048 : 1024;
;         const float osc = isq ? 0.0625f : 1.0f;
;         const int p0 = 16 * wc + 4 * fq;
;         f32x4 ctR[2][2], ctC[4][2];
;         if (lat) {
; #pragma unroll
;             for (int ai = 0; ai < 2; ++ai) { const int pr = ((gpm - 32) * 4 + 2 * ai + wr) & 31;
;                 ctR[ai][0] = *(const f32x4*)(cs + pr * 64 + p0); ctR[ai][1] = *(const f32x4*)(cs + pr * 64 + p0 + 2); }
; #pragma unroll
;             for (int m = 0; m < 4; ++m) { const int pc = m * 16 + fr;
;                 ctC[m][0] = *(const f32x4*)(cs + pc * 64 + p0); ctC[m][1] = *(const f32x4*)(cs + pc * 64 + p0 + 2); }
;         }
	ds_read_b128 v[106:109], v202 offset:49152
	ds_read_b128 v[110:113], v202 offset:50176
	ds_read_b128 v[130:133], v202 offset:51200
	ds_read_b128 v[134:137], v202 offset:52224
	ds_read_b128 v[154:157], v202 offset:53248
	ds_read_b128 v[158:161], v202 offset:54272
	ds_read_b128 v[170:173], v202 offset:55296
	ds_read_b128 v[174:177], v202 offset:56320
	global_load_lds_dwordx4 v[192:193], off
	v_lshl_add_u64 v[192:193], v[238:239], 0, s[86:87]
	s_mov_b32 m0, s66
	s_nop 0
	global_load_lds_dwordx4 v[192:193], off
	s_waitcnt lgkmcnt(0)
	s_barrier
	s_setprio 1
	v_mfma_f32_16x16x32_bf16 v[62:65], v[74:77], v[106:109], v[62:65]
	v_mfma_f32_16x16x32_bf16 v[58:61], v[86:89], v[106:109], v[58:61]
	v_mfma_f32_16x16x32_bf16 v[46:49], v[74:77], v[130:133], v[46:49]
	v_mfma_f32_16x16x32_bf16 v[42:45], v[86:89], v[130:133], v[42:45]
	v_mfma_f32_16x16x32_bf16 v[30:33], v[74:77], v[154:157], v[30:33]
	v_mfma_f32_16x16x32_bf16 v[26:29], v[86:89], v[154:157], v[26:29]
	v_mfma_f32_16x16x32_bf16 v[14:17], v[74:77], v[170:173], v[14:17]
	v_mfma_f32_16x16x32_bf16 v[10:13], v[86:89], v[170:173], v[10:13]
	v_mfma_f32_16x16x32_bf16 v[62:65], v[82:85], v[110:113], v[62:65]
	v_mfma_f32_16x16x32_bf16 v[58:61], v[94:97], v[110:113], v[58:61]
	v_mfma_f32_16x16x32_bf16 v[46:49], v[82:85], v[134:137], v[46:49]
	v_mfma_f32_16x16x32_bf16 v[42:45], v[94:97], v[134:137], v[42:45]
	v_mfma_f32_16x16x32_bf16 v[30:33], v[82:85], v[158:161], v[30:33]
	v_mfma_f32_16x16x32_bf16 v[26:29], v[94:97], v[158:161], v[26:29]
	v_mfma_f32_16x16x32_bf16 v[14:17], v[82:85], v[174:177], v[14:17]
	v_mfma_f32_16x16x32_bf16 v[10:13], v[94:97], v[174:177], v[10:13]
	s_setprio 0
	s_barrier
	s_add_u32 s60, s60, 0x40080
	s_addc_u32 s61, s61, 0
	s_add_i32 s64, s64, s1
	v_lshl_add_u64 v[74:75], s[60:61], 0, v[184:185]
	s_mov_b32 m0, s64
	s_nop 0
	global_load_lds_dwordx4 v[74:75], off
	v_lshl_add_u64 v[74:75], s[60:61], 0, v[180:181]
	s_add_i32 m0, s64, 0x2000
	s_nop 0
	global_load_lds_dwordx4 v[74:75], off
	s_waitcnt vmcnt(6)
	s_barrier
	s_setprio 1
	v_mfma_f32_16x16x32_bf16 v[54:57], v[196:199], v[106:109], v[54:57]
	v_mfma_f32_16x16x32_bf16 v[50:53], v[226:229], v[106:109], v[50:53]
	v_mfma_f32_16x16x32_bf16 v[38:41], v[196:199], v[130:133], v[38:41]
	v_mfma_f32_16x16x32_bf16 v[34:37], v[226:229], v[130:133], v[34:37]
	v_mfma_f32_16x16x32_bf16 v[22:25], v[196:199], v[154:157], v[22:25]
	v_mfma_f32_16x16x32_bf16 v[18:21], v[226:229], v[154:157], v[18:21]
	v_mfma_f32_16x16x32_bf16 v[6:9], v[196:199], v[170:173], v[6:9]
	v_mfma_f32_16x16x32_bf16 v[2:5], v[226:229], v[170:173], v[2:5]
	v_mfma_f32_16x16x32_bf16 v[54:57], v[204:207], v[110:113], v[54:57]
	v_mfma_f32_16x16x32_bf16 v[50:53], v[230:233], v[110:113], v[50:53]
	v_mfma_f32_16x16x32_bf16 v[38:41], v[204:207], v[134:137], v[38:41]
	v_mfma_f32_16x16x32_bf16 v[34:37], v[230:233], v[134:137], v[34:37]
	v_mfma_f32_16x16x32_bf16 v[22:25], v[204:207], v[158:161], v[22:25]
	v_mfma_f32_16x16x32_bf16 v[18:21], v[230:233], v[158:161], v[18:21]
	v_mfma_f32_16x16x32_bf16 v[6:9], v[204:207], v[174:177], v[6:9]
	v_mfma_f32_16x16x32_bf16 v[2:5], v[230:233], v[174:177], v[2:5]
	s_setprio 0
	s_add_i32 s53, s53, 2
	s_add_u32 s4, s4, 0x100
	s_addc_u32 s5, s5, 0
	s_add_u32 s15, s15, 0x100
	s_addc_u32 s52, s52, 0
	s_cmp_gt_u32 s53, 13
	s_barrier
	s_cbranch_scc0 .LBB0_331
	s_cmp_lt_i32 s10, 16
	s_cselect_b32 s4, s68, s18
	s_add_i32 s15, s10, s4
	s_cmp_lt_i32 s11, 8
	s_cselect_b64 s[60:61], -1, 0
	s_cmp_gt_i32 s15, 31
	s_cselect_b64 s[4:5], -1, 0
	s_and_b64 s[52:53], s[60:61], s[4:5]
	v_cndmask_b32_e64 v74, 0, 1, s[52:53]
	v_mov_b32_e32 v194, v200
	v_mov_b32_e32 v193, v1
	v_cmp_ne_u32_e64 s[4:5], 1, v74
	s_andn2_b64 vcc, exec, s[52:53]
	s_cbranch_vccnz .LBB0_334
	v_lshl_add_u32 v74, v193, 2, s67
	v_readlane_b32 s52, v254, 2
	s_lshl_b32 s15, s15, 8
	v_ashrrev_i32_e32 v75, 31, v74
	v_readlane_b32 s53, v254, 3
	s_add_i32 s15, s15, s44
	s_nop 0
	v_lshl_add_u64 v[74:75], v[74:75], 3, s[52:53]
	s_and_b32 s52, s15, 0x7c0
	s_addk_i32 s15, 0x80
	s_lshl_b32 s76, s52, 3
	s_and_b32 s15, s15, 0x7c0
	v_lshl_add_u64 v[76:77], v[74:75], 0, s[76:77]
	s_lshl_b32 s76, s15, 3
	global_load_dwordx4 v[170:173], v[76:77], off offset:16
	global_load_dwordx4 v[174:177], v[76:77], off
	v_lshl_add_u64 v[76:77], v[74:75], 0, s[76:77]
	global_load_dwordx4 v[86:89], v[76:77], off offset:16
	global_load_dwordx4 v[94:97], v[76:77], off
	v_lshlrev_b32_e32 v76, 6, v194
	v_ashrrev_i32_e32 v77, 31, v76
	v_lshl_add_u64 v[82:83], v[76:77], 3, v[74:75]
	global_load_dwordx4 v[154:157], v[82:83], off offset:16
	global_load_dwordx4 v[158:161], v[82:83], off
	v_add_u32_e32 v82, 0x400, v76
	v_ashrrev_i32_e32 v83, 31, v82
	v_lshl_add_u64 v[82:83], v[82:83], 3, v[74:75]
	global_load_dwordx4 v[130:133], v[82:83], off offset:16
	global_load_dwordx4 v[134:137], v[82:83], off
	v_add_u32_e32 v82, 0x800, v76
	v_ashrrev_i32_e32 v83, 31, v82
	v_add_u32_e32 v76, 0xc00, v76
	v_lshl_add_u64 v[82:83], v[82:83], 3, v[74:75]
	v_ashrrev_i32_e32 v77, 31, v76
	global_load_dwordx4 v[106:109], v[82:83], off offset:16
	global_load_dwordx4 v[110:113], v[82:83], off
	v_lshl_add_u64 v[82:83], v[76:77], 3, v[74:75]
	global_load_dwordx4 v[74:77], v[82:83], off offset:16
	s_nop 0
	global_load_dwordx4 v[82:85], v[82:83], off

; #define PG8_STAGE(bufoff, gbase, voff) do { _Pragma("unroll") for (int _i = 0; _i < 2; ++_i) \
;         __builtin_amdgcn_global_load_lds((const unsigned*)((const char*)(gbase) + (voff)[_i]), (LAS unsigned*)(lds + (bufoff) + ldsw + _i * 8192), 16, 0, 0); } while (0)
; #define PG8_LDA(dst, b, h) do { _Pragma("unroll") for (int m = 0; m < 4; ++m) _Pragma("unroll") for (int k = 0; k < 2; ++k) dst[m][k] = *(const LAS bf16x8*)(lds + PG8_SA(b, h) + aoff + m * 2048 + k * 1024); } while (0)
; #define PG8_LDB(dst, b, h) do { _Pragma("unroll") for (int n = 0; n < 2; ++n) _Pragma("unroll") for (int k = 0; k < 2; ++k) dst[n][k] = *(const LAS bf16x8*)(lds + PG8_SB(b, h) + boff + n * 2048 + k * 1024); } while (0)
; #define PG8_MMA(ai, bj, At, Bt) do { __builtin_amdgcn_s_setprio(1); _Pragma("unroll") for (int m = 0; m < 4; ++m) _Pragma("unroll") for (int n = 0; n < 2; ++n) _Pragma("unroll") for (int k = 0; k < 2; ++k) \
;         acc[ai][bj][m][n] = __builtin_amdgcn_mfma_f32_16x16x32_bf16(Bt[n][k], At[m][k], acc[ai][bj][m][n], 0, 0, 0); __builtin_amdgcn_s_setprio(0); } while (0)
; #define PG8_WAIT_L(n) asm volatile("s_waitcnt lgkmcnt(" #n ")" ::: "memory")
; #define PG8_BAR __builtin_amdgcn_s_barrier()
; #define PG8_SCHED __builtin_amdgcn_sched_barrier(0)
; template <class Epi>
; __device__ __forceinline__ void gemm_phase(LAS unsigned char* lds, const Gemm g, const Epi& E) {
;     ...
;         for (int t = 0; t < nt; t += 2) {
;             const bool last = (t == nt - 2);
;             const char* a1 = cA + (size_t)(t + 1) * kstep;
;             const char* a2 = last ? nA : cA + (size_t)(t + 2) * kstep; const char* b2 = last ? nB : cB + (size_t)(t + 2) * kstep;
;             const char* a3 = a2 + kstep; const char* b3 = b2 + kstep;
;             PG8_LDB(B0, 0, 0); PG8_SCHED; PG8_LDA(At, 0, 0); PG8_STAGE(PG8_SA(1, 1), a1 + hstepA, voffA);
;             PG8_WAIT_L(8); PG8_BAR; PG8_WAIT_L(0); PG8_MMA(0, 0, At, B0); PG8_BAR; PG8_SCHED;
;             PG8_LDB(B1, 0, 1); PG8_STAGE(PG8_SB(0, 0), b2, voffB);
;             PG8_BAR; PG8_WAIT_L(0); PG8_MMA(0, 1, At, B1); PG8_BAR;
;             PG8_LDA(At, 0, 1); PG8_STAGE(PG8_SA(0, 0), a2, voffA);
;             PG8_BAR; PG8_WAIT_L(0); PG8_MMA(1, 0, At, B0); PG8_BAR; PG8_SCHED;
.LBB0_475:
	s_add_u32 s16, s14, 0xfffc0080
	s_addc_u32 s17, s15, -1
	s_add_i32 s66, 0, 0x10000
	v_add_u32_e32 v86, s66, v226
	ds_read_b128 v[66:69], v86
	ds_read_b128 v[70:73], v86 offset:1024
	ds_read_b128 v[82:85], v86 offset:2048
	ds_read_b128 v[86:89], v86 offset:3072
	s_cmp_eq_u32 s65, 12
	s_cselect_b32 s29, s11, s17
	s_cselect_b32 s28, s10, s16
	s_cselect_b32 s17, s5, s53
	s_cselect_b32 s16, s4, s9
	v_lshl_add_u64 v[192:193], s[14:15], 0, v[174:175]
	s_add_i32 m0, s13, 0xc000
	ds_read_b128 v[146:149], v227
	ds_read_b128 v[150:153], v227 offset:1024
	ds_read_b128 v[154:157], v227 offset:2048
	ds_read_b128 v[158:161], v227 offset:3072
	ds_read_b128 v[162:165], v227 offset:4096
	ds_read_b128 v[180:183], v227 offset:5120
	ds_read_b128 v[184:187], v227 offset:6144
	ds_read_b128 v[188:191], v227 offset:7168
	global_load_lds_dwordx4 v[192:193], off
	v_lshl_add_u64 v[192:193], s[14:15], 0, v[176:177]
	s_add_i32 m0, s13, 0xe000
	s_nop 0
	global_load_lds_dwordx4 v[192:193], off
	s_waitcnt lgkmcnt(0)
	s_barrier
	s_setprio 1
	v_mfma_f32_16x16x32_bf16 v[142:145], v[66:69], v[146:149], v[142:145]
	v_mfma_f32_16x16x32_bf16 v[138:141], v[82:85], v[146:149], v[138:141]
	v_mfma_f32_16x16x32_bf16 v[126:129], v[66:69], v[154:157], v[126:129]
	v_mfma_f32_16x16x32_bf16 v[122:125], v[82:85], v[154:157], v[122:125]
	v_mfma_f32_16x16x32_bf16 v[110:113], v[66:69], v[162:165], v[110:113]
	v_mfma_f32_16x16x32_bf16 v[106:109], v[82:85], v[162:165], v[106:109]
	v_mfma_f32_16x16x32_bf16 v[94:97], v[66:69], v[184:187], v[94:97]
	v_mfma_f32_16x16x32_bf16 v[90:93], v[82:85], v[184:187], v[90:93]
	v_mfma_f32_16x16x32_bf16 v[142:145], v[70:73], v[150:153], v[142:145]
	v_mfma_f32_16x16x32_bf16 v[138:141], v[86:89], v[150:153], v[138:141]
	v_mfma_f32_16x16x32_bf16 v[126:129], v[70:73], v[158:161], v[126:129]
	v_mfma_f32_16x16x32_bf16 v[122:125], v[86:89], v[158:161], v[122:125]
	v_mfma_f32_16x16x32_bf16 v[110:113], v[70:73], v[180:183], v[110:113]
	v_mfma_f32_16x16x32_bf16 v[106:109], v[86:89], v[180:183], v[106:109]
	v_mfma_f32_16x16x32_bf16 v[94:97], v[70:73], v[188:191], v[94:97]
	v_mfma_f32_16x16x32_bf16 v[90:93], v[86:89], v[188:191], v[90:93]
	s_setprio 0
	s_barrier
	s_add_i32 s68, 0, 0x14000
	s_add_i32 s66, s66, s18
	v_add_u32_e32 v204, s68, v226
	v_lshl_add_u64 v[208:209], s[16:17], 0, v[170:171]
	s_mov_b32 m0, s66
	ds_read_b128 v[192:195], v204
	ds_read_b128 v[196:199], v204 offset:1024
	ds_read_b128 v[200:203], v204 offset:2048
	ds_read_b128 v[204:207], v204 offset:3072
	global_load_lds_dwordx4 v[208:209], off
	v_lshl_add_u64 v[228:229], s[16:17], 0, v[166:167]
	s_add_i32 m0, s66, 0x2000
	s_nop 0
	global_load_lds_dwordx4 v[228:229], off
	s_waitcnt lgkmcnt(0)
	s_barrier
	s_setprio 1
	v_mfma_f32_16x16x32_bf16 v[134:137], v[192:195], v[146:149], v[134:137]
	v_mfma_f32_16x16x32_bf16 v[130:133], v[200:203], v[146:149], v[130:133]
	v_mfma_f32_16x16x32_bf16 v[118:121], v[192:195], v[154:157], v[118:121]
	v_mfma_f32_16x16x32_bf16 v[114:117], v[200:203], v[154:157], v[114:117]
	v_mfma_f32_16x16x32_bf16 v[102:105], v[192:195], v[162:165], v[102:105]
	v_mfma_f32_16x16x32_bf16 v[98:101], v[200:203], v[162:165], v[98:101]
	v_mfma_f32_16x16x32_bf16 v[78:81], v[192:195], v[184:187], v[78:81]
	v_mfma_f32_16x16x32_bf16 v[74:77], v[200:203], v[184:187], v[74:77]
	v_mfma_f32_16x16x32_bf16 v[134:137], v[196:199], v[150:153], v[134:137]
	v_mfma_f32_16x16x32_bf16 v[130:133], v[204:207], v[150:153], v[130:133]
	v_mfma_f32_16x16x32_bf16 v[118:121], v[196:199], v[158:161], v[118:121]
	v_mfma_f32_16x16x32_bf16 v[114:117], v[204:207], v[158:161], v[114:117]
	v_mfma_f32_16x16x32_bf16 v[102:105], v[196:199], v[180:183], v[102:105]
	v_mfma_f32_16x16x32_bf16 v[98:101], v[204:207], v[180:183], v[98:101]
	v_mfma_f32_16x16x32_bf16 v[78:81], v[196:199], v[188:191], v[78:81]
	v_mfma_f32_16x16x32_bf16 v[74:77], v[204:207], v[188:191], v[74:77]
	s_setprio 0
	s_mov_b32 m0, s13
	v_lshl_add_u64 v[230:231], s[28:29], 0, v[172:173]
	s_barrier
	ds_read_b128 v[146:149], v227 offset:16384
	ds_read_b128 v[150:153], v227 offset:17408
	ds_read_b128 v[154:157], v227 offset:18432
	ds_read_b128 v[158:161], v227 offset:19456
	ds_read_b128 v[162:165], v227 offset:20480
	ds_read_b128 v[180:183], v227 offset:21504
	ds_read_b128 v[184:187], v227 offset:22528
	ds_read_b128 v[188:191], v227 offset:23552
	global_load_lds_dwordx4 v[230:231], off
	v_lshl_add_u64 v[232:233], s[28:29], 0, v[168:169]
	s_mov_b32 m0, s31
	s_nop 0
	global_load_lds_dwordx4 v[232:233], off
	s_waitcnt lgkmcnt(0)
	s_barrier
	s_setprio 1
	v_mfma_f32_16x16x32_bf16 v[62:65], v[66:69], v[146:149], v[62:65]
	v_mfma_f32_16x16x32_bf16 v[58:61], v[82:85], v[146:149], v[58:61]
	v_mfma_f32_16x16x32_bf16 v[46:49], v[66:69], v[154:157], v[46:49]
	v_mfma_f32_16x16x32_bf16 v[42:45], v[82:85], v[154:157], v[42:45]
	v_mfma_f32_16x16x32_bf16 v[30:33], v[66:69], v[162:165], v[30:33]
	v_mfma_f32_16x16x32_bf16 v[26:29], v[82:85], v[162:165], v[26:29]
	v_mfma_f32_16x16x32_bf16 v[14:17], v[66:69], v[184:187], v[14:17]
	v_mfma_f32_16x16x32_bf16 v[10:13], v[82:85], v[184:187], v[10:13]
	v_mfma_f32_16x16x32_bf16 v[62:65], v[70:73], v[150:153], v[62:65]
	v_mfma_f32_16x16x32_bf16 v[58:61], v[86:89], v[150:153], v[58:61]
	v_mfma_f32_16x16x32_bf16 v[46:49], v[70:73], v[158:161], v[46:49]
	v_mfma_f32_16x16x32_bf16 v[42:45], v[86:89], v[158:161], v[42:45]
	v_mfma_f32_16x16x32_bf16 v[30:33], v[70:73], v[180:183], v[30:33]
	v_mfma_f32_16x16x32_bf16 v[26:29], v[86:89], v[180:183], v[26:29]
	v_mfma_f32_16x16x32_bf16 v[14:17], v[70:73], v[188:191], v[14:17]
	v_mfma_f32_16x16x32_bf16 v[10:13], v[86:89], v[188:191], v[10:13]
	s_setprio 0
	s_barrier
; #define PG8_STAGE(bufoff, gbase, voff) do { _Pragma("unroll") for (int _i = 0; _i < 2; ++_i) \
;         __builtin_amdgcn_global_load_lds((const unsigned*)((const char*)(gbase) + (voff)[_i]), (LAS unsigned*)(lds + (bufoff) + ldsw + _i * 8192), 16, 0, 0); } while (0)
; #define PG8_LDA(dst, b, h) do { _Pragma("unroll") for (int m = 0; m < 4; ++m) _Pragma("unroll") for (int k = 0; k < 2; ++k) dst[m][k] = *(const LAS bf16x8*)(lds + PG8_SA(b, h) + aoff + m * 2048 + k * 1024); } while (0)
; #define PG8_LDB(dst, b, h) do { _Pragma("unroll") for (int n = 0; n < 2; ++n) _Pragma("unroll") for (int k = 0; k < 2; ++k) dst[n][k] = *(const LAS bf16x8*)(lds + PG8_SB(b, h) + boff + n * 2048 + k * 1024); } while (0)
; #define PG8_MMA(ai, bj, At, Bt) do { __builtin_amdgcn_s_setprio(1); _Pragma("unroll") for (int m = 0; m < 4; ++m) _Pragma("unroll") for (int n = 0; n < 2; ++n) _Pragma("unroll") for (int k = 0; k < 2; ++k) \
;         acc[ai][bj][m][n] = __builtin_amdgcn_mfma_f32_16x16x32_bf16(Bt[n][k], At[m][k], acc[ai][bj][m][n], 0, 0, 0); __builtin_amdgcn_s_setprio(0); } while (0)
; #define PG8_WAIT_V(n) asm volatile("s_waitcnt vmcnt(" #n ")" ::: "memory")
; #define PG8_WAIT_L(n) asm volatile("s_waitcnt lgkmcnt(" #n ")" ::: "memory")
; #define PG8_BAR __builtin_amdgcn_s_barrier()
; #define PG8_SCHED __builtin_amdgcn_sched_barrier(0)
; template <class Epi>
; __device__ __forceinline__ void gemm_phase(LAS unsigned char* lds, const Gemm g, const Epi& E) {
;     ...
;             PG8_STAGE(PG8_SB(0, 1), b2 + hstepB, voffB);
;             PG8_WAIT_V(6); PG8_BAR; PG8_MMA(1, 1, At, B1); PG8_BAR;
;             PG8_LDB(B0, 1, 0); PG8_SCHED; PG8_LDA(At, 1, 0); PG8_STAGE(PG8_SA(0, 1), a2 + hstepA, voffA);
;             PG8_WAIT_L(8); PG8_BAR; PG8_WAIT_L(0); PG8_MMA(0, 0, At, B0); PG8_BAR; PG8_SCHED;
;             PG8_LDB(B1, 1, 1); PG8_STAGE(PG8_SB(1, 0), b3, voffB);
;             PG8_BAR; PG8_WAIT_L(0); PG8_MMA(0, 1, At, B1); PG8_BAR;
;             PG8_LDA(At, 1, 1); PG8_STAGE(PG8_SA(1, 0), a3, voffA);
	s_add_u32 s66, s16, 0x40000
	s_addc_u32 s67, s17, 0
	s_add_i32 s68, s68, s18
	v_lshl_add_u64 v[66:67], s[66:67], 0, v[170:171]
	s_mov_b32 m0, s68
	s_nop 0
	global_load_lds_dwordx4 v[66:67], off
	v_lshl_add_u64 v[66:67], s[66:67], 0, v[166:167]
	s_add_i32 m0, s68, 0x2000
	s_nop 0
	global_load_lds_dwordx4 v[66:67], off
	s_waitcnt vmcnt(6)
	s_barrier
	s_setprio 1
	v_mfma_f32_16x16x32_bf16 v[54:57], v[192:195], v[146:149], v[54:57]
	v_mfma_f32_16x16x32_bf16 v[50:53], v[200:203], v[146:149], v[50:53]
	v_mfma_f32_16x16x32_bf16 v[38:41], v[192:195], v[154:157], v[38:41]
	v_mfma_f32_16x16x32_bf16 v[34:37], v[200:203], v[154:157], v[34:37]
	v_mfma_f32_16x16x32_bf16 v[22:25], v[192:195], v[162:165], v[22:25]
	v_mfma_f32_16x16x32_bf16 v[18:21], v[200:203], v[162:165], v[18:21]
	v_mfma_f32_16x16x32_bf16 v[6:9], v[192:195], v[184:187], v[6:9]
	v_mfma_f32_16x16x32_bf16 v[2:5], v[200:203], v[184:187], v[2:5]
	v_mfma_f32_16x16x32_bf16 v[54:57], v[196:199], v[150:153], v[54:57]
	v_mfma_f32_16x16x32_bf16 v[50:53], v[204:207], v[150:153], v[50:53]
	v_mfma_f32_16x16x32_bf16 v[38:41], v[196:199], v[158:161], v[38:41]
	v_mfma_f32_16x16x32_bf16 v[34:37], v[204:207], v[158:161], v[34:37]
	v_mfma_f32_16x16x32_bf16 v[22:25], v[196:199], v[180:183], v[22:25]
	v_mfma_f32_16x16x32_bf16 v[18:21], v[204:207], v[180:183], v[18:21]
	v_mfma_f32_16x16x32_bf16 v[6:9], v[196:199], v[188:191], v[6:9]
	v_mfma_f32_16x16x32_bf16 v[2:5], v[204:207], v[188:191], v[2:5]
	s_setprio 0
	s_add_i32 s66, 0, 0x18000
	v_add_u32_e32 v86, s66, v226
	s_barrier
	ds_read_b128 v[66:69], v86
	ds_read_b128 v[70:73], v86 offset:1024
	ds_read_b128 v[82:85], v86 offset:2048
	ds_read_b128 v[86:89], v86 offset:3072
	s_add_u32 s28, s28, 0x40000
	s_addc_u32 s29, s29, 0
	s_mov_b32 m0, s36
	v_lshl_add_u64 v[192:193], s[28:29], 0, v[172:173]
	ds_read_b128 v[146:149], v227 offset:32768
	ds_read_b128 v[150:153], v227 offset:33792
	ds_read_b128 v[154:157], v227 offset:34816
	ds_read_b128 v[158:161], v227 offset:35840
	ds_read_b128 v[162:165], v227 offset:36864
	ds_read_b128 v[180:183], v227 offset:37888
	ds_read_b128 v[184:187], v227 offset:38912
	ds_read_b128 v[188:191], v227 offset:39936
	global_load_lds_dwordx4 v[192:193], off
	v_lshl_add_u64 v[192:193], s[28:29], 0, v[168:169]
	s_mov_b32 m0, s44
	s_nop 0
	global_load_lds_dwordx4 v[192:193], off
	s_waitcnt lgkmcnt(0)
	s_barrier
	s_setprio 1
	v_mfma_f32_16x16x32_bf16 v[142:145], v[66:69], v[146:149], v[142:145]
	v_mfma_f32_16x16x32_bf16 v[138:141], v[82:85], v[146:149], v[138:141]
	v_mfma_f32_16x16x32_bf16 v[126:129], v[66:69], v[154:157], v[126:129]
	v_mfma_f32_16x16x32_bf16 v[122:125], v[82:85], v[154:157], v[122:125]
	v_mfma_f32_16x16x32_bf16 v[110:113], v[66:69], v[162:165], v[110:113]
	v_mfma_f32_16x16x32_bf16 v[106:109], v[82:85], v[162:165], v[106:109]
	v_mfma_f32_16x16x32_bf16 v[94:97], v[66:69], v[184:187], v[94:97]
	v_mfma_f32_16x16x32_bf16 v[90:93], v[82:85], v[184:187], v[90:93]
	v_mfma_f32_16x16x32_bf16 v[142:145], v[70:73], v[150:153], v[142:145]
	v_mfma_f32_16x16x32_bf16 v[138:141], v[86:89], v[150:153], v[138:141]
	v_mfma_f32_16x16x32_bf16 v[126:129], v[70:73], v[158:161], v[126:129]
	v_mfma_f32_16x16x32_bf16 v[122:125], v[86:89], v[158:161], v[122:125]
	v_mfma_f32_16x16x32_bf16 v[110:113], v[70:73], v[180:183], v[110:113]
	v_mfma_f32_16x16x32_bf16 v[106:109], v[86:89], v[180:183], v[106:109]
	v_mfma_f32_16x16x32_bf16 v[94:97], v[70:73], v[188:191], v[94:97]
	v_mfma_f32_16x16x32_bf16 v[90:93], v[86:89], v[188:191], v[90:93]
	s_setprio 0
	s_barrier
	s_add_i32 s28, 0, 0x1c000
	s_add_i32 s29, s66, s18
	v_add_u32_e32 v204, s28, v226
	v_lshl_add_u64 v[208:209], v[208:209], 0, s[86:87]
	s_mov_b32 m0, s29
	ds_read_b128 v[192:195], v204
	ds_read_b128 v[196:199], v204 offset:1024
	ds_read_b128 v[200:203], v204 offset:2048
	ds_read_b128 v[204:207], v204 offset:3072
	global_load_lds_dwordx4 v[208:209], off
	v_lshl_add_u64 v[208:209], v[228:229], 0, s[86:87]
	s_add_i32 m0, s29, 0x2000
	s_nop 0
	global_load_lds_dwordx4 v[208:209], off
	s_waitcnt lgkmcnt(0)
	s_barrier
	s_setprio 1
	v_mfma_f32_16x16x32_bf16 v[134:137], v[192:195], v[146:149], v[134:137]
	v_mfma_f32_16x16x32_bf16 v[130:133], v[200:203], v[146:149], v[130:133]
	v_mfma_f32_16x16x32_bf16 v[118:121], v[192:195], v[154:157], v[118:121]
	v_mfma_f32_16x16x32_bf16 v[114:117], v[200:203], v[154:157], v[114:117]
	v_mfma_f32_16x16x32_bf16 v[102:105], v[192:195], v[162:165], v[102:105]
	v_mfma_f32_16x16x32_bf16 v[98:101], v[200:203], v[162:165], v[98:101]
	v_mfma_f32_16x16x32_bf16 v[78:81], v[192:195], v[184:187], v[78:81]
	v_mfma_f32_16x16x32_bf16 v[74:77], v[200:203], v[184:187], v[74:77]
	v_mfma_f32_16x16x32_bf16 v[134:137], v[196:199], v[150:153], v[134:137]
	v_mfma_f32_16x16x32_bf16 v[130:133], v[204:207], v[150:153], v[130:133]
	v_mfma_f32_16x16x32_bf16 v[118:121], v[196:199], v[158:161], v[118:121]
	v_mfma_f32_16x16x32_bf16 v[114:117], v[204:207], v[158:161], v[114:117]
	v_mfma_f32_16x16x32_bf16 v[102:105], v[196:199], v[180:183], v[102:105]
	v_mfma_f32_16x16x32_bf16 v[98:101], v[204:207], v[180:183], v[98:101]
	v_mfma_f32_16x16x32_bf16 v[78:81], v[196:199], v[188:191], v[78:81]
	v_mfma_f32_16x16x32_bf16 v[74:77], v[204:207], v[188:191], v[74:77]
	s_setprio 0
	s_mov_b32 m0, s59
	v_lshl_add_u64 v[208:209], v[230:231], 0, s[86:87]
	s_barrier
	ds_read_b128 v[146:149], v227 offset:49152
	ds_read_b128 v[150:153], v227 offset:50176
	ds_read_b128 v[154:157], v227 offset:51200
	ds_read_b128 v[158:161], v227 offset:52224
	ds_read_b128 v[162:165], v227 offset:53248
	ds_read_b128 v[180:183], v227 offset:54272
	ds_read_b128 v[184:187], v227 offset:55296
	ds_read_b128 v[188:191], v227 offset:56320
	global_load_lds_dwordx4 v[208:209], off
	v_lshl_add_u64 v[208:209], v[232:233], 0, s[86:87]
	s_mov_b32 m0, s60
	s_nop 0
	global_load_lds_dwordx4 v[208:209], off
	s_waitcnt lgkmcnt(0)
	s_barrier
; #define PG8_STAGE(bufoff, gbase, voff) do { _Pragma("unroll") for (int _i = 0; _i < 2; ++_i) \
;         __builtin_amdgcn_global_load_lds((const unsigned*)((const char*)(gbase) + (voff)[_i]), (LAS unsigned*)(lds + (bufoff) + ldsw + _i * 8192), 16, 0, 0); } while (0)
; #define PG8_MMA(ai, bj, At, Bt) do { __builtin_amdgcn_s_setprio(1); _Pragma("unroll") for (int m = 0; m < 4; ++m) _Pragma("unroll") for (int n = 0; n < 2; ++n) _Pragma("unroll") for (int k = 0; k < 2; ++k) \
;         acc[ai][bj][m][n] = __builtin_amdgcn_mfma_f32_16x16x32_bf16(Bt[n][k], At[m][k], acc[ai][bj][m][n], 0, 0, 0); __builtin_amdgcn_s_setprio(0); } while (0)
; #define PG8_WAIT_V(n) asm volatile("s_waitcnt vmcnt(" #n ")" ::: "memory")
; #define PG8_WAIT_L(n) asm volatile("s_waitcnt lgkmcnt(" #n ")" ::: "memory")
; #define PG8_BAR __builtin_amdgcn_s_barrier()
; #define PG8_SCHED __builtin_amdgcn_sched_barrier(0)
; template <class Epi>
; __device__ __forceinline__ void gemm_phase(LAS unsigned char* lds, const Gemm g, const Epi& E) {
;     ...
;             PG8_BAR; PG8_WAIT_L(0); PG8_MMA(1, 0, At, B0); PG8_BAR; PG8_SCHED;
;             PG8_STAGE(PG8_SB(1, 1), b3 + hstepB, voffB);
;             PG8_WAIT_V(6); PG8_BAR; PG8_MMA(1, 1, At, B1); PG8_BAR;
;         }
;     __device__ __forceinline__ void operator()(const AccT& acc, const Unit& u, int wr, int wc, int fr, int fq) const {
;     ...
;         const int row0 = mapA.src(u.pm) * 256 + wr * 64 + fr, col0 = u.pn * 256 + wc * 32 + 8 * fq;
;         const int hd = u.pn >> 1;
;         f32x4 gw[2][2]; f32x2 st[2][4];
; #pragma unroll
;         for (int bj = 0; bj < 2; ++bj) { gw[bj][0] = *(const f32x4*)(gnw + col0 + bj * 128); gw[bj][1] = *(const f32x4*)(gnw + col0 + bj * 128 + 4); }
; #pragma unroll
;         for (int ai = 0; ai < 2; ++ai)
; #pragma unroll
;             for (int m = 0; m < 4; ++m) st[ai][m] = ST[(size_t)(row0 + ai * 128 + m * 16) * 4 + hd];
; #pragma unroll
;         for (int ai = 0; ai < 2; ++ai) {
;             u32x4 yv[4][2];
; #pragma unroll
;             for (int m = 0; m < 4; ++m)
; #pragma unroll
;                 for (int bj = 0; bj < 2; ++bj) yv[m][bj] = *(const u32x4*)(Y + (size_t)(row0 + ai * 128 + m * 16) * 2048 + col0 + bj * 128);
	s_setprio 1
	v_mfma_f32_16x16x32_bf16 v[62:65], v[66:69], v[146:149], v[62:65]
	v_mfma_f32_16x16x32_bf16 v[58:61], v[82:85], v[146:149], v[58:61]
	v_mfma_f32_16x16x32_bf16 v[46:49], v[66:69], v[154:157], v[46:49]
	v_mfma_f32_16x16x32_bf16 v[42:45], v[82:85], v[154:157], v[42:45]
	v_mfma_f32_16x16x32_bf16 v[30:33], v[66:69], v[162:165], v[30:33]
	v_mfma_f32_16x16x32_bf16 v[26:29], v[82:85], v[162:165], v[26:29]
	v_mfma_f32_16x16x32_bf16 v[14:17], v[66:69], v[184:187], v[14:17]
	v_mfma_f32_16x16x32_bf16 v[10:13], v[82:85], v[184:187], v[10:13]
	v_mfma_f32_16x16x32_bf16 v[62:65], v[70:73], v[150:153], v[62:65]
	v_mfma_f32_16x16x32_bf16 v[58:61], v[86:89], v[150:153], v[58:61]
	v_mfma_f32_16x16x32_bf16 v[46:49], v[70:73], v[158:161], v[46:49]
	v_mfma_f32_16x16x32_bf16 v[42:45], v[86:89], v[158:161], v[42:45]
	v_mfma_f32_16x16x32_bf16 v[30:33], v[70:73], v[180:183], v[30:33]
	v_mfma_f32_16x16x32_bf16 v[26:29], v[86:89], v[180:183], v[26:29]
	v_mfma_f32_16x16x32_bf16 v[14:17], v[70:73], v[188:191], v[14:17]
	v_mfma_f32_16x16x32_bf16 v[10:13], v[86:89], v[188:191], v[10:13]
	s_setprio 0
	s_barrier
	s_add_u32 s16, s16, 0x40080
	s_addc_u32 s17, s17, 0
	s_add_i32 s28, s28, s18
	v_lshl_add_u64 v[66:67], s[16:17], 0, v[170:171]
	s_mov_b32 m0, s28
	s_nop 0
	global_load_lds_dwordx4 v[66:67], off
	v_lshl_add_u64 v[66:67], s[16:17], 0, v[166:167]
	s_add_i32 m0, s28, 0x2000
	s_nop 0
	global_load_lds_dwordx4 v[66:67], off
	s_waitcnt vmcnt(6)
	s_barrier
	s_setprio 1
	v_mfma_f32_16x16x32_bf16 v[54:57], v[192:195], v[146:149], v[54:57]
	v_mfma_f32_16x16x32_bf16 v[50:53], v[200:203], v[146:149], v[50:53]
	v_mfma_f32_16x16x32_bf16 v[38:41], v[192:195], v[154:157], v[38:41]
	v_mfma_f32_16x16x32_bf16 v[34:37], v[200:203], v[154:157], v[34:37]
	v_mfma_f32_16x16x32_bf16 v[22:25], v[192:195], v[162:165], v[22:25]
	v_mfma_f32_16x16x32_bf16 v[18:21], v[200:203], v[162:165], v[18:21]
	v_mfma_f32_16x16x32_bf16 v[6:9], v[192:195], v[184:187], v[6:9]
	v_mfma_f32_16x16x32_bf16 v[2:5], v[200:203], v[184:187], v[2:5]
	v_mfma_f32_16x16x32_bf16 v[54:57], v[196:199], v[150:153], v[54:57]
	v_mfma_f32_16x16x32_bf16 v[50:53], v[204:207], v[150:153], v[50:53]
	v_mfma_f32_16x16x32_bf16 v[38:41], v[196:199], v[158:161], v[38:41]
	v_mfma_f32_16x16x32_bf16 v[34:37], v[204:207], v[158:161], v[34:37]
	v_mfma_f32_16x16x32_bf16 v[22:25], v[196:199], v[180:183], v[22:25]
	v_mfma_f32_16x16x32_bf16 v[18:21], v[204:207], v[180:183], v[18:21]
	v_mfma_f32_16x16x32_bf16 v[6:9], v[196:199], v[188:191], v[6:9]
	v_mfma_f32_16x16x32_bf16 v[2:5], v[204:207], v[188:191], v[2:5]
	s_setprio 0
	s_add_i32 s65, s65, 2
	s_add_u32 s14, s14, 0x100
	s_addc_u32 s15, s15, 0
	s_add_u32 s9, s9, 0x100
	s_addc_u32 s53, s53, 0
	s_cmp_gt_u32 s65, 13
	s_barrier
	s_cbranch_scc0 .LBB0_475
	v_readlane_b32 s9, v255, 27
	s_cmp_ge_i32 s52, s9
	s_cselect_b32 s9, s25, 0
	s_lshl_b32 s14, s12, 8
	v_mov_b32_e32 v148, v225
	v_mov_b32_e32 v66, v1
	s_add_i32 s9, s52, s9
	s_or_b32 s14, s14, s58
	s_lshl_b32 s9, s9, 8
	v_lshl_add_u32 v146, v66, 3, s14
	s_ashr_i32 s14, s12, 1
	s_add_i32 s9, s9, s50
	s_ashr_i32 s15, s14, 31
	v_add_u32_e32 v148, s9, v148
	s_lshl_b64 s[14:15], s[14:15], 3
	s_add_u32 s14, s26, s14
	v_ashrrev_i32_e32 v149, 31, v148
	v_add_u32_e32 v152, 16, v148
	v_add_u32_e32 v156, 32, v148
	v_add_u32_e32 v202, 48, v148
	v_ashrrev_i32_e32 v147, 31, v146
	s_addc_u32 s15, s27, s15
	v_lshlrev_b64 v[150:151], 5, v[148:149]
	v_ashrrev_i32_e32 v153, 31, v152
	v_ashrrev_i32_e32 v157, 31, v156
	v_ashrrev_i32_e32 v203, 31, v202
	v_add_u32_e32 v190, 0x80, v148
	v_lshl_add_u64 v[70:71], v[146:147], 2, s[6:7]
	v_lshl_add_u64 v[150:151], s[14:15], 0, v[150:151]
	v_lshlrev_b64 v[154:155], 5, v[152:153]
	v_lshlrev_b64 v[158:159], 5, v[156:157]
	v_lshlrev_b64 v[160:161], 5, v[202:203]
	v_ashrrev_i32_e32 v191, 31, v190
	v_add_u32_e32 v192, 0x90, v148
	v_add_u32_e32 v194, 0xa0, v148
	v_add_u32_e32 v196, 0xb0, v148
	v_lshlrev_b64 v[182:183], 1, v[146:147]
	global_load_dwordx4 v[82:85], v[70:71], off offset:16
	global_load_dwordx4 v[86:89], v[70:71], off
	global_load_dwordx4 v[66:69], v[70:71], off offset:528
	s_nop 0
	global_load_dwordx4 v[70:73], v[70:71], off offset:512
	v_lshl_add_u64 v[154:155], s[14:15], 0, v[154:155]
	v_lshl_add_u64 v[158:159], s[14:15], 0, v[158:159]
	v_lshl_add_u64 v[160:161], s[14:15], 0, v[160:161]
	global_load_dwordx2 v[240:241], v[150:151], off
	global_load_dwordx2 v[208:209], v[154:155], off
	global_load_dwordx2 v[204:205], v[158:159], off
	global_load_dwordx2 v[200:201], v[160:161], off
	v_lshlrev_b64 v[150:151], 5, v[190:191]
	v_ashrrev_i32_e32 v193, 31, v192
	v_ashrrev_i32_e32 v195, 31, v194
	v_ashrrev_i32_e32 v197, 31, v196
	v_lshl_add_u64 v[198:199], s[38:39], 0, v[182:183]
	v_lshlrev_b64 v[242:243], 12, v[148:149]
	v_lshl_add_u64 v[150:151], s[14:15], 0, v[150:151]
	v_lshlrev_b64 v[154:155], 5, v[192:193]
	v_lshlrev_b64 v[158:159], 5, v[194:195]
	v_lshlrev_b64 v[160:161], 5, v[196:197]
	v_lshl_add_u64 v[146:147], v[198:199], 0, v[242:243]
	v_lshlrev_b64 v[244:245], 12, v[152:153]
	v_lshl_add_u64 v[154:155], s[14:15], 0, v[154:155]
	v_lshl_add_u64 v[158:159], s[14:15], 0, v[158:159]
	v_lshl_add_u64 v[160:161], s[14:15], 0, v[160:161]
	global_load_dwordx2 v[188:189], v[150:151], off
	global_load_dwordx2 v[186:187], v[154:155], off
	global_load_dwordx2 v[184:185], v[158:159], off
	global_load_dwordx2 v[180:181], v[160:161], off
	global_load_dwordx4 v[228:231], v[146:147], off
	global_load_dwordx4 v[232:235], v[146:147], off offset:256
	v_lshl_add_u64 v[146:147], v[198:199], 0, v[244:245]
	v_lshlrev_b64 v[206:207], 12, v[156:157]
	global_load_dwordx4 v[236:239], v[146:147], off
	global_load_dwordx4 v[162:165], v[146:147], off offset:256
	v_lshl_add_u64 v[146:147], v[198:199], 0, v[206:207]
	v_lshlrev_b64 v[202:203], 12, v[202:203]
	global_load_dwordx4 v[158:161], v[146:147], off
	global_load_dwordx4 v[154:157], v[146:147], off offset:256
	v_lshl_add_u64 v[146:147], v[198:199], 0, v[202:203]
	global_load_dwordx4 v[150:153], v[146:147], off
	s_nop 0
	global_load_dwordx4 v[146:149], v[146:147], off offset:256
	s_waitcnt vmcnt(0)
; __device__ __forceinline__ unsigned cvt_pk_bf16(float lo, float hi) { unsigned r; asm("v_cvt_pk_bf16_f32 %0, %1, %2" : "=v"(r) : "v"(lo), "v"(hi)); return r; }
; __device__ __forceinline__ float bf_lo(unsigned u) { return __uint_as_float(u << 16); }
; __device__ __forceinline__ float bf_hi(unsigned u) { return __uint_as_float(u & 0xffff0000u); }
;     __device__ __forceinline__ void operator()(const AccT& acc, const Unit& u, int wr, int wc, int fr, int fq) const {
;     ...
;         for (int ai = 0; ai < 2; ++ai) {
;             u32x4 yv[4][2];
; #pragma unroll
;             for (int m = 0; m < 4; ++m)
; #pragma unroll
;                 for (int bj = 0; bj < 2; ++bj) yv[m][bj] = *(const u32x4*)(Y + (size_t)(row0 + ai * 128 + m * 16) * 2048 + col0 + bj * 128);
;             __builtin_amdgcn_sched_barrier(0);
; #pragma unroll
;             for (int m = 0; m < 4; ++m) { bf16_t* rowp = A2 + (size_t)(row0 + ai * 128 + m * 16) * 2048 + col0;
;                 const float mu = st[ai][m][0], rs = st[ai][m][1];
; #pragma unroll
;                 for (int bj = 0; bj < 2; ++bj) { const f32x4 v0 = acc[ai][bj][m][0], v1 = acc[ai][bj][m][1]; const u32x4 yw = yv[m][bj];
;                     const f32x4 y0 = (f32x4){bf_lo(yw.x), bf_hi(yw.x), bf_lo(yw.y), bf_hi(yw.y)}, y1 = (f32x4){bf_lo(yw.z), bf_hi(yw.z), bf_lo(yw.w), bf_hi(yw.w)};
;                     const f32x4 n0 = (y0 - mu) * rs * gw[bj][0], n1 = (y1 - mu) * rs * gw[bj][1];
;                     const f32x4 s0 = silu4(v0) * n0, s1 = silu4(v1) * n1;
;                     u32x4 w; w.x = cvt_pk_bf16(s0[0], s0[1]); w.y = cvt_pk_bf16(s0[2], s0[3]); w.z = cvt_pk_bf16(s1[0], s1[1]); w.w = cvt_pk_bf16(s1[2], s1[3]);
;                     *(u32x4*)(rowp + bj * 128) = w; } }
	v_lshlrev_b32_e32 v246, 16, v228
	v_and_b32_e32 v228, 0xffff0000, v228
	v_lshlrev_b32_e32 v247, 16, v229
	v_and_b32_e32 v248, 0xffff0000, v229
	v_lshlrev_b32_e32 v249, 16, v230
	v_and_b32_e32 v250, 0xffff0000, v230
	v_lshlrev_b32_e32 v251, 16, v231
	v_and_b32_e32 v252, 0xffff0000, v231
	v_sub_f32_e32 v229, v228, v240
	v_sub_f32_e32 v228, v246, v240
	v_sub_f32_e32 v231, v248, v240
	v_sub_f32_e32 v230, v247, v240
	v_sub_f32_e32 v247, v250, v240
	v_sub_f32_e32 v246, v249, v240
	v_sub_f32_e32 v249, v252, v240
	v_sub_f32_e32 v248, v251, v240
	v_mul_f32_e32 v250, 0xbfb8aa3b, v142
	v_mul_f32_e32 v251, 0xbfb8aa3b, v143
	v_mul_f32_e32 v252, 0xbfb8aa3b, v144
	v_mul_f32_e32 v253, 0xbfb8aa3b, v145
	v_exp_f32_e32 v250, v250
	v_exp_f32_e32 v251, v251
	v_exp_f32_e32 v252, v252
	v_exp_f32_e32 v253, v253
	v_add_f32_e32 v250, 1.0, v250
	v_add_f32_e32 v251, 1.0, v251
	v_add_f32_e32 v252, 1.0, v252
	v_add_f32_e32 v253, 1.0, v253
	v_rcp_f32_e32 v250, v250
	v_rcp_f32_e32 v251, v251
	v_rcp_f32_e32 v252, v252
	v_rcp_f32_e32 v253, v253
	v_pk_mul_f32 v[228:229], v[240:241], v[228:229] op_sel:[1,0]
	v_pk_mul_f32 v[142:143], v[142:143], v[250:251]
	v_mul_f32_e32 v250, 0xbfb8aa3b, v138
	v_pk_mul_f32 v[144:145], v[144:145], v[252:253]
	v_mul_f32_e32 v251, 0xbfb8aa3b, v139
	v_mul_f32_e32 v252, 0xbfb8aa3b, v140
	v_mul_f32_e32 v253, 0xbfb8aa3b, v141
	v_exp_f32_e32 v250, v250
	v_exp_f32_e32 v251, v251
	v_exp_f32_e32 v252, v252
	v_exp_f32_e32 v253, v253
	v_add_f32_e32 v250, 1.0, v250
	v_add_f32_e32 v251, 1.0, v251
	v_add_f32_e32 v252, 1.0, v252
	v_add_f32_e32 v253, 1.0, v253
	v_rcp_f32_e32 v250, v250
	v_rcp_f32_e32 v251, v251
	v_rcp_f32_e32 v252, v252
	v_rcp_f32_e32 v253, v253
	v_pk_mul_f32 v[248:249], v[240:241], v[248:249] op_sel:[1,0]
	v_pk_mul_f32 v[246:247], v[240:241], v[246:247] op_sel:[1,0]
	v_pk_mul_f32 v[230:231], v[240:241], v[230:231] op_sel:[1,0]
	v_pk_mul_f32 v[228:229], v[86:87], v[228:229]
	v_pk_mul_f32 v[246:247], v[82:83], v[246:247]
	v_pk_mul_f32 v[248:249], v[84:85], v[248:249]
	v_pk_mul_f32 v[138:139], v[138:139], v[250:251]
	v_pk_mul_f32 v[140:141], v[140:141], v[252:253]
	v_pk_mul_f32 v[230:231], v[88:89], v[230:231]
	v_pk_mul_f32 v[142:143], v[142:143], v[228:229]
	v_pk_mul_f32 v[228:229], v[140:141], v[248:249]
	v_pk_mul_f32 v[140:141], v[138:139], v[246:247]
	v_pk_mul_f32 v[144:145], v[144:145], v[230:231]
	v_cvt_pk_bf16_f32 v140, v140, v141
	v_cvt_pk_bf16_f32 v141, v228, v229
	v_mul_f32_e32 v228, 0xbfb8aa3b, v134
	v_mul_f32_e32 v229, 0xbfb8aa3b, v135
	v_mul_f32_e32 v230, 0xbfb8aa3b, v136
	v_mul_f32_e32 v231, 0xbfb8aa3b, v137
	v_exp_f32_e32 v228, v228
	v_exp_f32_e32 v229, v229
	v_exp_f32_e32 v230, v230
	v_exp_f32_e32 v231, v231
	v_add_f32_e32 v228, 1.0, v228
	v_add_f32_e32 v229, 1.0, v229
	v_add_f32_e32 v230, 1.0, v230
	v_add_f32_e32 v231, 1.0, v231
	v_rcp_f32_e32 v228, v228
	v_rcp_f32_e32 v229, v229
	v_rcp_f32_e32 v230, v230
	v_rcp_f32_e32 v231, v231
	v_lshl_add_u64 v[242:243], s[34:35], 0, v[242:243]
	v_pk_mul_f32 v[134:135], v[134:135], v[228:229]
	v_mul_f32_e32 v228, 0xbfb8aa3b, v130
	v_pk_mul_f32 v[136:137], v[136:137], v[230:231]
	v_mul_f32_e32 v229, 0xbfb8aa3b, v131
	v_mul_f32_e32 v230, 0xbfb8aa3b, v132
	v_mul_f32_e32 v231, 0xbfb8aa3b, v133
	v_exp_f32_e32 v228, v228
	v_exp_f32_e32 v229, v229
	v_exp_f32_e32 v230, v230
	v_exp_f32_e32 v231, v231
	v_add_f32_e32 v228, 1.0, v228
	v_add_f32_e32 v229, 1.0, v229
	v_add_f32_e32 v230, 1.0, v230
	v_add_f32_e32 v231, 1.0, v231
	v_lshl_add_u64 v[242:243], v[242:243], 0, v[182:183]
	v_cvt_pk_bf16_f32 v138, v142, v143
	v_cvt_pk_bf16_f32 v139, v144, v145
	v_rcp_f32_e32 v228, v228
	v_rcp_f32_e32 v229, v229
	v_rcp_f32_e32 v230, v230
	v_rcp_f32_e32 v231, v231
	global_store_dwordx4 v[242:243], v[138:141], off
	v_lshlrev_b32_e32 v142, 16, v234
	v_and_b32_e32 v143, 0xffff0000, v234
	v_lshlrev_b32_e32 v138, 16, v232
	v_and_b32_e32 v139, 0xffff0000, v232
	v_lshlrev_b32_e32 v140, 16, v233
	v_and_b32_e32 v141, 0xffff0000, v233
	v_lshlrev_b32_e32 v144, 16, v235
	v_and_b32_e32 v145, 0xffff0000, v235
	v_sub_f32_e32 v139, v139, v240
	v_sub_f32_e32 v138, v138, v240
	v_sub_f32_e32 v141, v141, v240
	v_sub_f32_e32 v140, v140, v240
	v_sub_f32_e32 v143, v143, v240
	v_sub_f32_e32 v142, v142, v240
	v_sub_f32_e32 v145, v145, v240
	v_sub_f32_e32 v144, v144, v240
	v_pk_mul_f32 v[140:141], v[240:241], v[140:141] op_sel:[1,0]
	v_pk_mul_f32 v[138:139], v[240:241], v[138:139] op_sel:[1,0]
	v_pk_mul_f32 v[144:145], v[240:241], v[144:145] op_sel:[1,0]
	v_pk_mul_f32 v[142:143], v[240:241], v[142:143] op_sel:[1,0]
	v_pk_mul_f32 v[138:139], v[70:71], v[138:139]
	v_pk_mul_f32 v[140:141], v[72:73], v[140:141]
	v_pk_mul_f32 v[142:143], v[66:67], v[142:143]
	v_pk_mul_f32 v[144:145], v[68:69], v[144:145]
	v_pk_mul_f32 v[130:131], v[130:131], v[228:229]
	v_pk_mul_f32 v[132:133], v[132:133], v[230:231]
	v_pk_mul_f32 v[136:137], v[136:137], v[140:141]
	v_pk_mul_f32 v[134:135], v[134:135], v[138:139]
	v_pk_mul_f32 v[138:139], v[132:133], v[144:145]
	v_pk_mul_f32 v[132:133], v[130:131], v[142:143]
	v_mul_f32_e32 v140, 0xbfb8aa3b, v126
	v_mul_f32_e32 v141, 0xbfb8aa3b, v127
	v_mul_f32_e32 v142, 0xbfb8aa3b, v128
	v_mul_f32_e32 v143, 0xbfb8aa3b, v129
	v_exp_f32_e32 v140, v140
	v_exp_f32_e32 v141, v141
	v_exp_f32_e32 v142, v142
	v_exp_f32_e32 v143, v143
	v_add_f32_e32 v140, 1.0, v140
	v_add_f32_e32 v141, 1.0, v141
	v_add_f32_e32 v142, 1.0, v142
	v_add_f32_e32 v143, 1.0, v143
	v_rcp_f32_e32 v140, v140
	v_rcp_f32_e32 v141, v141
	v_rcp_f32_e32 v142, v142
	v_rcp_f32_e32 v143, v143
	v_cvt_pk_bf16_f32 v132, v132, v133
	v_pk_mul_f32 v[126:127], v[126:127], v[140:141]
	v_mul_f32_e32 v140, 0xbfb8aa3b, v122
	v_pk_mul_f32 v[128:129], v[128:129], v[142:143]
; __device__ __forceinline__ unsigned cvt_pk_bf16(float lo, float hi) { unsigned r; asm("v_cvt_pk_bf16_f32 %0, %1, %2" : "=v"(r) : "v"(lo), "v"(hi)); return r; }
; __device__ __forceinline__ float bf_lo(unsigned u) { return __uint_as_float(u << 16); }
; __device__ __forceinline__ float bf_hi(unsigned u) { return __uint_as_float(u & 0xffff0000u); }
;     __device__ __forceinline__ void operator()(const AccT& acc, const Unit& u, int wr, int wc, int fr, int fq) const {
;     ...
;         for (int ai = 0; ai < 2; ++ai) {
;             u32x4 yv[4][2];
; #pragma unroll
;             for (int m = 0; m < 4; ++m)
; #pragma unroll
;                 for (int bj = 0; bj < 2; ++bj) yv[m][bj] = *(const u32x4*)(Y + (size_t)(row0 + ai * 128 + m * 16) * 2048 + col0 + bj * 128);
;             __builtin_amdgcn_sched_barrier(0);
; #pragma unroll
;             for (int m = 0; m < 4; ++m) { bf16_t* rowp = A2 + (size_t)(row0 + ai * 128 + m * 16) * 2048 + col0;
;                 const float mu = st[ai][m][0], rs = st[ai][m][1];
; #pragma unroll
;                 for (int bj = 0; bj < 2; ++bj) { const f32x4 v0 = acc[ai][bj][m][0], v1 = acc[ai][bj][m][1]; const u32x4 yw = yv[m][bj];
;                     const f32x4 y0 = (f32x4){bf_lo(yw.x), bf_hi(yw.x), bf_lo(yw.y), bf_hi(yw.y)}, y1 = (f32x4){bf_lo(yw.z), bf_hi(yw.z), bf_lo(yw.w), bf_hi(yw.w)};
;                     const f32x4 n0 = (y0 - mu) * rs * gw[bj][0], n1 = (y1 - mu) * rs * gw[bj][1];
;                     const f32x4 s0 = silu4(v0) * n0, s1 = silu4(v1) * n1;
;                     u32x4 w; w.x = cvt_pk_bf16(s0[0], s0[1]); w.y = cvt_pk_bf16(s0[2], s0[3]); w.z = cvt_pk_bf16(s1[0], s1[1]); w.w = cvt_pk_bf16(s1[2], s1[3]);
;                     *(u32x4*)(rowp + bj * 128) = w; } }
	v_mul_f32_e32 v141, 0xbfb8aa3b, v123
	v_mul_f32_e32 v142, 0xbfb8aa3b, v124
	v_mul_f32_e32 v143, 0xbfb8aa3b, v125
	v_exp_f32_e32 v140, v140
	v_exp_f32_e32 v141, v141
	v_exp_f32_e32 v142, v142
	v_exp_f32_e32 v143, v143
	v_add_f32_e32 v140, 1.0, v140
	v_add_f32_e32 v141, 1.0, v141
	v_add_f32_e32 v142, 1.0, v142
	v_add_f32_e32 v143, 1.0, v143
	v_cvt_pk_bf16_f32 v133, v138, v139
	v_rcp_f32_e32 v140, v140
	v_rcp_f32_e32 v141, v141
	v_rcp_f32_e32 v142, v142
	v_rcp_f32_e32 v143, v143
	v_cvt_pk_bf16_f32 v130, v134, v135
	v_cvt_pk_bf16_f32 v131, v136, v137
	global_store_dwordx4 v[242:243], v[130:133], off offset:256
	v_lshlrev_b32_e32 v136, 16, v238
	v_and_b32_e32 v137, 0xffff0000, v238
	v_lshlrev_b32_e32 v132, 16, v236
	v_and_b32_e32 v133, 0xffff0000, v236
	v_lshlrev_b32_e32 v138, 16, v239
	v_and_b32_e32 v139, 0xffff0000, v239
	v_lshlrev_b32_e32 v134, 16, v237
	v_and_b32_e32 v135, 0xffff0000, v237
	v_sub_f32_e32 v133, v133, v208
	v_sub_f32_e32 v132, v132, v208
	v_sub_f32_e32 v137, v137, v208
	v_sub_f32_e32 v136, v136, v208
	v_sub_f32_e32 v139, v139, v208
	v_sub_f32_e32 v138, v138, v208
	v_sub_f32_e32 v135, v135, v208
	v_sub_f32_e32 v134, v134, v208
	v_pk_mul_f32 v[132:133], v[208:209], v[132:133] op_sel:[1,0]
	v_pk_mul_f32 v[138:139], v[208:209], v[138:139] op_sel:[1,0]
	v_pk_mul_f32 v[136:137], v[208:209], v[136:137] op_sel:[1,0]
	v_pk_mul_f32 v[134:135], v[208:209], v[134:135] op_sel:[1,0]
	v_pk_mul_f32 v[132:133], v[86:87], v[132:133]
	v_pk_mul_f32 v[136:137], v[82:83], v[136:137]
	v_pk_mul_f32 v[138:139], v[84:85], v[138:139]
	v_pk_mul_f32 v[122:123], v[122:123], v[140:141]
	v_pk_mul_f32 v[124:125], v[124:125], v[142:143]
	v_pk_mul_f32 v[134:135], v[88:89], v[134:135]
	v_pk_mul_f32 v[126:127], v[126:127], v[132:133]
	v_pk_mul_f32 v[132:133], v[124:125], v[138:139]
	v_pk_mul_f32 v[124:125], v[122:123], v[136:137]
	v_pk_mul_f32 v[128:129], v[128:129], v[134:135]
	v_cvt_pk_bf16_f32 v124, v124, v125
	v_cvt_pk_bf16_f32 v125, v132, v133
	v_mul_f32_e32 v132, 0xbfb8aa3b, v118
	v_mul_f32_e32 v133, 0xbfb8aa3b, v119
	v_mul_f32_e32 v134, 0xbfb8aa3b, v120
	v_mul_f32_e32 v135, 0xbfb8aa3b, v121
	v_exp_f32_e32 v132, v132
	v_exp_f32_e32 v133, v133
	v_exp_f32_e32 v134, v134
	v_exp_f32_e32 v135, v135
	v_add_f32_e32 v132, 1.0, v132
	v_add_f32_e32 v133, 1.0, v133
	v_add_f32_e32 v134, 1.0, v134
	v_add_f32_e32 v135, 1.0, v135
	v_rcp_f32_e32 v132, v132
	v_rcp_f32_e32 v133, v133
	v_rcp_f32_e32 v134, v134
	v_rcp_f32_e32 v135, v135
	v_lshl_add_u64 v[130:131], s[34:35], 0, v[244:245]
	v_pk_mul_f32 v[118:119], v[118:119], v[132:133]
	v_mul_f32_e32 v132, 0xbfb8aa3b, v114
	v_pk_mul_f32 v[120:121], v[120:121], v[134:135]
	v_mul_f32_e32 v133, 0xbfb8aa3b, v115
	v_mul_f32_e32 v134, 0xbfb8aa3b, v116
	v_mul_f32_e32 v135, 0xbfb8aa3b, v117
	v_exp_f32_e32 v132, v132
	v_exp_f32_e32 v133, v133
	v_exp_f32_e32 v134, v134
	v_exp_f32_e32 v135, v135
	v_add_f32_e32 v132, 1.0, v132
	v_add_f32_e32 v133, 1.0, v133
	v_add_f32_e32 v134, 1.0, v134
	v_add_f32_e32 v135, 1.0, v135
	v_lshl_add_u64 v[130:131], v[130:131], 0, v[182:183]
	v_cvt_pk_bf16_f32 v122, v126, v127
	v_cvt_pk_bf16_f32 v123, v128, v129
	v_rcp_f32_e32 v132, v132
	v_rcp_f32_e32 v133, v133
	v_rcp_f32_e32 v134, v134
	v_rcp_f32_e32 v135, v135
	global_store_dwordx4 v[130:131], v[122:125], off
	v_lshlrev_b32_e32 v126, 16, v164
	v_and_b32_e32 v127, 0xffff0000, v164
	v_lshlrev_b32_e32 v122, 16, v162
	v_and_b32_e32 v123, 0xffff0000, v162
	v_lshlrev_b32_e32 v124, 16, v163
	v_and_b32_e32 v125, 0xffff0000, v163
	v_lshlrev_b32_e32 v128, 16, v165
	v_and_b32_e32 v129, 0xffff0000, v165
	v_sub_f32_e32 v123, v123, v208
	v_sub_f32_e32 v122, v122, v208
	v_sub_f32_e32 v125, v125, v208
	v_sub_f32_e32 v124, v124, v208
	v_sub_f32_e32 v127, v127, v208
	v_sub_f32_e32 v126, v126, v208
	v_sub_f32_e32 v129, v129, v208
	v_sub_f32_e32 v128, v128, v208
	v_pk_mul_f32 v[124:125], v[208:209], v[124:125] op_sel:[1,0]
	v_pk_mul_f32 v[122:123], v[208:209], v[122:123] op_sel:[1,0]
	v_pk_mul_f32 v[128:129], v[208:209], v[128:129] op_sel:[1,0]
	v_pk_mul_f32 v[126:127], v[208:209], v[126:127] op_sel:[1,0]
	v_pk_mul_f32 v[122:123], v[70:71], v[122:123]
	v_pk_mul_f32 v[124:125], v[72:73], v[124:125]
	v_pk_mul_f32 v[126:127], v[66:67], v[126:127]
	v_pk_mul_f32 v[128:129], v[68:69], v[128:129]
	v_pk_mul_f32 v[114:115], v[114:115], v[132:133]
	v_pk_mul_f32 v[116:117], v[116:117], v[134:135]
	v_pk_mul_f32 v[120:121], v[120:121], v[124:125]
	v_pk_mul_f32 v[118:119], v[118:119], v[122:123]
	v_pk_mul_f32 v[122:123], v[116:117], v[128:129]
	v_pk_mul_f32 v[116:117], v[114:115], v[126:127]
	v_mul_f32_e32 v124, 0xbfb8aa3b, v110
	v_mul_f32_e32 v125, 0xbfb8aa3b, v111
	v_mul_f32_e32 v126, 0xbfb8aa3b, v112
	v_mul_f32_e32 v127, 0xbfb8aa3b, v113
	v_exp_f32_e32 v124, v124
	v_exp_f32_e32 v125, v125
	v_exp_f32_e32 v126, v126
	v_exp_f32_e32 v127, v127
	v_add_f32_e32 v124, 1.0, v124
	v_add_f32_e32 v125, 1.0, v125
	v_add_f32_e32 v126, 1.0, v126
	v_add_f32_e32 v127, 1.0, v127
	v_rcp_f32_e32 v124, v124
	v_rcp_f32_e32 v125, v125
	v_rcp_f32_e32 v126, v126
	v_rcp_f32_e32 v127, v127
	v_cvt_pk_bf16_f32 v116, v116, v117
	v_pk_mul_f32 v[110:111], v[110:111], v[124:125]
	v_mul_f32_e32 v124, 0xbfb8aa3b, v106
	v_pk_mul_f32 v[112:113], v[112:113], v[126:127]
	v_mul_f32_e32 v125, 0xbfb8aa3b, v107
	v_mul_f32_e32 v126, 0xbfb8aa3b, v108
	v_mul_f32_e32 v127, 0xbfb8aa3b, v109
	v_exp_f32_e32 v124, v124
	v_exp_f32_e32 v125, v125
	v_exp_f32_e32 v126, v126
	v_exp_f32_e32 v127, v127
	v_add_f32_e32 v124, 1.0, v124
	v_add_f32_e32 v125, 1.0, v125
	v_add_f32_e32 v126, 1.0, v126
	v_add_f32_e32 v127, 1.0, v127
	v_cvt_pk_bf16_f32 v117, v122, v123
	v_rcp_f32_e32 v124, v124
	v_rcp_f32_e32 v125, v125
	v_rcp_f32_e32 v126, v126
; __device__ __forceinline__ unsigned cvt_pk_bf16(float lo, float hi) { unsigned r; asm("v_cvt_pk_bf16_f32 %0, %1, %2" : "=v"(r) : "v"(lo), "v"(hi)); return r; }
; __device__ __forceinline__ float bf_lo(unsigned u) { return __uint_as_float(u << 16); }
; __device__ __forceinline__ float bf_hi(unsigned u) { return __uint_as_float(u & 0xffff0000u); }
;     __device__ __forceinline__ void operator()(const AccT& acc, const Unit& u, int wr, int wc, int fr, int fq) const {
;     ...
;         for (int ai = 0; ai < 2; ++ai) {
;             u32x4 yv[4][2];
; #pragma unroll
;             for (int m = 0; m < 4; ++m)
; #pragma unroll
;                 for (int bj = 0; bj < 2; ++bj) yv[m][bj] = *(const u32x4*)(Y + (size_t)(row0 + ai * 128 + m * 16) * 2048 + col0 + bj * 128);
;             __builtin_amdgcn_sched_barrier(0);
; #pragma unroll
;             for (int m = 0; m < 4; ++m) { bf16_t* rowp = A2 + (size_t)(row0 + ai * 128 + m * 16) * 2048 + col0;
;                 const float mu = st[ai][m][0], rs = st[ai][m][1];
; #pragma unroll
;                 for (int bj = 0; bj < 2; ++bj) { const f32x4 v0 = acc[ai][bj][m][0], v1 = acc[ai][bj][m][1]; const u32x4 yw = yv[m][bj];
;                     const f32x4 y0 = (f32x4){bf_lo(yw.x), bf_hi(yw.x), bf_lo(yw.y), bf_hi(yw.y)}, y1 = (f32x4){bf_lo(yw.z), bf_hi(yw.z), bf_lo(yw.w), bf_hi(yw.w)};
;                     const f32x4 n0 = (y0 - mu) * rs * gw[bj][0], n1 = (y1 - mu) * rs * gw[bj][1];
;                     const f32x4 s0 = silu4(v0) * n0, s1 = silu4(v1) * n1;
;                     u32x4 w; w.x = cvt_pk_bf16(s0[0], s0[1]); w.y = cvt_pk_bf16(s0[2], s0[3]); w.z = cvt_pk_bf16(s1[0], s1[1]); w.w = cvt_pk_bf16(s1[2], s1[3]);
;                     *(u32x4*)(rowp + bj * 128) = w; } }
	v_rcp_f32_e32 v127, v127
	v_cvt_pk_bf16_f32 v114, v118, v119
	v_cvt_pk_bf16_f32 v115, v120, v121
	global_store_dwordx4 v[130:131], v[114:117], off offset:256
	v_lshlrev_b32_e32 v120, 16, v160
	v_and_b32_e32 v121, 0xffff0000, v160
	v_lshlrev_b32_e32 v116, 16, v158
	v_and_b32_e32 v117, 0xffff0000, v158
	v_lshlrev_b32_e32 v122, 16, v161
	v_and_b32_e32 v123, 0xffff0000, v161
	v_lshlrev_b32_e32 v118, 16, v159
	v_and_b32_e32 v119, 0xffff0000, v159
	v_sub_f32_e32 v117, v117, v204
	v_sub_f32_e32 v116, v116, v204
	v_sub_f32_e32 v121, v121, v204
	v_sub_f32_e32 v120, v120, v204
	v_sub_f32_e32 v123, v123, v204
	v_sub_f32_e32 v122, v122, v204
	v_sub_f32_e32 v119, v119, v204
	v_sub_f32_e32 v118, v118, v204
	v_pk_mul_f32 v[116:117], v[204:205], v[116:117] op_sel:[1,0]
	v_pk_mul_f32 v[122:123], v[204:205], v[122:123] op_sel:[1,0]
	v_pk_mul_f32 v[120:121], v[204:205], v[120:121] op_sel:[1,0]
	v_pk_mul_f32 v[118:119], v[204:205], v[118:119] op_sel:[1,0]
	v_pk_mul_f32 v[116:117], v[86:87], v[116:117]
	v_pk_mul_f32 v[120:121], v[82:83], v[120:121]
	v_pk_mul_f32 v[122:123], v[84:85], v[122:123]
	v_pk_mul_f32 v[106:107], v[106:107], v[124:125]
	v_pk_mul_f32 v[108:109], v[108:109], v[126:127]
	v_pk_mul_f32 v[118:119], v[88:89], v[118:119]
	v_pk_mul_f32 v[110:111], v[110:111], v[116:117]
	v_pk_mul_f32 v[116:117], v[108:109], v[122:123]
	v_pk_mul_f32 v[108:109], v[106:107], v[120:121]
	v_pk_mul_f32 v[112:113], v[112:113], v[118:119]
	v_cvt_pk_bf16_f32 v108, v108, v109
	v_cvt_pk_bf16_f32 v109, v116, v117
	v_mul_f32_e32 v116, 0xbfb8aa3b, v102
	v_mul_f32_e32 v117, 0xbfb8aa3b, v103
	v_mul_f32_e32 v118, 0xbfb8aa3b, v104
	v_mul_f32_e32 v119, 0xbfb8aa3b, v105
	v_exp_f32_e32 v116, v116
	v_exp_f32_e32 v117, v117
	v_exp_f32_e32 v118, v118
	v_exp_f32_e32 v119, v119
	v_add_f32_e32 v116, 1.0, v116
	v_add_f32_e32 v117, 1.0, v117
	v_add_f32_e32 v118, 1.0, v118
	v_add_f32_e32 v119, 1.0, v119
	v_rcp_f32_e32 v116, v116
	v_rcp_f32_e32 v117, v117
	v_rcp_f32_e32 v118, v118
	v_rcp_f32_e32 v119, v119
	v_lshl_add_u64 v[114:115], s[34:35], 0, v[206:207]
	v_pk_mul_f32 v[102:103], v[102:103], v[116:117]
	v_mul_f32_e32 v116, 0xbfb8aa3b, v98
	v_pk_mul_f32 v[104:105], v[104:105], v[118:119]
	v_mul_f32_e32 v117, 0xbfb8aa3b, v99
	v_mul_f32_e32 v118, 0xbfb8aa3b, v100
	v_mul_f32_e32 v119, 0xbfb8aa3b, v101
	v_exp_f32_e32 v116, v116
	v_exp_f32_e32 v117, v117
	v_exp_f32_e32 v118, v118
	v_exp_f32_e32 v119, v119
	v_add_f32_e32 v116, 1.0, v116
	v_add_f32_e32 v117, 1.0, v117
	v_add_f32_e32 v118, 1.0, v118
	v_add_f32_e32 v119, 1.0, v119
	v_lshl_add_u64 v[114:115], v[114:115], 0, v[182:183]
	v_cvt_pk_bf16_f32 v106, v110, v111
	v_cvt_pk_bf16_f32 v107, v112, v113
	v_rcp_f32_e32 v116, v116
	v_rcp_f32_e32 v117, v117
	v_rcp_f32_e32 v118, v118
	v_rcp_f32_e32 v119, v119
	global_store_dwordx4 v[114:115], v[106:109], off
	v_lshlrev_b32_e32 v110, 16, v156
	v_and_b32_e32 v111, 0xffff0000, v156
	v_lshlrev_b32_e32 v106, 16, v154
	v_and_b32_e32 v107, 0xffff0000, v154
	v_lshlrev_b32_e32 v108, 16, v155
	v_and_b32_e32 v109, 0xffff0000, v155
	v_lshlrev_b32_e32 v112, 16, v157
	v_and_b32_e32 v113, 0xffff0000, v157
	v_sub_f32_e32 v107, v107, v204
	v_sub_f32_e32 v106, v106, v204
	v_sub_f32_e32 v109, v109, v204
	v_sub_f32_e32 v108, v108, v204
	v_sub_f32_e32 v111, v111, v204
	v_sub_f32_e32 v110, v110, v204
	v_sub_f32_e32 v113, v113, v204
	v_sub_f32_e32 v112, v112, v204
	v_pk_mul_f32 v[108:109], v[204:205], v[108:109] op_sel:[1,0]
	v_pk_mul_f32 v[106:107], v[204:205], v[106:107] op_sel:[1,0]
	v_pk_mul_f32 v[112:113], v[204:205], v[112:113] op_sel:[1,0]
	v_pk_mul_f32 v[110:111], v[204:205], v[110:111] op_sel:[1,0]
	v_pk_mul_f32 v[106:107], v[70:71], v[106:107]
	v_pk_mul_f32 v[108:109], v[72:73], v[108:109]
	v_pk_mul_f32 v[110:111], v[66:67], v[110:111]
	v_pk_mul_f32 v[112:113], v[68:69], v[112:113]
	v_pk_mul_f32 v[98:99], v[98:99], v[116:117]
	v_pk_mul_f32 v[100:101], v[100:101], v[118:119]
	v_pk_mul_f32 v[104:105], v[104:105], v[108:109]
	v_pk_mul_f32 v[102:103], v[102:103], v[106:107]
	v_pk_mul_f32 v[106:107], v[100:101], v[112:113]
	v_pk_mul_f32 v[100:101], v[98:99], v[110:111]
	v_mul_f32_e32 v108, 0xbfb8aa3b, v94
	v_mul_f32_e32 v109, 0xbfb8aa3b, v95
	v_mul_f32_e32 v110, 0xbfb8aa3b, v96
	v_mul_f32_e32 v111, 0xbfb8aa3b, v97
	v_exp_f32_e32 v108, v108
	v_exp_f32_e32 v109, v109
	v_exp_f32_e32 v110, v110
	v_exp_f32_e32 v111, v111
	v_add_f32_e32 v108, 1.0, v108
	v_add_f32_e32 v109, 1.0, v109
	v_add_f32_e32 v110, 1.0, v110
	v_add_f32_e32 v111, 1.0, v111
	v_rcp_f32_e32 v108, v108
	v_rcp_f32_e32 v109, v109
	v_rcp_f32_e32 v110, v110
	v_rcp_f32_e32 v111, v111
	v_cvt_pk_bf16_f32 v100, v100, v101
	v_pk_mul_f32 v[94:95], v[94:95], v[108:109]
	v_mul_f32_e32 v108, 0xbfb8aa3b, v90
	v_pk_mul_f32 v[96:97], v[96:97], v[110:111]
	v_mul_f32_e32 v109, 0xbfb8aa3b, v91
	v_mul_f32_e32 v110, 0xbfb8aa3b, v92
	v_mul_f32_e32 v111, 0xbfb8aa3b, v93
	v_exp_f32_e32 v108, v108
	v_exp_f32_e32 v109, v109
	v_exp_f32_e32 v110, v110
	v_exp_f32_e32 v111, v111
	v_add_f32_e32 v108, 1.0, v108
	v_add_f32_e32 v109, 1.0, v109
	v_add_f32_e32 v110, 1.0, v110
	v_add_f32_e32 v111, 1.0, v111
	v_cvt_pk_bf16_f32 v101, v106, v107
	v_rcp_f32_e32 v108, v108
	v_rcp_f32_e32 v109, v109
	v_rcp_f32_e32 v110, v110
	v_rcp_f32_e32 v111, v111
	v_cvt_pk_bf16_f32 v98, v102, v103
	v_cvt_pk_bf16_f32 v99, v104, v105
	global_store_dwordx4 v[114:115], v[98:101], off offset:256
	v_lshlrev_b32_e32 v104, 16, v152
	v_and_b32_e32 v105, 0xffff0000, v152
	v_lshlrev_b32_e32 v100, 16, v150
	v_and_b32_e32 v101, 0xffff0000, v150
	v_lshlrev_b32_e32 v106, 16, v153
	v_and_b32_e32 v107, 0xffff0000, v153
	v_lshlrev_b32_e32 v102, 16, v151
	v_and_b32_e32 v103, 0xffff0000, v151
	v_sub_f32_e32 v101, v101, v200
; __device__ __forceinline__ unsigned cvt_pk_bf16(float lo, float hi) { unsigned r; asm("v_cvt_pk_bf16_f32 %0, %1, %2" : "=v"(r) : "v"(lo), "v"(hi)); return r; }
; __device__ __forceinline__ float bf_lo(unsigned u) { return __uint_as_float(u << 16); }
; __device__ __forceinline__ float bf_hi(unsigned u) { return __uint_as_float(u & 0xffff0000u); }
;     __device__ __forceinline__ void operator()(const AccT& acc, const Unit& u, int wr, int wc, int fr, int fq) const {
;     ...
;         for (int ai = 0; ai < 2; ++ai) {
;             u32x4 yv[4][2];
; #pragma unroll
;             for (int m = 0; m < 4; ++m)
; #pragma unroll
;                 for (int bj = 0; bj < 2; ++bj) yv[m][bj] = *(const u32x4*)(Y + (size_t)(row0 + ai * 128 + m * 16) * 2048 + col0 + bj * 128);
;             __builtin_amdgcn_sched_barrier(0);
; #pragma unroll
;             for (int m = 0; m < 4; ++m) { bf16_t* rowp = A2 + (size_t)(row0 + ai * 128 + m * 16) * 2048 + col0;
;                 const float mu = st[ai][m][0], rs = st[ai][m][1];
; #pragma unroll
;                 for (int bj = 0; bj < 2; ++bj) { const f32x4 v0 = acc[ai][bj][m][0], v1 = acc[ai][bj][m][1]; const u32x4 yw = yv[m][bj];
;                     const f32x4 y0 = (f32x4){bf_lo(yw.x), bf_hi(yw.x), bf_lo(yw.y), bf_hi(yw.y)}, y1 = (f32x4){bf_lo(yw.z), bf_hi(yw.z), bf_lo(yw.w), bf_hi(yw.w)};
;                     const f32x4 n0 = (y0 - mu) * rs * gw[bj][0], n1 = (y1 - mu) * rs * gw[bj][1];
;                     const f32x4 s0 = silu4(v0) * n0, s1 = silu4(v1) * n1;
;                     u32x4 w; w.x = cvt_pk_bf16(s0[0], s0[1]); w.y = cvt_pk_bf16(s0[2], s0[3]); w.z = cvt_pk_bf16(s1[0], s1[1]); w.w = cvt_pk_bf16(s1[2], s1[3]);
;                     *(u32x4*)(rowp + bj * 128) = w; } }
	v_sub_f32_e32 v100, v100, v200
	v_sub_f32_e32 v105, v105, v200
	v_sub_f32_e32 v104, v104, v200
	v_sub_f32_e32 v107, v107, v200
	v_sub_f32_e32 v106, v106, v200
	v_sub_f32_e32 v103, v103, v200
	v_sub_f32_e32 v102, v102, v200
	v_pk_mul_f32 v[100:101], v[200:201], v[100:101] op_sel:[1,0]
	v_pk_mul_f32 v[106:107], v[200:201], v[106:107] op_sel:[1,0]
	v_pk_mul_f32 v[104:105], v[200:201], v[104:105] op_sel:[1,0]
	v_pk_mul_f32 v[102:103], v[200:201], v[102:103] op_sel:[1,0]
	v_pk_mul_f32 v[100:101], v[86:87], v[100:101]
	v_pk_mul_f32 v[104:105], v[82:83], v[104:105]
	v_pk_mul_f32 v[106:107], v[84:85], v[106:107]
	v_pk_mul_f32 v[90:91], v[90:91], v[108:109]
	v_pk_mul_f32 v[92:93], v[92:93], v[110:111]
	v_pk_mul_f32 v[102:103], v[88:89], v[102:103]
	v_pk_mul_f32 v[94:95], v[94:95], v[100:101]
	v_pk_mul_f32 v[100:101], v[92:93], v[106:107]
	v_pk_mul_f32 v[92:93], v[90:91], v[104:105]
	v_pk_mul_f32 v[96:97], v[96:97], v[102:103]
	v_cvt_pk_bf16_f32 v92, v92, v93
	v_cvt_pk_bf16_f32 v93, v100, v101
	v_mul_f32_e32 v100, 0xbfb8aa3b, v78
	v_mul_f32_e32 v101, 0xbfb8aa3b, v79
	v_mul_f32_e32 v102, 0xbfb8aa3b, v80
	v_mul_f32_e32 v103, 0xbfb8aa3b, v81
	v_exp_f32_e32 v100, v100
	v_exp_f32_e32 v101, v101
	v_exp_f32_e32 v102, v102
	v_exp_f32_e32 v103, v103
	v_add_f32_e32 v100, 1.0, v100
	v_add_f32_e32 v101, 1.0, v101
	v_add_f32_e32 v102, 1.0, v102
	v_add_f32_e32 v103, 1.0, v103
	v_rcp_f32_e32 v100, v100
	v_rcp_f32_e32 v101, v101
	v_rcp_f32_e32 v102, v102
	v_rcp_f32_e32 v103, v103
	v_lshl_add_u64 v[98:99], s[34:35], 0, v[202:203]
	v_pk_mul_f32 v[78:79], v[78:79], v[100:101]
	v_mul_f32_e32 v100, 0xbfb8aa3b, v74
	v_pk_mul_f32 v[80:81], v[80:81], v[102:103]
	v_mul_f32_e32 v101, 0xbfb8aa3b, v75
	v_mul_f32_e32 v102, 0xbfb8aa3b, v76
	v_mul_f32_e32 v103, 0xbfb8aa3b, v77
	v_exp_f32_e32 v100, v100
	v_exp_f32_e32 v101, v101
	v_exp_f32_e32 v102, v102
	v_exp_f32_e32 v103, v103
	v_add_f32_e32 v100, 1.0, v100
	v_add_f32_e32 v101, 1.0, v101
	v_add_f32_e32 v102, 1.0, v102
	v_add_f32_e32 v103, 1.0, v103
	v_lshl_add_u64 v[98:99], v[98:99], 0, v[182:183]
	v_cvt_pk_bf16_f32 v90, v94, v95
	v_cvt_pk_bf16_f32 v91, v96, v97
	v_rcp_f32_e32 v100, v100
	v_rcp_f32_e32 v101, v101
	v_rcp_f32_e32 v102, v102
	v_rcp_f32_e32 v103, v103
	global_store_dwordx4 v[98:99], v[90:93], off
	v_lshlrev_b32_e32 v94, 16, v148
	v_and_b32_e32 v95, 0xffff0000, v148
	v_lshlrev_b32_e32 v90, 16, v146
	v_and_b32_e32 v91, 0xffff0000, v146
	v_lshlrev_b32_e32 v96, 16, v149
	v_and_b32_e32 v97, 0xffff0000, v149
	v_lshlrev_b32_e32 v92, 16, v147
	v_and_b32_e32 v93, 0xffff0000, v147
	v_sub_f32_e32 v91, v91, v200
	v_sub_f32_e32 v90, v90, v200
	v_sub_f32_e32 v95, v95, v200
	v_sub_f32_e32 v94, v94, v200
	v_sub_f32_e32 v97, v97, v200
	v_sub_f32_e32 v96, v96, v200
	v_sub_f32_e32 v93, v93, v200
	v_sub_f32_e32 v92, v92, v200
	v_pk_mul_f32 v[90:91], v[200:201], v[90:91] op_sel:[1,0]
	v_pk_mul_f32 v[96:97], v[200:201], v[96:97] op_sel:[1,0]
	v_pk_mul_f32 v[94:95], v[200:201], v[94:95] op_sel:[1,0]
	v_pk_mul_f32 v[92:93], v[200:201], v[92:93] op_sel:[1,0]
	v_pk_mul_f32 v[90:91], v[70:71], v[90:91]
	v_pk_mul_f32 v[94:95], v[66:67], v[94:95]
	v_pk_mul_f32 v[96:97], v[68:69], v[96:97]
	v_pk_mul_f32 v[74:75], v[74:75], v[100:101]
	v_pk_mul_f32 v[76:77], v[76:77], v[102:103]
	v_pk_mul_f32 v[92:93], v[72:73], v[92:93]
	v_pk_mul_f32 v[78:79], v[78:79], v[90:91]
	v_pk_mul_f32 v[90:91], v[76:77], v[96:97]
	v_pk_mul_f32 v[76:77], v[74:75], v[94:95]
	v_pk_mul_f32 v[80:81], v[80:81], v[92:93]
	v_cvt_pk_bf16_f32 v74, v78, v79
	v_cvt_pk_bf16_f32 v76, v76, v77
	v_cvt_pk_bf16_f32 v77, v90, v91
	s_nop 0
	v_cvt_pk_bf16_f32 v75, v80, v81
	global_store_dwordx4 v[98:99], v[74:77], off offset:256
	v_lshlrev_b64 v[118:119], 12, v[190:191]
	s_nop 0
	v_lshl_add_u64 v[74:75], v[198:199], 0, v[118:119]
	v_lshlrev_b64 v[120:121], 12, v[192:193]
	global_load_dwordx4 v[106:109], v[74:75], off
	global_load_dwordx4 v[110:113], v[74:75], off offset:256
	v_lshl_add_u64 v[74:75], v[198:199], 0, v[120:121]
	v_lshlrev_b64 v[104:105], 12, v[194:195]
	global_load_dwordx4 v[114:117], v[74:75], off
	global_load_dwordx4 v[98:101], v[74:75], off offset:256
	v_lshl_add_u64 v[74:75], v[198:199], 0, v[104:105]
	v_lshlrev_b64 v[102:103], 12, v[196:197]
	global_load_dwordx4 v[94:97], v[74:75], off
	global_load_dwordx4 v[90:93], v[74:75], off offset:256
	v_lshl_add_u64 v[74:75], v[198:199], 0, v[102:103]
	global_load_dwordx4 v[78:81], v[74:75], off
	s_nop 0
	global_load_dwordx4 v[74:77], v[74:75], off offset:256
	s_waitcnt vmcnt(0)
; __device__ __forceinline__ unsigned cvt_pk_bf16(float lo, float hi) { unsigned r; asm("v_cvt_pk_bf16_f32 %0, %1, %2" : "=v"(r) : "v"(lo), "v"(hi)); return r; }
; __device__ __forceinline__ float bf_lo(unsigned u) { return __uint_as_float(u << 16); }
; __device__ __forceinline__ float bf_hi(unsigned u) { return __uint_as_float(u & 0xffff0000u); }
;     __device__ __forceinline__ void operator()(const AccT& acc, const Unit& u, int wr, int wc, int fr, int fq) const {
;     ...
;         for (int ai = 0; ai < 2; ++ai) {
;             u32x4 yv[4][2];
; #pragma unroll
;             for (int m = 0; m < 4; ++m)
; #pragma unroll
;                 for (int bj = 0; bj < 2; ++bj) yv[m][bj] = *(const u32x4*)(Y + (size_t)(row0 + ai * 128 + m * 16) * 2048 + col0 + bj * 128);
;             __builtin_amdgcn_sched_barrier(0);
; #pragma unroll
;             for (int m = 0; m < 4; ++m) { bf16_t* rowp = A2 + (size_t)(row0 + ai * 128 + m * 16) * 2048 + col0;
;                 const float mu = st[ai][m][0], rs = st[ai][m][1];
; #pragma unroll
;                 for (int bj = 0; bj < 2; ++bj) { const f32x4 v0 = acc[ai][bj][m][0], v1 = acc[ai][bj][m][1]; const u32x4 yw = yv[m][bj];
;                     const f32x4 y0 = (f32x4){bf_lo(yw.x), bf_hi(yw.x), bf_lo(yw.y), bf_hi(yw.y)}, y1 = (f32x4){bf_lo(yw.z), bf_hi(yw.z), bf_lo(yw.w), bf_hi(yw.w)};
;                     const f32x4 n0 = (y0 - mu) * rs * gw[bj][0], n1 = (y1 - mu) * rs * gw[bj][1];
;                     const f32x4 s0 = silu4(v0) * n0, s1 = silu4(v1) * n1;
;                     u32x4 w; w.x = cvt_pk_bf16(s0[0], s0[1]); w.y = cvt_pk_bf16(s0[2], s0[3]); w.z = cvt_pk_bf16(s1[0], s1[1]); w.w = cvt_pk_bf16(s1[2], s1[3]);
;                     *(u32x4*)(rowp + bj * 128) = w; } }
	v_lshlrev_b32_e32 v122, 16, v106
	v_and_b32_e32 v106, 0xffff0000, v106
	v_lshlrev_b32_e32 v123, 16, v107
	v_and_b32_e32 v124, 0xffff0000, v107
	v_lshlrev_b32_e32 v125, 16, v108
	v_and_b32_e32 v126, 0xffff0000, v108
	v_lshlrev_b32_e32 v127, 16, v109
	v_and_b32_e32 v128, 0xffff0000, v109
	v_sub_f32_e32 v107, v106, v188
	v_sub_f32_e32 v106, v122, v188
	v_sub_f32_e32 v109, v124, v188
	v_sub_f32_e32 v108, v123, v188
	v_sub_f32_e32 v123, v126, v188
	v_sub_f32_e32 v122, v125, v188
	v_sub_f32_e32 v125, v128, v188
	v_sub_f32_e32 v124, v127, v188
	v_mul_f32_e32 v126, 0xbfb8aa3b, v62
	v_mul_f32_e32 v127, 0xbfb8aa3b, v63
	v_mul_f32_e32 v128, 0xbfb8aa3b, v64
	v_mul_f32_e32 v129, 0xbfb8aa3b, v65
	v_exp_f32_e32 v126, v126
	v_exp_f32_e32 v127, v127
	v_exp_f32_e32 v128, v128
	v_exp_f32_e32 v129, v129
	v_add_f32_e32 v126, 1.0, v126
	v_add_f32_e32 v127, 1.0, v127
	v_add_f32_e32 v128, 1.0, v128
	v_add_f32_e32 v129, 1.0, v129
	v_rcp_f32_e32 v126, v126
	v_rcp_f32_e32 v127, v127
	v_rcp_f32_e32 v128, v128
	v_rcp_f32_e32 v129, v129
	v_pk_mul_f32 v[106:107], v[188:189], v[106:107] op_sel:[1,0]
	v_pk_mul_f32 v[62:63], v[62:63], v[126:127]
	v_mul_f32_e32 v126, 0xbfb8aa3b, v58
	v_pk_mul_f32 v[64:65], v[64:65], v[128:129]
	v_mul_f32_e32 v127, 0xbfb8aa3b, v59
	v_mul_f32_e32 v128, 0xbfb8aa3b, v60
	v_mul_f32_e32 v129, 0xbfb8aa3b, v61
	v_exp_f32_e32 v126, v126
	v_exp_f32_e32 v127, v127
	v_exp_f32_e32 v128, v128
	v_exp_f32_e32 v129, v129
	v_add_f32_e32 v126, 1.0, v126
	v_add_f32_e32 v127, 1.0, v127
	v_add_f32_e32 v128, 1.0, v128
	v_add_f32_e32 v129, 1.0, v129
	v_rcp_f32_e32 v126, v126
	v_rcp_f32_e32 v127, v127
	v_rcp_f32_e32 v128, v128
	v_rcp_f32_e32 v129, v129
	v_pk_mul_f32 v[124:125], v[188:189], v[124:125] op_sel:[1,0]
	v_pk_mul_f32 v[122:123], v[188:189], v[122:123] op_sel:[1,0]
	v_pk_mul_f32 v[108:109], v[188:189], v[108:109] op_sel:[1,0]
	v_pk_mul_f32 v[106:107], v[86:87], v[106:107]
	v_pk_mul_f32 v[122:123], v[82:83], v[122:123]
	v_pk_mul_f32 v[124:125], v[84:85], v[124:125]
	v_pk_mul_f32 v[58:59], v[58:59], v[126:127]
	v_pk_mul_f32 v[60:61], v[60:61], v[128:129]
	v_pk_mul_f32 v[108:109], v[88:89], v[108:109]
	v_pk_mul_f32 v[62:63], v[62:63], v[106:107]
	v_pk_mul_f32 v[106:107], v[60:61], v[124:125]
	v_pk_mul_f32 v[60:61], v[58:59], v[122:123]
	v_pk_mul_f32 v[64:65], v[64:65], v[108:109]
	v_cvt_pk_bf16_f32 v60, v60, v61
	v_cvt_pk_bf16_f32 v61, v106, v107
	v_mul_f32_e32 v106, 0xbfb8aa3b, v54
	v_mul_f32_e32 v107, 0xbfb8aa3b, v55
	v_mul_f32_e32 v108, 0xbfb8aa3b, v56
	v_mul_f32_e32 v109, 0xbfb8aa3b, v57
	v_exp_f32_e32 v106, v106
	v_exp_f32_e32 v107, v107
	v_exp_f32_e32 v108, v108
	v_exp_f32_e32 v109, v109
	v_add_f32_e32 v106, 1.0, v106
	v_add_f32_e32 v107, 1.0, v107
	v_add_f32_e32 v108, 1.0, v108
	v_add_f32_e32 v109, 1.0, v109
	v_rcp_f32_e32 v106, v106
	v_rcp_f32_e32 v107, v107
	v_rcp_f32_e32 v108, v108
	v_rcp_f32_e32 v109, v109
	v_lshl_add_u64 v[118:119], s[34:35], 0, v[118:119]
	v_pk_mul_f32 v[54:55], v[54:55], v[106:107]
	v_mul_f32_e32 v106, 0xbfb8aa3b, v50
	v_pk_mul_f32 v[56:57], v[56:57], v[108:109]
	v_mul_f32_e32 v107, 0xbfb8aa3b, v51
	v_mul_f32_e32 v108, 0xbfb8aa3b, v52
	v_mul_f32_e32 v109, 0xbfb8aa3b, v53
	v_exp_f32_e32 v106, v106
	v_exp_f32_e32 v107, v107
	v_exp_f32_e32 v108, v108
	v_exp_f32_e32 v109, v109
	v_add_f32_e32 v106, 1.0, v106
	v_add_f32_e32 v107, 1.0, v107
	v_add_f32_e32 v108, 1.0, v108
	v_add_f32_e32 v109, 1.0, v109
	v_lshl_add_u64 v[118:119], v[118:119], 0, v[182:183]
	v_cvt_pk_bf16_f32 v58, v62, v63
	v_cvt_pk_bf16_f32 v59, v64, v65
	v_rcp_f32_e32 v106, v106
	v_rcp_f32_e32 v107, v107
	v_rcp_f32_e32 v108, v108
	v_rcp_f32_e32 v109, v109
	global_store_dwordx4 v[118:119], v[58:61], off
	v_lshlrev_b32_e32 v62, 16, v112
	v_and_b32_e32 v63, 0xffff0000, v112
	v_lshlrev_b32_e32 v58, 16, v110
	v_and_b32_e32 v59, 0xffff0000, v110
	v_lshlrev_b32_e32 v60, 16, v111
	v_and_b32_e32 v61, 0xffff0000, v111
	v_lshlrev_b32_e32 v64, 16, v113
	v_and_b32_e32 v65, 0xffff0000, v113
	v_sub_f32_e32 v59, v59, v188
	v_sub_f32_e32 v58, v58, v188
	v_sub_f32_e32 v61, v61, v188
	v_sub_f32_e32 v60, v60, v188
	v_sub_f32_e32 v63, v63, v188
	v_sub_f32_e32 v62, v62, v188
	v_sub_f32_e32 v65, v65, v188
	v_sub_f32_e32 v64, v64, v188
	v_pk_mul_f32 v[60:61], v[188:189], v[60:61] op_sel:[1,0]
	v_pk_mul_f32 v[58:59], v[188:189], v[58:59] op_sel:[1,0]
	v_pk_mul_f32 v[64:65], v[188:189], v[64:65] op_sel:[1,0]
	v_pk_mul_f32 v[62:63], v[188:189], v[62:63] op_sel:[1,0]
	v_pk_mul_f32 v[58:59], v[70:71], v[58:59]
	v_pk_mul_f32 v[60:61], v[72:73], v[60:61]
	v_pk_mul_f32 v[62:63], v[66:67], v[62:63]
	v_pk_mul_f32 v[64:65], v[68:69], v[64:65]
	v_pk_mul_f32 v[50:51], v[50:51], v[106:107]
	v_pk_mul_f32 v[52:53], v[52:53], v[108:109]
	v_pk_mul_f32 v[56:57], v[56:57], v[60:61]
	v_pk_mul_f32 v[54:55], v[54:55], v[58:59]
	v_pk_mul_f32 v[58:59], v[52:53], v[64:65]
	v_pk_mul_f32 v[52:53], v[50:51], v[62:63]
	v_mul_f32_e32 v60, 0xbfb8aa3b, v46
	v_mul_f32_e32 v61, 0xbfb8aa3b, v47
	v_mul_f32_e32 v62, 0xbfb8aa3b, v48
	v_mul_f32_e32 v63, 0xbfb8aa3b, v49
	v_exp_f32_e32 v60, v60
	v_exp_f32_e32 v61, v61
	v_exp_f32_e32 v62, v62
	v_exp_f32_e32 v63, v63
	v_add_f32_e32 v60, 1.0, v60
	v_add_f32_e32 v61, 1.0, v61
	v_add_f32_e32 v62, 1.0, v62
	v_add_f32_e32 v63, 1.0, v63
	v_rcp_f32_e32 v60, v60
	v_rcp_f32_e32 v61, v61
	v_rcp_f32_e32 v62, v62
	v_rcp_f32_e32 v63, v63
	v_cvt_pk_bf16_f32 v52, v52, v53
	v_pk_mul_f32 v[46:47], v[46:47], v[60:61]
	v_mul_f32_e32 v60, 0xbfb8aa3b, v42
	v_pk_mul_f32 v[48:49], v[48:49], v[62:63]
	v_mul_f32_e32 v61, 0xbfb8aa3b, v43
	v_mul_f32_e32 v62, 0xbfb8aa3b, v44
	v_mul_f32_e32 v63, 0xbfb8aa3b, v45
	v_exp_f32_e32 v60, v60
	v_exp_f32_e32 v61, v61
	v_exp_f32_e32 v62, v62
	v_exp_f32_e32 v63, v63
; __device__ __forceinline__ unsigned cvt_pk_bf16(float lo, float hi) { unsigned r; asm("v_cvt_pk_bf16_f32 %0, %1, %2" : "=v"(r) : "v"(lo), "v"(hi)); return r; }
; __device__ __forceinline__ float bf_lo(unsigned u) { return __uint_as_float(u << 16); }
; __device__ __forceinline__ float bf_hi(unsigned u) { return __uint_as_float(u & 0xffff0000u); }
;     __device__ __forceinline__ void operator()(const AccT& acc, const Unit& u, int wr, int wc, int fr, int fq) const {
;     ...
;         for (int ai = 0; ai < 2; ++ai) {
;             u32x4 yv[4][2];
; #pragma unroll
;             for (int m = 0; m < 4; ++m)
; #pragma unroll
;                 for (int bj = 0; bj < 2; ++bj) yv[m][bj] = *(const u32x4*)(Y + (size_t)(row0 + ai * 128 + m * 16) * 2048 + col0 + bj * 128);
;             __builtin_amdgcn_sched_barrier(0);
; #pragma unroll
;             for (int m = 0; m < 4; ++m) { bf16_t* rowp = A2 + (size_t)(row0 + ai * 128 + m * 16) * 2048 + col0;
;                 const float mu = st[ai][m][0], rs = st[ai][m][1];
; #pragma unroll
;                 for (int bj = 0; bj < 2; ++bj) { const f32x4 v0 = acc[ai][bj][m][0], v1 = acc[ai][bj][m][1]; const u32x4 yw = yv[m][bj];
;                     const f32x4 y0 = (f32x4){bf_lo(yw.x), bf_hi(yw.x), bf_lo(yw.y), bf_hi(yw.y)}, y1 = (f32x4){bf_lo(yw.z), bf_hi(yw.z), bf_lo(yw.w), bf_hi(yw.w)};
;                     const f32x4 n0 = (y0 - mu) * rs * gw[bj][0], n1 = (y1 - mu) * rs * gw[bj][1];
;                     const f32x4 s0 = silu4(v0) * n0, s1 = silu4(v1) * n1;
;                     u32x4 w; w.x = cvt_pk_bf16(s0[0], s0[1]); w.y = cvt_pk_bf16(s0[2], s0[3]); w.z = cvt_pk_bf16(s1[0], s1[1]); w.w = cvt_pk_bf16(s1[2], s1[3]);
;                     *(u32x4*)(rowp + bj * 128) = w; } }
	v_add_f32_e32 v60, 1.0, v60
	v_add_f32_e32 v61, 1.0, v61
	v_add_f32_e32 v62, 1.0, v62
	v_add_f32_e32 v63, 1.0, v63
	v_cvt_pk_bf16_f32 v53, v58, v59
	v_rcp_f32_e32 v60, v60
	v_rcp_f32_e32 v61, v61
	v_rcp_f32_e32 v62, v62
	v_rcp_f32_e32 v63, v63
	v_cvt_pk_bf16_f32 v50, v54, v55
	v_cvt_pk_bf16_f32 v51, v56, v57
	global_store_dwordx4 v[118:119], v[50:53], off offset:256
	v_lshlrev_b32_e32 v56, 16, v116
	v_and_b32_e32 v57, 0xffff0000, v116
	v_lshlrev_b32_e32 v52, 16, v114
	v_and_b32_e32 v53, 0xffff0000, v114
	v_lshlrev_b32_e32 v58, 16, v117
	v_and_b32_e32 v59, 0xffff0000, v117
	v_lshlrev_b32_e32 v54, 16, v115
	v_and_b32_e32 v55, 0xffff0000, v115
	v_sub_f32_e32 v53, v53, v186
	v_sub_f32_e32 v52, v52, v186
	v_sub_f32_e32 v57, v57, v186
	v_sub_f32_e32 v56, v56, v186
	v_sub_f32_e32 v59, v59, v186
	v_sub_f32_e32 v58, v58, v186
	v_sub_f32_e32 v55, v55, v186
	v_sub_f32_e32 v54, v54, v186
	v_pk_mul_f32 v[52:53], v[186:187], v[52:53] op_sel:[1,0]
	v_pk_mul_f32 v[58:59], v[186:187], v[58:59] op_sel:[1,0]
	v_pk_mul_f32 v[56:57], v[186:187], v[56:57] op_sel:[1,0]
	v_pk_mul_f32 v[54:55], v[186:187], v[54:55] op_sel:[1,0]
	v_pk_mul_f32 v[52:53], v[86:87], v[52:53]
	v_pk_mul_f32 v[56:57], v[82:83], v[56:57]
	v_pk_mul_f32 v[58:59], v[84:85], v[58:59]
	v_pk_mul_f32 v[42:43], v[42:43], v[60:61]
	v_pk_mul_f32 v[44:45], v[44:45], v[62:63]
	v_pk_mul_f32 v[54:55], v[88:89], v[54:55]
	v_pk_mul_f32 v[46:47], v[46:47], v[52:53]
	v_pk_mul_f32 v[52:53], v[44:45], v[58:59]
	v_pk_mul_f32 v[44:45], v[42:43], v[56:57]
	v_pk_mul_f32 v[48:49], v[48:49], v[54:55]
	v_cvt_pk_bf16_f32 v44, v44, v45
	v_cvt_pk_bf16_f32 v45, v52, v53
	v_mul_f32_e32 v52, 0xbfb8aa3b, v38
	v_mul_f32_e32 v53, 0xbfb8aa3b, v39
	v_mul_f32_e32 v54, 0xbfb8aa3b, v40
	v_mul_f32_e32 v55, 0xbfb8aa3b, v41
	v_exp_f32_e32 v52, v52
	v_exp_f32_e32 v53, v53
	v_exp_f32_e32 v54, v54
	v_exp_f32_e32 v55, v55
	v_add_f32_e32 v52, 1.0, v52
	v_add_f32_e32 v53, 1.0, v53
	v_add_f32_e32 v54, 1.0, v54
	v_add_f32_e32 v55, 1.0, v55
	v_rcp_f32_e32 v52, v52
	v_rcp_f32_e32 v53, v53
	v_rcp_f32_e32 v54, v54
	v_rcp_f32_e32 v55, v55
	v_lshl_add_u64 v[50:51], s[34:35], 0, v[120:121]
	v_pk_mul_f32 v[38:39], v[38:39], v[52:53]
	v_mul_f32_e32 v52, 0xbfb8aa3b, v34
	v_pk_mul_f32 v[40:41], v[40:41], v[54:55]
	v_mul_f32_e32 v53, 0xbfb8aa3b, v35
	v_mul_f32_e32 v54, 0xbfb8aa3b, v36
	v_mul_f32_e32 v55, 0xbfb8aa3b, v37
	v_exp_f32_e32 v52, v52
	v_exp_f32_e32 v53, v53
	v_exp_f32_e32 v54, v54
	v_exp_f32_e32 v55, v55
	v_add_f32_e32 v52, 1.0, v52
	v_add_f32_e32 v53, 1.0, v53
	v_add_f32_e32 v54, 1.0, v54
	v_add_f32_e32 v55, 1.0, v55
	v_lshl_add_u64 v[50:51], v[50:51], 0, v[182:183]
	v_cvt_pk_bf16_f32 v42, v46, v47
	v_cvt_pk_bf16_f32 v43, v48, v49
	v_rcp_f32_e32 v52, v52
	v_rcp_f32_e32 v53, v53
	v_rcp_f32_e32 v54, v54
	v_rcp_f32_e32 v55, v55
	global_store_dwordx4 v[50:51], v[42:45], off
	v_lshlrev_b32_e32 v46, 16, v100
	v_and_b32_e32 v47, 0xffff0000, v100
	v_lshlrev_b32_e32 v42, 16, v98
	v_and_b32_e32 v43, 0xffff0000, v98
	v_lshlrev_b32_e32 v44, 16, v99
	v_and_b32_e32 v45, 0xffff0000, v99
	v_lshlrev_b32_e32 v48, 16, v101
	v_and_b32_e32 v49, 0xffff0000, v101
	v_sub_f32_e32 v43, v43, v186
	v_sub_f32_e32 v42, v42, v186
	v_sub_f32_e32 v45, v45, v186
	v_sub_f32_e32 v44, v44, v186
	v_sub_f32_e32 v47, v47, v186
	v_sub_f32_e32 v46, v46, v186
	v_sub_f32_e32 v49, v49, v186
	v_sub_f32_e32 v48, v48, v186
	v_pk_mul_f32 v[44:45], v[186:187], v[44:45] op_sel:[1,0]
	v_pk_mul_f32 v[42:43], v[186:187], v[42:43] op_sel:[1,0]
	v_pk_mul_f32 v[48:49], v[186:187], v[48:49] op_sel:[1,0]
	v_pk_mul_f32 v[46:47], v[186:187], v[46:47] op_sel:[1,0]
	v_pk_mul_f32 v[42:43], v[70:71], v[42:43]
	v_pk_mul_f32 v[44:45], v[72:73], v[44:45]
	v_pk_mul_f32 v[46:47], v[66:67], v[46:47]
	v_pk_mul_f32 v[48:49], v[68:69], v[48:49]
	v_pk_mul_f32 v[34:35], v[34:35], v[52:53]
	v_pk_mul_f32 v[36:37], v[36:37], v[54:55]
	v_pk_mul_f32 v[40:41], v[40:41], v[44:45]
	v_pk_mul_f32 v[38:39], v[38:39], v[42:43]
	v_pk_mul_f32 v[42:43], v[36:37], v[48:49]
	v_pk_mul_f32 v[36:37], v[34:35], v[46:47]
	v_mul_f32_e32 v44, 0xbfb8aa3b, v30
	v_mul_f32_e32 v45, 0xbfb8aa3b, v31
	v_mul_f32_e32 v46, 0xbfb8aa3b, v32
	v_mul_f32_e32 v47, 0xbfb8aa3b, v33
	v_exp_f32_e32 v44, v44
	v_exp_f32_e32 v45, v45
	v_exp_f32_e32 v46, v46
	v_exp_f32_e32 v47, v47
	v_add_f32_e32 v44, 1.0, v44
	v_add_f32_e32 v45, 1.0, v45
	v_add_f32_e32 v46, 1.0, v46
	v_add_f32_e32 v47, 1.0, v47
	v_rcp_f32_e32 v44, v44
	v_rcp_f32_e32 v45, v45
	v_rcp_f32_e32 v46, v46
	v_rcp_f32_e32 v47, v47
	v_cvt_pk_bf16_f32 v36, v36, v37
	v_pk_mul_f32 v[30:31], v[30:31], v[44:45]
	v_mul_f32_e32 v44, 0xbfb8aa3b, v26
	v_pk_mul_f32 v[32:33], v[32:33], v[46:47]
	v_mul_f32_e32 v45, 0xbfb8aa3b, v27
	v_mul_f32_e32 v46, 0xbfb8aa3b, v28
	v_mul_f32_e32 v47, 0xbfb8aa3b, v29
	v_exp_f32_e32 v44, v44
	v_exp_f32_e32 v45, v45
	v_exp_f32_e32 v46, v46
	v_exp_f32_e32 v47, v47
	v_add_f32_e32 v44, 1.0, v44
	v_add_f32_e32 v45, 1.0, v45
	v_add_f32_e32 v46, 1.0, v46
	v_add_f32_e32 v47, 1.0, v47
	v_cvt_pk_bf16_f32 v37, v42, v43
	v_rcp_f32_e32 v44, v44
	v_rcp_f32_e32 v45, v45
	v_rcp_f32_e32 v46, v46
	v_rcp_f32_e32 v47, v47
	v_cvt_pk_bf16_f32 v34, v38, v39
	v_cvt_pk_bf16_f32 v35, v40, v41
	global_store_dwordx4 v[50:51], v[34:37], off offset:256
	v_lshlrev_b32_e32 v40, 16, v96
	v_and_b32_e32 v41, 0xffff0000, v96
	v_lshlrev_b32_e32 v36, 16, v94
	v_and_b32_e32 v37, 0xffff0000, v94
	v_lshlrev_b32_e32 v42, 16, v97
	v_and_b32_e32 v43, 0xffff0000, v97
	v_lshlrev_b32_e32 v38, 16, v95
	v_and_b32_e32 v39, 0xffff0000, v95
	v_sub_f32_e32 v37, v37, v184
	v_sub_f32_e32 v36, v36, v184
	v_sub_f32_e32 v41, v41, v184
	v_sub_f32_e32 v40, v40, v184
	v_sub_f32_e32 v43, v43, v184
	v_sub_f32_e32 v42, v42, v184
; __device__ __forceinline__ unsigned cvt_pk_bf16(float lo, float hi) { unsigned r; asm("v_cvt_pk_bf16_f32 %0, %1, %2" : "=v"(r) : "v"(lo), "v"(hi)); return r; }
; __device__ __forceinline__ float bf_lo(unsigned u) { return __uint_as_float(u << 16); }
; __device__ __forceinline__ float bf_hi(unsigned u) { return __uint_as_float(u & 0xffff0000u); }
;     __device__ __forceinline__ void operator()(const AccT& acc, const Unit& u, int wr, int wc, int fr, int fq) const {
;     ...
;         for (int ai = 0; ai < 2; ++ai) {
;             u32x4 yv[4][2];
; #pragma unroll
;             for (int m = 0; m < 4; ++m)
; #pragma unroll
;                 for (int bj = 0; bj < 2; ++bj) yv[m][bj] = *(const u32x4*)(Y + (size_t)(row0 + ai * 128 + m * 16) * 2048 + col0 + bj * 128);
;             __builtin_amdgcn_sched_barrier(0);
; #pragma unroll
;             for (int m = 0; m < 4; ++m) { bf16_t* rowp = A2 + (size_t)(row0 + ai * 128 + m * 16) * 2048 + col0;
;                 const float mu = st[ai][m][0], rs = st[ai][m][1];
; #pragma unroll
;                 for (int bj = 0; bj < 2; ++bj) { const f32x4 v0 = acc[ai][bj][m][0], v1 = acc[ai][bj][m][1]; const u32x4 yw = yv[m][bj];
;                     const f32x4 y0 = (f32x4){bf_lo(yw.x), bf_hi(yw.x), bf_lo(yw.y), bf_hi(yw.y)}, y1 = (f32x4){bf_lo(yw.z), bf_hi(yw.z), bf_lo(yw.w), bf_hi(yw.w)};
;                     const f32x4 n0 = (y0 - mu) * rs * gw[bj][0], n1 = (y1 - mu) * rs * gw[bj][1];
;                     const f32x4 s0 = silu4(v0) * n0, s1 = silu4(v1) * n1;
;                     u32x4 w; w.x = cvt_pk_bf16(s0[0], s0[1]); w.y = cvt_pk_bf16(s0[2], s0[3]); w.z = cvt_pk_bf16(s1[0], s1[1]); w.w = cvt_pk_bf16(s1[2], s1[3]);
;                     *(u32x4*)(rowp + bj * 128) = w; } }
	v_sub_f32_e32 v39, v39, v184
	v_sub_f32_e32 v38, v38, v184
	v_pk_mul_f32 v[36:37], v[184:185], v[36:37] op_sel:[1,0]
	v_pk_mul_f32 v[42:43], v[184:185], v[42:43] op_sel:[1,0]
	v_pk_mul_f32 v[40:41], v[184:185], v[40:41] op_sel:[1,0]
	v_pk_mul_f32 v[38:39], v[184:185], v[38:39] op_sel:[1,0]
	v_pk_mul_f32 v[36:37], v[86:87], v[36:37]
	v_pk_mul_f32 v[40:41], v[82:83], v[40:41]
	v_pk_mul_f32 v[42:43], v[84:85], v[42:43]
	v_pk_mul_f32 v[26:27], v[26:27], v[44:45]
	v_pk_mul_f32 v[28:29], v[28:29], v[46:47]
	v_pk_mul_f32 v[38:39], v[88:89], v[38:39]
	v_pk_mul_f32 v[30:31], v[30:31], v[36:37]
	v_pk_mul_f32 v[36:37], v[28:29], v[42:43]
	v_pk_mul_f32 v[28:29], v[26:27], v[40:41]
	v_pk_mul_f32 v[32:33], v[32:33], v[38:39]
	v_cvt_pk_bf16_f32 v28, v28, v29
	v_cvt_pk_bf16_f32 v29, v36, v37
	v_mul_f32_e32 v36, 0xbfb8aa3b, v22
	v_mul_f32_e32 v37, 0xbfb8aa3b, v23
	v_mul_f32_e32 v38, 0xbfb8aa3b, v24
	v_mul_f32_e32 v39, 0xbfb8aa3b, v25
	v_exp_f32_e32 v36, v36
	v_exp_f32_e32 v37, v37
	v_exp_f32_e32 v38, v38
	v_exp_f32_e32 v39, v39
	v_add_f32_e32 v36, 1.0, v36
	v_add_f32_e32 v37, 1.0, v37
	v_add_f32_e32 v38, 1.0, v38
	v_add_f32_e32 v39, 1.0, v39
	v_rcp_f32_e32 v36, v36
	v_rcp_f32_e32 v37, v37
	v_rcp_f32_e32 v38, v38
	v_rcp_f32_e32 v39, v39
	v_lshl_add_u64 v[34:35], s[34:35], 0, v[104:105]
	v_pk_mul_f32 v[22:23], v[22:23], v[36:37]
	v_mul_f32_e32 v36, 0xbfb8aa3b, v18
	v_pk_mul_f32 v[24:25], v[24:25], v[38:39]
	v_mul_f32_e32 v37, 0xbfb8aa3b, v19
	v_mul_f32_e32 v38, 0xbfb8aa3b, v20
	v_mul_f32_e32 v39, 0xbfb8aa3b, v21
	v_exp_f32_e32 v36, v36
	v_exp_f32_e32 v37, v37
	v_exp_f32_e32 v38, v38
	v_exp_f32_e32 v39, v39
	v_add_f32_e32 v36, 1.0, v36
	v_add_f32_e32 v37, 1.0, v37
	v_add_f32_e32 v38, 1.0, v38
	v_add_f32_e32 v39, 1.0, v39
	v_lshl_add_u64 v[34:35], v[34:35], 0, v[182:183]
	v_cvt_pk_bf16_f32 v26, v30, v31
	v_cvt_pk_bf16_f32 v27, v32, v33
	v_rcp_f32_e32 v36, v36
	v_rcp_f32_e32 v37, v37
	v_rcp_f32_e32 v38, v38
	v_rcp_f32_e32 v39, v39
	global_store_dwordx4 v[34:35], v[26:29], off
	v_lshlrev_b32_e32 v30, 16, v92
	v_and_b32_e32 v31, 0xffff0000, v92
	v_lshlrev_b32_e32 v26, 16, v90
	v_and_b32_e32 v27, 0xffff0000, v90
	v_lshlrev_b32_e32 v28, 16, v91
	v_and_b32_e32 v29, 0xffff0000, v91
	v_lshlrev_b32_e32 v32, 16, v93
	v_and_b32_e32 v33, 0xffff0000, v93
	v_sub_f32_e32 v27, v27, v184
	v_sub_f32_e32 v26, v26, v184
	v_sub_f32_e32 v29, v29, v184
	v_sub_f32_e32 v28, v28, v184
	v_sub_f32_e32 v31, v31, v184
	v_sub_f32_e32 v30, v30, v184
	v_sub_f32_e32 v33, v33, v184
	v_sub_f32_e32 v32, v32, v184
	v_pk_mul_f32 v[28:29], v[184:185], v[28:29] op_sel:[1,0]
	v_pk_mul_f32 v[26:27], v[184:185], v[26:27] op_sel:[1,0]
	v_pk_mul_f32 v[32:33], v[184:185], v[32:33] op_sel:[1,0]
	v_pk_mul_f32 v[30:31], v[184:185], v[30:31] op_sel:[1,0]
	v_pk_mul_f32 v[26:27], v[70:71], v[26:27]
	v_pk_mul_f32 v[28:29], v[72:73], v[28:29]
	v_pk_mul_f32 v[30:31], v[66:67], v[30:31]
	v_pk_mul_f32 v[32:33], v[68:69], v[32:33]
	v_pk_mul_f32 v[18:19], v[18:19], v[36:37]
	v_pk_mul_f32 v[20:21], v[20:21], v[38:39]
	v_pk_mul_f32 v[24:25], v[24:25], v[28:29]
	v_pk_mul_f32 v[22:23], v[22:23], v[26:27]
	v_pk_mul_f32 v[26:27], v[20:21], v[32:33]
	v_pk_mul_f32 v[20:21], v[18:19], v[30:31]
	v_mul_f32_e32 v28, 0xbfb8aa3b, v14
	v_mul_f32_e32 v29, 0xbfb8aa3b, v15
	v_mul_f32_e32 v30, 0xbfb8aa3b, v16
	v_mul_f32_e32 v31, 0xbfb8aa3b, v17
	v_exp_f32_e32 v28, v28
	v_exp_f32_e32 v29, v29
	v_exp_f32_e32 v30, v30
	v_exp_f32_e32 v31, v31
	v_add_f32_e32 v28, 1.0, v28
	v_add_f32_e32 v29, 1.0, v29
	v_add_f32_e32 v30, 1.0, v30
	v_add_f32_e32 v31, 1.0, v31
	v_rcp_f32_e32 v28, v28
	v_rcp_f32_e32 v29, v29
	v_rcp_f32_e32 v30, v30
	v_rcp_f32_e32 v31, v31
	v_cvt_pk_bf16_f32 v20, v20, v21
	v_pk_mul_f32 v[14:15], v[14:15], v[28:29]
	v_mul_f32_e32 v28, 0xbfb8aa3b, v10
	v_pk_mul_f32 v[16:17], v[16:17], v[30:31]
	v_mul_f32_e32 v29, 0xbfb8aa3b, v11
	v_mul_f32_e32 v30, 0xbfb8aa3b, v12
	v_mul_f32_e32 v31, 0xbfb8aa3b, v13
	v_exp_f32_e32 v28, v28
	v_exp_f32_e32 v29, v29
	v_exp_f32_e32 v30, v30
	v_exp_f32_e32 v31, v31
	v_add_f32_e32 v28, 1.0, v28
	v_add_f32_e32 v29, 1.0, v29
	v_add_f32_e32 v30, 1.0, v30
	v_add_f32_e32 v31, 1.0, v31
	v_cvt_pk_bf16_f32 v21, v26, v27
	v_rcp_f32_e32 v28, v28
	v_rcp_f32_e32 v29, v29
; __device__ __forceinline__ unsigned cvt_pk_bf16(float lo, float hi) { unsigned r; asm("v_cvt_pk_bf16_f32 %0, %1, %2" : "=v"(r) : "v"(lo), "v"(hi)); return r; }
; __device__ __forceinline__ float bf_lo(unsigned u) { return __uint_as_float(u << 16); }
; __device__ __forceinline__ float bf_hi(unsigned u) { return __uint_as_float(u & 0xffff0000u); }
; #define PG8_WAIT_V(n) asm volatile("s_waitcnt vmcnt(" #n ")" ::: "memory")
; #define PG8_BAR __builtin_amdgcn_s_barrier()
; template <class Epi>
; __device__ __forceinline__ void gemm_phase(LAS unsigned char* lds, const Gemm g, const Epi& E) {
;     ...
;         if (!has_next) break;
; #pragma unroll
;         for (int a = 0; a < 2; ++a)
; #pragma unroll
;             for (int b = 0; b < 2; ++b)
; #pragma unroll
;                 for (int m = 0; m < 4; ++m)
; #pragma unroll
;                     for (int n = 0; n < 2; ++n) acc[a][b][m][n] = (f32x4){0.f, 0.f, 0.f, 0.f};
;         cur = nxt; cA = nA; cB = nB; ++ui;
;     }
;     PG8_WAIT_V(0);
;     if (wr == 0) PG8_BAR;
;     PG8_BAR;
;     __device__ __forceinline__ void operator()(const AccT& acc, const Unit& u, int wr, int wc, int fr, int fq) const {
;     ...
;             for (int m = 0; m < 4; ++m) { bf16_t* rowp = A2 + (size_t)(row0 + ai * 128 + m * 16) * 2048 + col0;
;                 const float mu = st[ai][m][0], rs = st[ai][m][1];
; #pragma unroll
;                 for (int bj = 0; bj < 2; ++bj) { const f32x4 v0 = acc[ai][bj][m][0], v1 = acc[ai][bj][m][1]; const u32x4 yw = yv[m][bj];
;                     const f32x4 y0 = (f32x4){bf_lo(yw.x), bf_hi(yw.x), bf_lo(yw.y), bf_hi(yw.y)}, y1 = (f32x4){bf_lo(yw.z), bf_hi(yw.z), bf_lo(yw.w), bf_hi(yw.w)};
;                     const f32x4 n0 = (y0 - mu) * rs * gw[bj][0], n1 = (y1 - mu) * rs * gw[bj][1];
;                     const f32x4 s0 = silu4(v0) * n0, s1 = silu4(v1) * n1;
;                     u32x4 w; w.x = cvt_pk_bf16(s0[0], s0[1]); w.y = cvt_pk_bf16(s0[2], s0[3]); w.z = cvt_pk_bf16(s1[0], s1[1]); w.w = cvt_pk_bf16(s1[2], s1[3]);
;                     *(u32x4*)(rowp + bj * 128) = w; } }
	v_rcp_f32_e32 v30, v30
	v_rcp_f32_e32 v31, v31
	v_cvt_pk_bf16_f32 v18, v22, v23
	v_cvt_pk_bf16_f32 v19, v24, v25
	global_store_dwordx4 v[34:35], v[18:21], off offset:256
	v_lshlrev_b32_e32 v24, 16, v80
	v_and_b32_e32 v25, 0xffff0000, v80
	v_lshlrev_b32_e32 v20, 16, v78
	v_and_b32_e32 v21, 0xffff0000, v78
	v_lshlrev_b32_e32 v26, 16, v81
	v_and_b32_e32 v27, 0xffff0000, v81
	v_lshlrev_b32_e32 v22, 16, v79
	v_and_b32_e32 v23, 0xffff0000, v79
	v_sub_f32_e32 v21, v21, v180
	v_sub_f32_e32 v20, v20, v180
	v_sub_f32_e32 v25, v25, v180
	v_sub_f32_e32 v24, v24, v180
	v_sub_f32_e32 v27, v27, v180
	v_sub_f32_e32 v26, v26, v180
	v_sub_f32_e32 v23, v23, v180
	v_sub_f32_e32 v22, v22, v180
	v_pk_mul_f32 v[20:21], v[180:181], v[20:21] op_sel:[1,0]
	v_pk_mul_f32 v[26:27], v[180:181], v[26:27] op_sel:[1,0]
	v_pk_mul_f32 v[24:25], v[180:181], v[24:25] op_sel:[1,0]
	v_pk_mul_f32 v[22:23], v[180:181], v[22:23] op_sel:[1,0]
	v_pk_mul_f32 v[20:21], v[86:87], v[20:21]
	v_pk_mul_f32 v[24:25], v[82:83], v[24:25]
	v_pk_mul_f32 v[26:27], v[84:85], v[26:27]
	v_pk_mul_f32 v[10:11], v[10:11], v[28:29]
	v_pk_mul_f32 v[12:13], v[12:13], v[30:31]
	v_pk_mul_f32 v[22:23], v[88:89], v[22:23]
	v_pk_mul_f32 v[14:15], v[14:15], v[20:21]
	v_pk_mul_f32 v[20:21], v[12:13], v[26:27]
	v_pk_mul_f32 v[12:13], v[10:11], v[24:25]
	v_pk_mul_f32 v[16:17], v[16:17], v[22:23]
	v_cvt_pk_bf16_f32 v12, v12, v13
	v_cvt_pk_bf16_f32 v13, v20, v21
	v_mul_f32_e32 v20, 0xbfb8aa3b, v6
	v_mul_f32_e32 v21, 0xbfb8aa3b, v7
	v_mul_f32_e32 v22, 0xbfb8aa3b, v8
	v_mul_f32_e32 v23, 0xbfb8aa3b, v9
	v_exp_f32_e32 v20, v20
	v_exp_f32_e32 v21, v21
	v_exp_f32_e32 v22, v22
	v_exp_f32_e32 v23, v23
	v_add_f32_e32 v20, 1.0, v20
	v_add_f32_e32 v21, 1.0, v21
	v_add_f32_e32 v22, 1.0, v22
	v_add_f32_e32 v23, 1.0, v23
	v_rcp_f32_e32 v20, v20
	v_rcp_f32_e32 v21, v21
	v_rcp_f32_e32 v22, v22
	v_rcp_f32_e32 v23, v23
	v_lshl_add_u64 v[18:19], s[34:35], 0, v[102:103]
	v_pk_mul_f32 v[6:7], v[6:7], v[20:21]
	v_mul_f32_e32 v20, 0xbfb8aa3b, v2
	v_pk_mul_f32 v[8:9], v[8:9], v[22:23]
	v_mul_f32_e32 v21, 0xbfb8aa3b, v3
	v_mul_f32_e32 v22, 0xbfb8aa3b, v4
	v_mul_f32_e32 v23, 0xbfb8aa3b, v5
	v_exp_f32_e32 v20, v20
	v_exp_f32_e32 v21, v21
	v_exp_f32_e32 v22, v22
	v_exp_f32_e32 v23, v23
	v_add_f32_e32 v20, 1.0, v20
	v_add_f32_e32 v21, 1.0, v21
	v_add_f32_e32 v22, 1.0, v22
	v_add_f32_e32 v23, 1.0, v23
	v_lshl_add_u64 v[18:19], v[18:19], 0, v[182:183]
	v_cvt_pk_bf16_f32 v10, v14, v15
	v_cvt_pk_bf16_f32 v11, v16, v17
	v_rcp_f32_e32 v20, v20
	v_rcp_f32_e32 v21, v21
	v_rcp_f32_e32 v22, v22
	v_rcp_f32_e32 v23, v23
	global_store_dwordx4 v[18:19], v[10:13], off
	v_lshlrev_b32_e32 v14, 16, v76
	v_and_b32_e32 v15, 0xffff0000, v76
	v_lshlrev_b32_e32 v10, 16, v74
	v_and_b32_e32 v11, 0xffff0000, v74
	v_lshlrev_b32_e32 v16, 16, v77
	v_and_b32_e32 v17, 0xffff0000, v77
	v_lshlrev_b32_e32 v12, 16, v75
	v_and_b32_e32 v13, 0xffff0000, v75
	v_sub_f32_e32 v11, v11, v180
	v_sub_f32_e32 v10, v10, v180
	v_sub_f32_e32 v15, v15, v180
	v_sub_f32_e32 v14, v14, v180
	v_sub_f32_e32 v17, v17, v180
	v_sub_f32_e32 v16, v16, v180
	v_sub_f32_e32 v13, v13, v180
	v_sub_f32_e32 v12, v12, v180
	v_pk_mul_f32 v[10:11], v[180:181], v[10:11] op_sel:[1,0]
	v_pk_mul_f32 v[16:17], v[180:181], v[16:17] op_sel:[1,0]
	v_pk_mul_f32 v[14:15], v[180:181], v[14:15] op_sel:[1,0]
	v_pk_mul_f32 v[12:13], v[180:181], v[12:13] op_sel:[1,0]
	v_pk_mul_f32 v[10:11], v[70:71], v[10:11]
	v_pk_mul_f32 v[14:15], v[66:67], v[14:15]
	v_pk_mul_f32 v[16:17], v[68:69], v[16:17]
	v_pk_mul_f32 v[2:3], v[2:3], v[20:21]
	v_pk_mul_f32 v[4:5], v[4:5], v[22:23]
	v_pk_mul_f32 v[12:13], v[72:73], v[12:13]
	v_pk_mul_f32 v[6:7], v[6:7], v[10:11]
	v_pk_mul_f32 v[10:11], v[4:5], v[16:17]
	v_pk_mul_f32 v[4:5], v[2:3], v[14:15]
	v_pk_mul_f32 v[8:9], v[8:9], v[12:13]
	v_cvt_pk_bf16_f32 v2, v6, v7
	v_cvt_pk_bf16_f32 v4, v4, v5
	v_cvt_pk_bf16_f32 v5, v10, v11
	s_nop 0
	v_cvt_pk_bf16_f32 v3, v8, v9
	global_store_dwordx4 v[18:19], v[2:5], off offset:256
	s_and_b64 vcc, exec, s[2:3]
	s_mov_b32 s12, s8
	s_mov_b32 s52, s64
	s_mov_b64 s[16:17], s[4:5]
	s_mov_b64 s[14:15], s[10:11]
	s_cbranch_vccz .LBB0_470
	s_waitcnt vmcnt(0)
	s_cmpk_gt_u32 s1, 0xff
	s_cbranch_scc1 .LBB0_479
	s_barrier

; #define PG8_STAGE(bufoff, gbase, voff) do { _Pragma("unroll") for (int _i = 0; _i < 2; ++_i) \
;         __builtin_amdgcn_global_load_lds((const unsigned*)((const char*)(gbase) + (voff)[_i]), (LAS unsigned*)(lds + (bufoff) + ldsw + _i * 8192), 16, 0, 0); } while (0)
; #define PG8_LDA(dst, b, h) do { _Pragma("unroll") for (int m = 0; m < 4; ++m) _Pragma("unroll") for (int k = 0; k < 2; ++k) dst[m][k] = *(const LAS bf16x8*)(lds + PG8_SA(b, h) + aoff + m * 2048 + k * 1024); } while (0)
; #define PG8_LDB(dst, b, h) do { _Pragma("unroll") for (int n = 0; n < 2; ++n) _Pragma("unroll") for (int k = 0; k < 2; ++k) dst[n][k] = *(const LAS bf16x8*)(lds + PG8_SB(b, h) + boff + n * 2048 + k * 1024); } while (0)
; #define PG8_MMA(ai, bj, At, Bt) do { __builtin_amdgcn_s_setprio(1); _Pragma("unroll") for (int m = 0; m < 4; ++m) _Pragma("unroll") for (int n = 0; n < 2; ++n) _Pragma("unroll") for (int k = 0; k < 2; ++k) \
;         acc[ai][bj][m][n] = __builtin_amdgcn_mfma_f32_16x16x32_bf16(Bt[n][k], At[m][k], acc[ai][bj][m][n], 0, 0, 0); __builtin_amdgcn_s_setprio(0); } while (0)
; #define PG8_WAIT_L(n) asm volatile("s_waitcnt lgkmcnt(" #n ")" ::: "memory")
; #define PG8_BAR __builtin_amdgcn_s_barrier()
; #define PG8_SCHED __builtin_amdgcn_sched_barrier(0)
; template <class Epi>
; __device__ __forceinline__ void gemm_phase(LAS unsigned char* lds, const Gemm g, const Epi& E) {
;     ...
;             PG8_LDB(B0, 0, 0); PG8_SCHED; PG8_LDA(At, 0, 0); PG8_STAGE(PG8_SA(1, 1), a1 + hstepA, voffA);
;             PG8_WAIT_L(8); PG8_BAR; PG8_WAIT_L(0); PG8_MMA(0, 0, At, B0); PG8_BAR; PG8_SCHED;
;             PG8_LDB(B1, 0, 1); PG8_STAGE(PG8_SB(0, 0), b2, voffB);
;             PG8_BAR; PG8_WAIT_L(0); PG8_MMA(0, 1, At, B1); PG8_BAR;
;             PG8_LDA(At, 0, 1); PG8_STAGE(PG8_SA(0, 0), a2, voffA);
;             PG8_BAR; PG8_WAIT_L(0); PG8_MMA(1, 0, At, B0); PG8_BAR; PG8_SCHED;
.LBB0_495:
	s_add_u32 s14, s12, 0xfff80080
	s_addc_u32 s15, s13, -1
	s_add_i32 s66, 0, 0x10000
	v_add_u32_e32 v142, s66, v159
	ds_read_b128 v[130:133], v142
	ds_read_b128 v[134:137], v142 offset:1024
	ds_read_b128 v[138:141], v142 offset:2048
	ds_read_b128 v[142:145], v142 offset:3072
	s_cmp_eq_u32 s65, 28
	s_cselect_b32 s17, s9, s15
	s_cselect_b32 s16, s8, s14
	s_cselect_b32 s15, s5, s64
	s_cselect_b32 s14, s4, s7
	v_lshl_add_u64 v[192:193], s[12:13], 0, v[150:151]
	s_add_i32 m0, s11, 0xc000
	ds_read_b128 v[154:157], v160
	ds_read_b128 v[162:165], v160 offset:1024
	ds_read_b128 v[166:169], v160 offset:2048
	ds_read_b128 v[170:173], v160 offset:3072
	ds_read_b128 v[174:177], v160 offset:4096
	ds_read_b128 v[180:183], v160 offset:5120
	ds_read_b128 v[184:187], v160 offset:6144
	ds_read_b128 v[188:191], v160 offset:7168
	global_load_lds_dwordx4 v[192:193], off
	v_lshl_add_u64 v[192:193], s[12:13], 0, v[152:153]
	s_add_i32 m0, s11, 0xe000
	s_nop 0
	global_load_lds_dwordx4 v[192:193], off
	s_waitcnt lgkmcnt(0)
	s_barrier
	s_setprio 1
	v_mfma_f32_16x16x32_bf16 v[126:129], v[130:133], v[154:157], v[126:129]
	v_mfma_f32_16x16x32_bf16 v[122:125], v[138:141], v[154:157], v[122:125]
	v_mfma_f32_16x16x32_bf16 v[114:117], v[130:133], v[166:169], v[114:117]
	v_mfma_f32_16x16x32_bf16 v[106:109], v[138:141], v[166:169], v[106:109]
	v_mfma_f32_16x16x32_bf16 v[102:105], v[130:133], v[174:177], v[102:105]
	v_mfma_f32_16x16x32_bf16 v[90:93], v[138:141], v[174:177], v[90:93]
	v_mfma_f32_16x16x32_bf16 v[86:89], v[130:133], v[184:187], v[86:89]
	v_mfma_f32_16x16x32_bf16 v[74:77], v[138:141], v[184:187], v[74:77]
	v_mfma_f32_16x16x32_bf16 v[126:129], v[134:137], v[162:165], v[126:129]
	v_mfma_f32_16x16x32_bf16 v[122:125], v[142:145], v[162:165], v[122:125]
	v_mfma_f32_16x16x32_bf16 v[114:117], v[134:137], v[170:173], v[114:117]
	v_mfma_f32_16x16x32_bf16 v[106:109], v[142:145], v[170:173], v[106:109]
	v_mfma_f32_16x16x32_bf16 v[102:105], v[134:137], v[180:183], v[102:105]
	v_mfma_f32_16x16x32_bf16 v[90:93], v[142:145], v[180:183], v[90:93]
	v_mfma_f32_16x16x32_bf16 v[86:89], v[134:137], v[188:191], v[86:89]
	v_mfma_f32_16x16x32_bf16 v[74:77], v[142:145], v[188:191], v[74:77]
	s_setprio 0
	s_barrier
	s_add_i32 s68, 0, 0x14000
	s_add_i32 s66, s66, s25
	v_add_u32_e32 v161, s68, v159
	v_lshl_add_u64 v[208:209], s[14:15], 0, v[148:149]
	s_mov_b32 m0, s66
	ds_read_b128 v[192:195], v161
	ds_read_b128 v[196:199], v161 offset:1024
	ds_read_b128 v[200:203], v161 offset:2048
	ds_read_b128 v[204:207], v161 offset:3072
	global_load_lds_dwordx4 v[208:209], off
	v_lshl_add_u64 v[226:227], s[14:15], 0, v[146:147]
	s_add_i32 m0, s66, 0x2000
	s_nop 0
	global_load_lds_dwordx4 v[226:227], off
	s_waitcnt lgkmcnt(0)
	s_barrier
	s_setprio 1
	v_mfma_f32_16x16x32_bf16 v[118:121], v[192:195], v[154:157], v[118:121]
	v_mfma_f32_16x16x32_bf16 v[110:113], v[200:203], v[154:157], v[110:113]
	v_mfma_f32_16x16x32_bf16 v[98:101], v[192:195], v[166:169], v[98:101]
	v_mfma_f32_16x16x32_bf16 v[94:97], v[200:203], v[166:169], v[94:97]
	v_mfma_f32_16x16x32_bf16 v[82:85], v[192:195], v[174:177], v[82:85]
	v_mfma_f32_16x16x32_bf16 v[78:81], v[200:203], v[174:177], v[78:81]
	v_mfma_f32_16x16x32_bf16 v[70:73], v[192:195], v[184:187], v[70:73]
	v_mfma_f32_16x16x32_bf16 v[66:69], v[200:203], v[184:187], v[66:69]
	v_mfma_f32_16x16x32_bf16 v[118:121], v[196:199], v[162:165], v[118:121]
	v_mfma_f32_16x16x32_bf16 v[110:113], v[204:207], v[162:165], v[110:113]
	v_mfma_f32_16x16x32_bf16 v[98:101], v[196:199], v[170:173], v[98:101]
	v_mfma_f32_16x16x32_bf16 v[94:97], v[204:207], v[170:173], v[94:97]
	v_mfma_f32_16x16x32_bf16 v[82:85], v[196:199], v[180:183], v[82:85]
	v_mfma_f32_16x16x32_bf16 v[78:81], v[204:207], v[180:183], v[78:81]
	v_mfma_f32_16x16x32_bf16 v[70:73], v[196:199], v[188:191], v[70:73]
	v_mfma_f32_16x16x32_bf16 v[66:69], v[204:207], v[188:191], v[66:69]
	s_setprio 0
	s_mov_b32 m0, s11
	v_lshl_add_u64 v[228:229], s[16:17], 0, v[148:149]
	s_barrier
	ds_read_b128 v[154:157], v160 offset:16384
	ds_read_b128 v[162:165], v160 offset:17408
	ds_read_b128 v[166:169], v160 offset:18432
	ds_read_b128 v[170:173], v160 offset:19456
	ds_read_b128 v[174:177], v160 offset:20480
	ds_read_b128 v[180:183], v160 offset:21504
	ds_read_b128 v[184:187], v160 offset:22528
	ds_read_b128 v[188:191], v160 offset:23552
	global_load_lds_dwordx4 v[228:229], off
	v_lshl_add_u64 v[230:231], s[16:17], 0, v[146:147]
	s_mov_b32 m0, s31
	s_nop 0
	global_load_lds_dwordx4 v[230:231], off
	s_waitcnt lgkmcnt(0)
	s_barrier
	s_setprio 1
	v_mfma_f32_16x16x32_bf16 v[62:65], v[130:133], v[154:157], v[62:65]
	v_mfma_f32_16x16x32_bf16 v[58:61], v[138:141], v[154:157], v[58:61]
	v_mfma_f32_16x16x32_bf16 v[54:57], v[130:133], v[166:169], v[54:57]
	v_mfma_f32_16x16x32_bf16 v[42:45], v[138:141], v[166:169], v[42:45]
	v_mfma_f32_16x16x32_bf16 v[38:41], v[130:133], v[174:177], v[38:41]
	v_mfma_f32_16x16x32_bf16 v[26:29], v[138:141], v[174:177], v[26:29]
	v_mfma_f32_16x16x32_bf16 v[22:25], v[130:133], v[184:187], v[22:25]
	v_mfma_f32_16x16x32_bf16 v[10:13], v[138:141], v[184:187], v[10:13]
	v_mfma_f32_16x16x32_bf16 v[62:65], v[134:137], v[162:165], v[62:65]
	v_mfma_f32_16x16x32_bf16 v[58:61], v[142:145], v[162:165], v[58:61]
	v_mfma_f32_16x16x32_bf16 v[54:57], v[134:137], v[170:173], v[54:57]
	v_mfma_f32_16x16x32_bf16 v[42:45], v[142:145], v[170:173], v[42:45]
	v_mfma_f32_16x16x32_bf16 v[38:41], v[134:137], v[180:183], v[38:41]
	v_mfma_f32_16x16x32_bf16 v[26:29], v[142:145], v[180:183], v[26:29]
	v_mfma_f32_16x16x32_bf16 v[22:25], v[134:137], v[188:191], v[22:25]
	v_mfma_f32_16x16x32_bf16 v[10:13], v[142:145], v[188:191], v[10:13]
	s_setprio 0
	s_barrier
; #define PG8_STAGE(bufoff, gbase, voff) do { _Pragma("unroll") for (int _i = 0; _i < 2; ++_i) \
;         __builtin_amdgcn_global_load_lds((const unsigned*)((const char*)(gbase) + (voff)[_i]), (LAS unsigned*)(lds + (bufoff) + ldsw + _i * 8192), 16, 0, 0); } while (0)
; #define PG8_LDA(dst, b, h) do { _Pragma("unroll") for (int m = 0; m < 4; ++m) _Pragma("unroll") for (int k = 0; k < 2; ++k) dst[m][k] = *(const LAS bf16x8*)(lds + PG8_SA(b, h) + aoff + m * 2048 + k * 1024); } while (0)
; #define PG8_LDB(dst, b, h) do { _Pragma("unroll") for (int n = 0; n < 2; ++n) _Pragma("unroll") for (int k = 0; k < 2; ++k) dst[n][k] = *(const LAS bf16x8*)(lds + PG8_SB(b, h) + boff + n * 2048 + k * 1024); } while (0)
; #define PG8_MMA(ai, bj, At, Bt) do { __builtin_amdgcn_s_setprio(1); _Pragma("unroll") for (int m = 0; m < 4; ++m) _Pragma("unroll") for (int n = 0; n < 2; ++n) _Pragma("unroll") for (int k = 0; k < 2; ++k) \
;         acc[ai][bj][m][n] = __builtin_amdgcn_mfma_f32_16x16x32_bf16(Bt[n][k], At[m][k], acc[ai][bj][m][n], 0, 0, 0); __builtin_amdgcn_s_setprio(0); } while (0)
; #define PG8_WAIT_V(n) asm volatile("s_waitcnt vmcnt(" #n ")" ::: "memory")
; #define PG8_WAIT_L(n) asm volatile("s_waitcnt lgkmcnt(" #n ")" ::: "memory")
; #define PG8_BAR __builtin_amdgcn_s_barrier()
; #define PG8_SCHED __builtin_amdgcn_sched_barrier(0)
; template <class Epi>
; __device__ __forceinline__ void gemm_phase(LAS unsigned char* lds, const Gemm g, const Epi& E) {
;     ...
;             PG8_STAGE(PG8_SB(0, 1), b2 + hstepB, voffB);
;             PG8_WAIT_V(6); PG8_BAR; PG8_MMA(1, 1, At, B1); PG8_BAR;
;             PG8_LDB(B0, 1, 0); PG8_SCHED; PG8_LDA(At, 1, 0); PG8_STAGE(PG8_SA(0, 1), a2 + hstepA, voffA);
;             PG8_WAIT_L(8); PG8_BAR; PG8_WAIT_L(0); PG8_MMA(0, 0, At, B0); PG8_BAR; PG8_SCHED;
;             PG8_LDB(B1, 1, 1); PG8_STAGE(PG8_SB(1, 0), b3, voffB);
;             PG8_BAR; PG8_WAIT_L(0); PG8_MMA(0, 1, At, B1); PG8_BAR;
;             PG8_LDA(At, 1, 1); PG8_STAGE(PG8_SA(1, 0), a3, voffA);
	s_add_u32 s66, s14, 0x80000
	s_addc_u32 s67, s15, 0
	s_add_i32 s68, s68, s25
	v_lshl_add_u64 v[130:131], s[66:67], 0, v[148:149]
	s_mov_b32 m0, s68
	s_nop 0
	global_load_lds_dwordx4 v[130:131], off
	v_lshl_add_u64 v[130:131], s[66:67], 0, v[146:147]
	s_add_i32 m0, s68, 0x2000
	s_nop 0
	global_load_lds_dwordx4 v[130:131], off
	s_waitcnt vmcnt(6)
	s_barrier
	s_setprio 1
	v_mfma_f32_16x16x32_bf16 v[50:53], v[192:195], v[154:157], v[50:53]
	v_mfma_f32_16x16x32_bf16 v[46:49], v[200:203], v[154:157], v[46:49]
	v_mfma_f32_16x16x32_bf16 v[34:37], v[192:195], v[166:169], v[34:37]
	v_mfma_f32_16x16x32_bf16 v[30:33], v[200:203], v[166:169], v[30:33]
	v_mfma_f32_16x16x32_bf16 v[18:21], v[192:195], v[174:177], v[18:21]
	v_mfma_f32_16x16x32_bf16 v[14:17], v[200:203], v[174:177], v[14:17]
	v_mfma_f32_16x16x32_bf16 v[6:9], v[192:195], v[184:187], v[6:9]
	v_mfma_f32_16x16x32_bf16 v[2:5], v[200:203], v[184:187], v[2:5]
	v_mfma_f32_16x16x32_bf16 v[50:53], v[196:199], v[162:165], v[50:53]
	v_mfma_f32_16x16x32_bf16 v[46:49], v[204:207], v[162:165], v[46:49]
	v_mfma_f32_16x16x32_bf16 v[34:37], v[196:199], v[170:173], v[34:37]
	v_mfma_f32_16x16x32_bf16 v[30:33], v[204:207], v[170:173], v[30:33]
	v_mfma_f32_16x16x32_bf16 v[18:21], v[196:199], v[180:183], v[18:21]
	v_mfma_f32_16x16x32_bf16 v[14:17], v[204:207], v[180:183], v[14:17]
	v_mfma_f32_16x16x32_bf16 v[6:9], v[196:199], v[188:191], v[6:9]
	v_mfma_f32_16x16x32_bf16 v[2:5], v[204:207], v[188:191], v[2:5]
	s_setprio 0
	s_add_i32 s66, 0, 0x18000
	v_add_u32_e32 v142, s66, v159
	s_barrier
	ds_read_b128 v[130:133], v142
	ds_read_b128 v[134:137], v142 offset:1024
	ds_read_b128 v[138:141], v142 offset:2048
	ds_read_b128 v[142:145], v142 offset:3072
	s_add_u32 s16, s16, 0x80000
	s_addc_u32 s17, s17, 0
	s_mov_b32 m0, s36
	v_lshl_add_u64 v[192:193], s[16:17], 0, v[148:149]
	ds_read_b128 v[154:157], v160 offset:32768
	ds_read_b128 v[162:165], v160 offset:33792
	ds_read_b128 v[166:169], v160 offset:34816
	ds_read_b128 v[170:173], v160 offset:35840
	ds_read_b128 v[174:177], v160 offset:36864
	ds_read_b128 v[180:183], v160 offset:37888
	ds_read_b128 v[184:187], v160 offset:38912
	ds_read_b128 v[188:191], v160 offset:39936
	global_load_lds_dwordx4 v[192:193], off
	v_lshl_add_u64 v[192:193], s[16:17], 0, v[146:147]
	s_mov_b32 m0, s44
	s_nop 0
	global_load_lds_dwordx4 v[192:193], off
	s_waitcnt lgkmcnt(0)
	s_barrier
	s_setprio 1
	v_mfma_f32_16x16x32_bf16 v[126:129], v[130:133], v[154:157], v[126:129]
	v_mfma_f32_16x16x32_bf16 v[122:125], v[138:141], v[154:157], v[122:125]
	v_mfma_f32_16x16x32_bf16 v[114:117], v[130:133], v[166:169], v[114:117]
	v_mfma_f32_16x16x32_bf16 v[106:109], v[138:141], v[166:169], v[106:109]
	v_mfma_f32_16x16x32_bf16 v[102:105], v[130:133], v[174:177], v[102:105]
	v_mfma_f32_16x16x32_bf16 v[90:93], v[138:141], v[174:177], v[90:93]
	v_mfma_f32_16x16x32_bf16 v[86:89], v[130:133], v[184:187], v[86:89]
	v_mfma_f32_16x16x32_bf16 v[74:77], v[138:141], v[184:187], v[74:77]
	v_mfma_f32_16x16x32_bf16 v[126:129], v[134:137], v[162:165], v[126:129]
	v_mfma_f32_16x16x32_bf16 v[122:125], v[142:145], v[162:165], v[122:125]
	v_mfma_f32_16x16x32_bf16 v[114:117], v[134:137], v[170:173], v[114:117]
	v_mfma_f32_16x16x32_bf16 v[106:109], v[142:145], v[170:173], v[106:109]
	v_mfma_f32_16x16x32_bf16 v[102:105], v[134:137], v[180:183], v[102:105]
	v_mfma_f32_16x16x32_bf16 v[90:93], v[142:145], v[180:183], v[90:93]
	v_mfma_f32_16x16x32_bf16 v[86:89], v[134:137], v[188:191], v[86:89]
	v_mfma_f32_16x16x32_bf16 v[74:77], v[142:145], v[188:191], v[74:77]
	s_setprio 0
	s_barrier
	s_add_i32 s16, 0, 0x1c000
	s_add_i32 s17, s66, s25
	v_add_u32_e32 v161, s16, v159
	v_lshl_add_u64 v[208:209], v[208:209], 0, s[86:87]
	s_mov_b32 m0, s17
	ds_read_b128 v[192:195], v161
	ds_read_b128 v[196:199], v161 offset:1024
	ds_read_b128 v[200:203], v161 offset:2048
	ds_read_b128 v[204:207], v161 offset:3072
	global_load_lds_dwordx4 v[208:209], off
	v_lshl_add_u64 v[208:209], v[226:227], 0, s[86:87]
	s_add_i32 m0, s17, 0x2000
	s_nop 0
	global_load_lds_dwordx4 v[208:209], off
	s_waitcnt lgkmcnt(0)
	s_barrier
	s_setprio 1
	v_mfma_f32_16x16x32_bf16 v[118:121], v[192:195], v[154:157], v[118:121]
	v_mfma_f32_16x16x32_bf16 v[110:113], v[200:203], v[154:157], v[110:113]
	v_mfma_f32_16x16x32_bf16 v[98:101], v[192:195], v[166:169], v[98:101]
	v_mfma_f32_16x16x32_bf16 v[94:97], v[200:203], v[166:169], v[94:97]
	v_mfma_f32_16x16x32_bf16 v[82:85], v[192:195], v[174:177], v[82:85]
	v_mfma_f32_16x16x32_bf16 v[78:81], v[200:203], v[174:177], v[78:81]
	v_mfma_f32_16x16x32_bf16 v[70:73], v[192:195], v[184:187], v[70:73]
	v_mfma_f32_16x16x32_bf16 v[66:69], v[200:203], v[184:187], v[66:69]
	v_mfma_f32_16x16x32_bf16 v[118:121], v[196:199], v[162:165], v[118:121]
	v_mfma_f32_16x16x32_bf16 v[110:113], v[204:207], v[162:165], v[110:113]
	v_mfma_f32_16x16x32_bf16 v[98:101], v[196:199], v[170:173], v[98:101]
	v_mfma_f32_16x16x32_bf16 v[94:97], v[204:207], v[170:173], v[94:97]
	v_mfma_f32_16x16x32_bf16 v[82:85], v[196:199], v[180:183], v[82:85]
	v_mfma_f32_16x16x32_bf16 v[78:81], v[204:207], v[180:183], v[78:81]
	v_mfma_f32_16x16x32_bf16 v[70:73], v[196:199], v[188:191], v[70:73]
	v_mfma_f32_16x16x32_bf16 v[66:69], v[204:207], v[188:191], v[66:69]
	s_setprio 0
	s_mov_b32 m0, s53
	v_lshl_add_u64 v[208:209], v[228:229], 0, s[86:87]
	s_barrier
	ds_read_b128 v[154:157], v160 offset:49152
	ds_read_b128 v[162:165], v160 offset:50176
	ds_read_b128 v[166:169], v160 offset:51200
	ds_read_b128 v[170:173], v160 offset:52224
	ds_read_b128 v[174:177], v160 offset:53248
	ds_read_b128 v[180:183], v160 offset:54272
	ds_read_b128 v[184:187], v160 offset:55296
	ds_read_b128 v[188:191], v160 offset:56320
	global_load_lds_dwordx4 v[208:209], off
	v_lshl_add_u64 v[208:209], v[230:231], 0, s[86:87]
	s_mov_b32 m0, s58
	s_nop 0
	global_load_lds_dwordx4 v[208:209], off
	s_waitcnt lgkmcnt(0)
	s_barrier
; #define PG8_STAGE(bufoff, gbase, voff) do { _Pragma("unroll") for (int _i = 0; _i < 2; ++_i) \
;         __builtin_amdgcn_global_load_lds((const unsigned*)((const char*)(gbase) + (voff)[_i]), (LAS unsigned*)(lds + (bufoff) + ldsw + _i * 8192), 16, 0, 0); } while (0)
; #define PG8_MMA(ai, bj, At, Bt) do { __builtin_amdgcn_s_setprio(1); _Pragma("unroll") for (int m = 0; m < 4; ++m) _Pragma("unroll") for (int n = 0; n < 2; ++n) _Pragma("unroll") for (int k = 0; k < 2; ++k) \
;         acc[ai][bj][m][n] = __builtin_amdgcn_mfma_f32_16x16x32_bf16(Bt[n][k], At[m][k], acc[ai][bj][m][n], 0, 0, 0); __builtin_amdgcn_s_setprio(0); } while (0)
; #define PG8_WAIT_V(n) asm volatile("s_waitcnt vmcnt(" #n ")" ::: "memory")
; #define PG8_WAIT_L(n) asm volatile("s_waitcnt lgkmcnt(" #n ")" ::: "memory")
; #define PG8_BAR __builtin_amdgcn_s_barrier()
; template <class Epi>
; __device__ __forceinline__ void gemm_phase(LAS unsigned char* lds, const Gemm g, const Epi& E) {
;     ...
;             PG8_BAR; PG8_WAIT_L(0); PG8_MMA(1, 0, At, B0); PG8_BAR; PG8_SCHED;
;             PG8_STAGE(PG8_SB(1, 1), b3 + hstepB, voffB);
;             PG8_WAIT_V(6); PG8_BAR; PG8_MMA(1, 1, At, B1); PG8_BAR;
;         }
;     __device__ __forceinline__ void operator()(const AccT& acc, const Unit& u, int wr, int wc, int fr, int fq) const {
;         asm volatile("" : "+v"(fr), "+v"(fq));
;         const int gpm = mapA.src(u.pm);
;         const int mb = gpm < 32 ? 32 : (gpm - 32) >> 3;
;         const int row0 = gpm * 256 + wr * 64 + fr, col0 = u.pn * 256 + wc * 32 + 4 * fq;
;         const float* gp = modl + ((size_t)mb * 6 + gi) * 1024;
;         f32x4 gv[2][2];
; #pragma unroll
;         for (int bj = 0; bj < 2; ++bj)
; #pragma unroll
;             for (int n = 0; n < 2; ++n) { gv[bj][n] = *(const f32x4*)(gp + col0 + bj * 128 + n * 16); if (scale) gv[bj][n] = gv[bj][n] * *(const f32x4*)(scale + col0 + bj * 128 + n * 16); }
;         const float* sbase = (gpm < 32 ? Xc : Xl) + (size_t)row0 * 1024 + col0;
; #pragma unroll
;         for (int ai = 0; ai < 2; ++ai) {
;             f32x4 xo[4][2][2];
; #pragma unroll
;             for (int m = 0; m < 4; ++m)
; #pragma unroll
;                 for (int bj = 0; bj < 2; ++bj)
; #pragma unroll
;                     for (int n = 0; n < 2; ++n) xo[m][bj][n] = *(const f32x4*)(sbase + (size_t)(ai * 128 + m * 16) * 1024 + bj * 128 + n * 16);
	s_setprio 1
	v_mfma_f32_16x16x32_bf16 v[62:65], v[130:133], v[154:157], v[62:65]
	v_mfma_f32_16x16x32_bf16 v[58:61], v[138:141], v[154:157], v[58:61]
	v_mfma_f32_16x16x32_bf16 v[54:57], v[130:133], v[166:169], v[54:57]
	v_mfma_f32_16x16x32_bf16 v[42:45], v[138:141], v[166:169], v[42:45]
	v_mfma_f32_16x16x32_bf16 v[38:41], v[130:133], v[174:177], v[38:41]
	v_mfma_f32_16x16x32_bf16 v[26:29], v[138:141], v[174:177], v[26:29]
	v_mfma_f32_16x16x32_bf16 v[22:25], v[130:133], v[184:187], v[22:25]
	v_mfma_f32_16x16x32_bf16 v[10:13], v[138:141], v[184:187], v[10:13]
	v_mfma_f32_16x16x32_bf16 v[62:65], v[134:137], v[162:165], v[62:65]
	v_mfma_f32_16x16x32_bf16 v[58:61], v[142:145], v[162:165], v[58:61]
	v_mfma_f32_16x16x32_bf16 v[54:57], v[134:137], v[170:173], v[54:57]
	v_mfma_f32_16x16x32_bf16 v[42:45], v[142:145], v[170:173], v[42:45]
	v_mfma_f32_16x16x32_bf16 v[38:41], v[134:137], v[180:183], v[38:41]
	v_mfma_f32_16x16x32_bf16 v[26:29], v[142:145], v[180:183], v[26:29]
	v_mfma_f32_16x16x32_bf16 v[22:25], v[134:137], v[188:191], v[22:25]
	v_mfma_f32_16x16x32_bf16 v[10:13], v[142:145], v[188:191], v[10:13]
	s_setprio 0
	s_barrier
	s_add_u32 s14, s14, 0x80080
	s_addc_u32 s15, s15, 0
	s_add_i32 s16, s16, s25
	v_lshl_add_u64 v[130:131], s[14:15], 0, v[148:149]
	s_mov_b32 m0, s16
	s_nop 0
	global_load_lds_dwordx4 v[130:131], off
	v_lshl_add_u64 v[130:131], s[14:15], 0, v[146:147]
	s_add_i32 m0, s16, 0x2000
	s_nop 0
	global_load_lds_dwordx4 v[130:131], off
	s_waitcnt vmcnt(6)
	s_barrier
	s_setprio 1
	v_mfma_f32_16x16x32_bf16 v[50:53], v[192:195], v[154:157], v[50:53]
	v_mfma_f32_16x16x32_bf16 v[46:49], v[200:203], v[154:157], v[46:49]
	v_mfma_f32_16x16x32_bf16 v[34:37], v[192:195], v[166:169], v[34:37]
	v_mfma_f32_16x16x32_bf16 v[30:33], v[200:203], v[166:169], v[30:33]
	v_mfma_f32_16x16x32_bf16 v[18:21], v[192:195], v[174:177], v[18:21]
	v_mfma_f32_16x16x32_bf16 v[14:17], v[200:203], v[174:177], v[14:17]
	v_mfma_f32_16x16x32_bf16 v[6:9], v[192:195], v[184:187], v[6:9]
	v_mfma_f32_16x16x32_bf16 v[2:5], v[200:203], v[184:187], v[2:5]
	v_mfma_f32_16x16x32_bf16 v[50:53], v[196:199], v[162:165], v[50:53]
	v_mfma_f32_16x16x32_bf16 v[46:49], v[204:207], v[162:165], v[46:49]
	v_mfma_f32_16x16x32_bf16 v[34:37], v[196:199], v[170:173], v[34:37]
	v_mfma_f32_16x16x32_bf16 v[30:33], v[204:207], v[170:173], v[30:33]
	v_mfma_f32_16x16x32_bf16 v[18:21], v[196:199], v[180:183], v[18:21]
	v_mfma_f32_16x16x32_bf16 v[14:17], v[204:207], v[180:183], v[14:17]
	v_mfma_f32_16x16x32_bf16 v[6:9], v[196:199], v[188:191], v[6:9]
	v_mfma_f32_16x16x32_bf16 v[2:5], v[204:207], v[188:191], v[2:5]
	s_setprio 0
	s_add_i32 s65, s65, 2
	s_add_u32 s12, s12, 0x100
	s_addc_u32 s13, s13, 0
	s_add_u32 s7, s7, 0x100
	s_addc_u32 s64, s64, 0
	s_cmp_gt_u32 s65, 29
	s_barrier
	s_cbranch_scc0 .LBB0_495
	v_readlane_b32 s7, v255, 27
	s_cmp_ge_i32 s61, s7
	s_cselect_b32 s7, s29, 0
	s_add_i32 s7, s61, s7
	s_cmp_lt_i32 s7, 32
	v_mov_b32_e32 v156, v158
	v_mov_b32_e32 v130, v1
	s_cselect_b64 s[12:13], -1, 0
	s_sub_i32 s14, s7, 32
	s_lshl_b32 s10, s10, 8
	s_ashr_i32 s14, s14, 3
	s_or_b32 s10, s10, s52
	v_lshl_add_u32 v130, v130, 2, s10
	s_mul_i32 s10, s14, 6
	s_and_b64 s[14:15], s[12:13], exec
	s_cselect_b32 s14, 0xc0, s10
	s_ashr_i32 s15, s14, 31
	s_lshl_b64 s[14:15], s[14:15], 12
	s_add_u32 s14, s88, s14
	s_addc_u32 s15, s89, s15
	s_lshl_b32 s7, s7, 8
	s_add_i32 s7, s7, s50
	v_ashrrev_i32_e32 v131, 31, v130
	v_add_u32_e32 v156, s7, v156
	s_and_b64 s[12:13], s[12:13], exec
	v_readlane_b32 s7, v255, 16
	v_readlane_b32 s10, v255, 18
	v_lshlrev_b64 v[154:155], 2, v[130:131]
	s_cselect_b32 s13, s7, s10
	v_readlane_b32 s7, v255, 17
	v_readlane_b32 s10, v255, 19
	v_ashrrev_i32_e32 v157, 31, v156
	v_lshl_add_u64 v[130:131], s[14:15], 0, v[154:155]
	s_mov_b64 s[14:15], 0x2000
	s_cselect_b32 s12, s7, s10
	v_lshlrev_b64 v[208:209], 12, v[156:157]
	v_lshl_add_u64 v[132:133], v[130:131], 0, s[14:15]
	v_add_co_u32_e32 v130, vcc, s71, v130
	v_lshl_add_u64 v[156:157], s[12:13], 0, v[208:209]
	s_nop 0
	v_addc_co_u32_e32 v131, vcc, 0, v131, vcc
	v_lshl_add_u64 v[156:157], v[156:157], 0, v[154:155]
	v_add_co_u32_e32 v192, vcc, s45, v156
	global_load_dwordx4 v[138:141], v[132:133], off offset:64
	global_load_dwordx4 v[134:137], v[132:133], off offset:512
	global_load_dwordx4 v[142:145], v[130:131], off
	s_nop 0
	global_load_dwordx4 v[130:133], v[132:133], off offset:576
	v_addc_co_u32_e32 v193, vcc, 0, v157, vcc
	v_add_co_u32_e32 v226, vcc, s19, v156
	global_load_dwordx4 v[162:165], v[156:157], off
	global_load_dwordx4 v[166:169], v[156:157], off offset:64
	global_load_dwordx4 v[170:173], v[156:157], off offset:512
	global_load_dwordx4 v[174:177], v[156:157], off offset:576
	v_addc_co_u32_e32 v227, vcc, 0, v157, vcc
	v_add_co_u32_e32 v242, vcc, s69, v156
	global_load_dwordx4 v[180:183], v[192:193], off
	global_load_dwordx4 v[184:187], v[192:193], off offset:64
	global_load_dwordx4 v[188:191], v[192:193], off offset:512
	s_nop 0
	global_load_dwordx4 v[192:195], v[192:193], off offset:576
	v_addc_co_u32_e32 v243, vcc, 0, v157, vcc
	global_load_dwordx4 v[196:199], v[226:227], off
	global_load_dwordx4 v[200:203], v[226:227], off offset:64
	global_load_dwordx4 v[204:207], v[226:227], off offset:512
	s_nop 0
	global_load_dwordx4 v[226:229], v[226:227], off offset:576
	s_nop 0
	global_load_dwordx4 v[230:233], v[242:243], off
	global_load_dwordx4 v[234:237], v[242:243], off offset:64
	global_load_dwordx4 v[238:241], v[242:243], off offset:512
	s_nop 0
	global_load_dwordx4 v[242:245], v[242:243], off offset:576
	v_readlane_b32 s12, v254, 0
	v_readlane_b32 s13, v254, 1
	s_waitcnt vmcnt(0)
;     __device__ __forceinline__ void operator()(const AccT& acc, const Unit& u, int wr, int wc, int fr, int fq) const {
;     ...
;         for (int ai = 0; ai < 2; ++ai) {
;             f32x4 xo[4][2][2];
; #pragma unroll
;             for (int m = 0; m < 4; ++m)
; #pragma unroll
;                 for (int bj = 0; bj < 2; ++bj)
; #pragma unroll
;                     for (int n = 0; n < 2; ++n) xo[m][bj][n] = *(const f32x4*)(sbase + (size_t)(ai * 128 + m * 16) * 1024 + bj * 128 + n * 16);
;             __builtin_amdgcn_sched_barrier(0);
; #pragma unroll
;             for (int m = 0; m < 4; ++m) { float* rowp = X + (size_t)(row0 + ai * 128 + m * 16) * 1024 + col0;
; #pragma unroll
;                 for (int bj = 0; bj < 2; ++bj)
; #pragma unroll
;                     for (int n = 0; n < 2; ++n) *(f32x4*)(rowp + bj * 128 + n * 16) = xo[m][bj][n] + gv[bj][n] * acc[ai][bj][m][n]; }
	v_pk_fma_f32 v[112:113], v[112:113], v[132:133], v[176:177]
	v_pk_fma_f32 v[110:111], v[110:111], v[130:131], v[174:175]
	v_lshl_add_u64 v[208:209], s[12:13], 0, v[208:209]
	v_lshl_add_u64 v[154:155], v[208:209], 0, v[154:155]
	v_pk_fma_f32 v[120:121], v[120:121], v[136:137], v[172:173]
	v_pk_fma_f32 v[118:119], v[118:119], v[134:135], v[170:171]
	global_store_dwordx4 v[154:155], v[110:113], off offset:576
	global_store_dwordx4 v[154:155], v[118:121], off offset:512
	v_pk_fma_f32 v[100:101], v[100:101], v[136:137], v[190:191]
	v_pk_fma_f32 v[110:111], v[114:115], v[142:143], v[180:181]
	v_add_co_u32_e32 v114, vcc, s45, v154
	v_lshl_add_u64 v[118:119], v[154:155], 0, s[84:85]
	s_nop 0
	v_addc_co_u32_e32 v115, vcc, 0, v155, vcc
	v_pk_fma_f32 v[98:99], v[98:99], v[134:135], v[188:189]
	global_store_dwordx4 v[118:119], v[98:101], off offset:512
	v_pk_fma_f32 v[84:85], v[84:85], v[136:137], v[206:207]
	v_pk_fma_f32 v[82:83], v[82:83], v[134:135], v[204:205]
	v_add_co_u32_e32 v100, vcc, s19, v154
	v_lshl_add_u64 v[98:99], v[154:155], 0, s[82:83]
	s_nop 0
	v_addc_co_u32_e32 v101, vcc, 0, v155, vcc
	v_pk_fma_f32 v[96:97], v[96:97], v[132:133], v[194:195]
	v_pk_fma_f32 v[94:95], v[94:95], v[130:131], v[192:193]
	global_store_dwordx4 v[98:99], v[82:85], off offset:512
	v_pk_fma_f32 v[80:81], v[80:81], v[132:133], v[228:229]
	v_pk_fma_f32 v[78:79], v[78:79], v[130:131], v[226:227]
	s_mov_b64 s[12:13], 0x30000
	v_add_co_u32_e32 v84, vcc, s69, v154
	v_pk_fma_f32 v[128:129], v[128:129], v[144:145], v[164:165]
	v_pk_fma_f32 v[126:127], v[126:127], v[142:143], v[162:163]
	v_pk_fma_f32 v[124:125], v[124:125], v[140:141], v[168:169]
	v_pk_fma_f32 v[122:123], v[122:123], v[138:139], v[166:167]
	v_pk_fma_f32 v[112:113], v[116:117], v[144:145], v[182:183]
	v_pk_fma_f32 v[108:109], v[108:109], v[140:141], v[186:187]
	v_pk_fma_f32 v[106:107], v[106:107], v[138:139], v[184:185]
	global_store_dwordx4 v[118:119], v[94:97], off offset:576
	v_pk_fma_f32 v[92:93], v[92:93], v[140:141], v[202:203]
	v_pk_fma_f32 v[90:91], v[90:91], v[138:139], v[200:201]
	v_pk_fma_f32 v[96:97], v[104:105], v[144:145], v[198:199]
	v_pk_fma_f32 v[94:95], v[102:103], v[142:143], v[196:197]
	global_store_dwordx4 v[98:99], v[78:81], off offset:576
	v_lshl_add_u64 v[82:83], v[154:155], 0, s[12:13]
	v_addc_co_u32_e32 v85, vcc, 0, v155, vcc
	v_pk_fma_f32 v[80:81], v[88:89], v[144:145], v[232:233]
	v_pk_fma_f32 v[78:79], v[86:87], v[142:143], v[230:231]
	v_pk_fma_f32 v[76:77], v[76:77], v[140:141], v[236:237]
	v_pk_fma_f32 v[74:75], v[74:75], v[138:139], v[234:235]
	v_pk_fma_f32 v[72:73], v[72:73], v[136:137], v[240:241]
	v_pk_fma_f32 v[70:71], v[70:71], v[134:135], v[238:239]
	v_pk_fma_f32 v[68:69], v[68:69], v[132:133], v[244:245]
	v_pk_fma_f32 v[66:67], v[66:67], v[130:131], v[242:243]
	global_store_dwordx4 v[154:155], v[126:129], off
	global_store_dwordx4 v[154:155], v[122:125], off offset:64
	global_store_dwordx4 v[114:115], v[110:113], off
	global_store_dwordx4 v[118:119], v[106:109], off offset:64
	global_store_dwordx4 v[100:101], v[94:97], off
	global_store_dwordx4 v[98:99], v[90:93], off offset:64
	global_store_dwordx4 v[84:85], v[78:81], off
	global_store_dwordx4 v[82:83], v[74:77], off offset:64
	global_store_dwordx4 v[82:83], v[70:73], off offset:512
	global_store_dwordx4 v[82:83], v[66:69], off offset:576
	s_mov_b32 s7, 0x80000
	v_add_co_u32_e32 v78, vcc, s7, v156
	s_mov_b32 s10, 0x90000
	s_nop 0
	v_addc_co_u32_e32 v79, vcc, 0, v157, vcc
	v_add_co_u32_e32 v94, vcc, s10, v156
	s_mov_b32 s12, 0xa0000
	s_nop 0
	v_addc_co_u32_e32 v95, vcc, 0, v157, vcc
	v_add_co_u32_e32 v110, vcc, s12, v156
	s_mov_b32 s13, 0xb0000
	s_nop 0
	v_addc_co_u32_e32 v111, vcc, 0, v157, vcc
	v_add_co_u32_e32 v126, vcc, s13, v156
	global_load_dwordx4 v[66:69], v[78:79], off
	global_load_dwordx4 v[70:73], v[78:79], off offset:64
	global_load_dwordx4 v[74:77], v[78:79], off offset:512
	s_nop 0
	global_load_dwordx4 v[78:81], v[78:79], off offset:576
	v_addc_co_u32_e32 v127, vcc, 0, v157, vcc
	global_load_dwordx4 v[82:85], v[94:95], off
	global_load_dwordx4 v[86:89], v[94:95], off offset:64
	global_load_dwordx4 v[90:93], v[94:95], off offset:512
	s_nop 0
	global_load_dwordx4 v[94:97], v[94:95], off offset:576
	s_nop 0
	global_load_dwordx4 v[98:101], v[110:111], off
	global_load_dwordx4 v[102:105], v[110:111], off offset:64
	global_load_dwordx4 v[106:109], v[110:111], off offset:512
	s_nop 0
	global_load_dwordx4 v[110:113], v[110:111], off offset:576
	s_nop 0
	global_load_dwordx4 v[114:117], v[126:127], off
	global_load_dwordx4 v[118:121], v[126:127], off offset:64
	global_load_dwordx4 v[122:125], v[126:127], off offset:512
	s_nop 0
	global_load_dwordx4 v[126:129], v[126:127], off offset:576
	s_mov_b64 s[14:15], 0x80000
	s_waitcnt vmcnt(0)
; #define PG8_WAIT_V(n) asm volatile("s_waitcnt vmcnt(" #n ")" ::: "memory")
; #define PG8_BAR __builtin_amdgcn_s_barrier()
; template <class Epi>
; __device__ __forceinline__ void gemm_phase(LAS unsigned char* lds, const Gemm g, const Epi& E) {
;     ...
;         if (!has_next) break;
; #pragma unroll
;         for (int a = 0; a < 2; ++a)
; #pragma unroll
;             for (int b = 0; b < 2; ++b)
; #pragma unroll
;                 for (int m = 0; m < 4; ++m)
; #pragma unroll
;                     for (int n = 0; n < 2; ++n) acc[a][b][m][n] = (f32x4){0.f, 0.f, 0.f, 0.f};
;         cur = nxt; cA = nA; cB = nB; ++ui;
;     }
;     PG8_WAIT_V(0);
;     if (wr == 0) PG8_BAR;
;     __device__ __forceinline__ void operator()(const AccT& acc, const Unit& u, int wr, int wc, int fr, int fq) const {
;     ...
;                     for (int n = 0; n < 2; ++n) xo[m][bj][n] = *(const f32x4*)(sbase + (size_t)(ai * 128 + m * 16) * 1024 + bj * 128 + n * 16);
;             __builtin_amdgcn_sched_barrier(0);
; #pragma unroll
;             for (int m = 0; m < 4; ++m) { float* rowp = X + (size_t)(row0 + ai * 128 + m * 16) * 1024 + col0;
; #pragma unroll
;                 for (int bj = 0; bj < 2; ++bj)
; #pragma unroll
;                     for (int n = 0; n < 2; ++n) *(f32x4*)(rowp + bj * 128 + n * 16) = xo[m][bj][n] + gv[bj][n] * acc[ai][bj][m][n]; }
	v_pk_fma_f32 v[62:63], v[62:63], v[142:143], v[66:67]
	v_add_co_u32_e32 v66, vcc, s7, v154
	v_lshl_add_u64 v[156:157], v[154:155], 0, s[14:15]
	s_nop 0
	v_addc_co_u32_e32 v67, vcc, 0, v155, vcc
	v_pk_fma_f32 v[52:53], v[52:53], v[136:137], v[76:77]
	v_pk_fma_f32 v[50:51], v[50:51], v[134:135], v[74:75]
	global_store_dwordx4 v[156:157], v[50:53], off offset:512
	s_mov_b64 s[14:15], 0x90000
	v_pk_fma_f32 v[36:37], v[36:37], v[136:137], v[92:93]
	v_add_co_u32_e32 v52, vcc, s10, v154
	v_lshl_add_u64 v[50:51], v[154:155], 0, s[14:15]
	s_nop 0
	v_addc_co_u32_e32 v53, vcc, 0, v155, vcc
	v_pk_fma_f32 v[34:35], v[34:35], v[134:135], v[90:91]
	global_store_dwordx4 v[50:51], v[34:37], off offset:512
	s_mov_b64 s[14:15], 0xa0000
	v_pk_fma_f32 v[20:21], v[20:21], v[136:137], v[108:109]
	v_add_co_u32_e32 v36, vcc, s12, v154
	v_lshl_add_u64 v[34:35], v[154:155], 0, s[14:15]
	s_nop 0
	v_addc_co_u32_e32 v37, vcc, 0, v155, vcc
	v_pk_fma_f32 v[18:19], v[18:19], v[134:135], v[106:107]
	v_pk_fma_f32 v[48:49], v[48:49], v[132:133], v[80:81]
	v_pk_fma_f32 v[46:47], v[46:47], v[130:131], v[78:79]
	v_pk_fma_f32 v[32:33], v[32:33], v[132:133], v[96:97]
	v_pk_fma_f32 v[30:31], v[30:31], v[130:131], v[94:95]
	global_store_dwordx4 v[34:35], v[18:21], off offset:512
	v_pk_fma_f32 v[16:17], v[16:17], v[132:133], v[112:113]
	v_pk_fma_f32 v[14:15], v[14:15], v[130:131], v[110:111]
	s_mov_b64 s[14:15], 0xb0000
	v_add_co_u32_e32 v20, vcc, s13, v154
	v_pk_fma_f32 v[64:65], v[64:65], v[144:145], v[68:69]
	v_pk_fma_f32 v[60:61], v[60:61], v[140:141], v[72:73]
	v_pk_fma_f32 v[58:59], v[58:59], v[138:139], v[70:71]
	global_store_dwordx4 v[156:157], v[46:49], off offset:576
	v_pk_fma_f32 v[44:45], v[44:45], v[140:141], v[88:89]
	v_pk_fma_f32 v[42:43], v[42:43], v[138:139], v[86:87]
	v_pk_fma_f32 v[48:49], v[56:57], v[144:145], v[84:85]
	v_pk_fma_f32 v[46:47], v[54:55], v[142:143], v[82:83]
	global_store_dwordx4 v[50:51], v[30:33], off offset:576
	v_pk_fma_f32 v[28:29], v[28:29], v[140:141], v[104:105]
	v_pk_fma_f32 v[26:27], v[26:27], v[138:139], v[102:103]
	v_pk_fma_f32 v[32:33], v[40:41], v[144:145], v[100:101]
	v_pk_fma_f32 v[30:31], v[38:39], v[142:143], v[98:99]
	global_store_dwordx4 v[34:35], v[14:17], off offset:576
	v_lshl_add_u64 v[18:19], v[154:155], 0, s[14:15]
	v_addc_co_u32_e32 v21, vcc, 0, v155, vcc
	v_pk_fma_f32 v[16:17], v[24:25], v[144:145], v[116:117]
	v_pk_fma_f32 v[14:15], v[22:23], v[142:143], v[114:115]
	v_pk_fma_f32 v[12:13], v[12:13], v[140:141], v[120:121]
	v_pk_fma_f32 v[10:11], v[10:11], v[138:139], v[118:119]
	v_pk_fma_f32 v[8:9], v[8:9], v[136:137], v[124:125]
	v_pk_fma_f32 v[6:7], v[6:7], v[134:135], v[122:123]
	v_pk_fma_f32 v[4:5], v[4:5], v[132:133], v[128:129]
	v_pk_fma_f32 v[2:3], v[2:3], v[130:131], v[126:127]
	global_store_dwordx4 v[66:67], v[62:65], off
	global_store_dwordx4 v[156:157], v[58:61], off offset:64
	global_store_dwordx4 v[52:53], v[46:49], off
	global_store_dwordx4 v[50:51], v[42:45], off offset:64
	global_store_dwordx4 v[36:37], v[30:33], off
	global_store_dwordx4 v[34:35], v[26:29], off offset:64
	global_store_dwordx4 v[20:21], v[14:17], off
	global_store_dwordx4 v[18:19], v[10:13], off offset:64
	global_store_dwordx4 v[18:19], v[6:9], off offset:512
	global_store_dwordx4 v[18:19], v[2:5], off offset:576
	s_and_b64 vcc, exec, s[2:3]
	s_mov_b32 s10, s6
	s_mov_b32 s61, s60
	s_mov_b64 s[14:15], s[4:5]
	s_mov_b64 s[12:13], s[8:9]
	s_cbranch_vccz .LBB0_490
	s_waitcnt vmcnt(0)
	s_cmpk_gt_u32 s1, 0xff
	s_cbranch_scc1 .LBB0_499
	s_barrier

; #define PG8_STAGE(bufoff, gbase, voff) do { _Pragma("unroll") for (int _i = 0; _i < 2; ++_i) \
;         __builtin_amdgcn_global_load_lds((const unsigned*)((const char*)(gbase) + (voff)[_i]), (LAS unsigned*)(lds + (bufoff) + ldsw + _i * 8192), 16, 0, 0); } while (0)
; #define PG8_LDA(dst, b, h) do { _Pragma("unroll") for (int m = 0; m < 4; ++m) _Pragma("unroll") for (int k = 0; k < 2; ++k) dst[m][k] = *(const LAS bf16x8*)(lds + PG8_SA(b, h) + aoff + m * 2048 + k * 1024); } while (0)
; #define PG8_LDB(dst, b, h) do { _Pragma("unroll") for (int n = 0; n < 2; ++n) _Pragma("unroll") for (int k = 0; k < 2; ++k) dst[n][k] = *(const LAS bf16x8*)(lds + PG8_SB(b, h) + boff + n * 2048 + k * 1024); } while (0)
; #define PG8_MMA(ai, bj, At, Bt) do { __builtin_amdgcn_s_setprio(1); _Pragma("unroll") for (int m = 0; m < 4; ++m) _Pragma("unroll") for (int n = 0; n < 2; ++n) _Pragma("unroll") for (int k = 0; k < 2; ++k) \
;         acc[ai][bj][m][n] = __builtin_amdgcn_mfma_f32_16x16x32_bf16(Bt[n][k], At[m][k], acc[ai][bj][m][n], 0, 0, 0); __builtin_amdgcn_s_setprio(0); } while (0)
; #define PG8_WAIT_L(n) asm volatile("s_waitcnt lgkmcnt(" #n ")" ::: "memory")
; #define PG8_BAR __builtin_amdgcn_s_barrier()
; #define PG8_SCHED __builtin_amdgcn_sched_barrier(0)
; template <class Epi>
; __device__ __forceinline__ void gemm_phase(LAS unsigned char* lds, const Gemm g, const Epi& E) {
;     ...
;             PG8_LDB(B0, 0, 0); PG8_SCHED; PG8_LDA(At, 0, 0); PG8_STAGE(PG8_SA(1, 1), a1 + hstepA, voffA);
;             PG8_WAIT_L(8); PG8_BAR; PG8_WAIT_L(0); PG8_MMA(0, 0, At, B0); PG8_BAR; PG8_SCHED;
;             PG8_LDB(B1, 0, 1); PG8_STAGE(PG8_SB(0, 0), b2, voffB);
;             PG8_BAR; PG8_WAIT_L(0); PG8_MMA(0, 1, At, B1); PG8_BAR;
;             PG8_LDA(At, 0, 1); PG8_STAGE(PG8_SA(0, 0), a2, voffA);
;             PG8_BAR; PG8_WAIT_L(0); PG8_MMA(1, 0, At, B0); PG8_BAR; PG8_SCHED;
.LBB0_525:
	s_add_u32 s14, s12, 0xfffc0080
	s_addc_u32 s15, s13, -1
	s_add_i32 s26, 0, 0x10000
	v_add_u32_e32 v149, s26, v147
	ds_read_b128 v[142:145], v149
	ds_read_b128 v[150:153], v149 offset:1024
	ds_read_b128 v[154:157], v149 offset:2048
	ds_read_b128 v[158:161], v149 offset:3072
	s_cmp_eq_u32 s66, 12
	s_cselect_b32 s17, s9, s15
	s_cselect_b32 s16, s8, s14
	s_cselect_b32 s15, s5, s65
	s_cselect_b32 s14, s4, s7
	v_lshl_add_u64 v[196:197], s[12:13], 0, v[138:139]
	s_add_i32 m0, s11, 0xc000
	ds_read_b128 v[162:165], v148
	ds_read_b128 v[166:169], v148 offset:1024
	ds_read_b128 v[170:173], v148 offset:2048
	ds_read_b128 v[174:177], v148 offset:3072
	ds_read_b128 v[180:183], v148 offset:4096
	ds_read_b128 v[184:187], v148 offset:5120
	ds_read_b128 v[188:191], v148 offset:6144
	ds_read_b128 v[192:195], v148 offset:7168
	global_load_lds_dwordx4 v[196:197], off
	v_lshl_add_u64 v[196:197], s[12:13], 0, v[140:141]
	s_add_i32 m0, s11, 0xe000
	s_nop 0
	global_load_lds_dwordx4 v[196:197], off
	s_waitcnt lgkmcnt(0)
	s_barrier
	s_setprio 1
	v_mfma_f32_16x16x32_bf16 v[126:129], v[142:145], v[162:165], v[126:129]
	v_mfma_f32_16x16x32_bf16 v[118:121], v[154:157], v[162:165], v[118:121]
	v_mfma_f32_16x16x32_bf16 v[110:113], v[142:145], v[170:173], v[110:113]
	v_mfma_f32_16x16x32_bf16 v[102:105], v[154:157], v[170:173], v[102:105]
	v_mfma_f32_16x16x32_bf16 v[94:97], v[142:145], v[180:183], v[94:97]
	v_mfma_f32_16x16x32_bf16 v[86:89], v[154:157], v[180:183], v[86:89]
	v_mfma_f32_16x16x32_bf16 v[78:81], v[142:145], v[188:191], v[78:81]
	v_mfma_f32_16x16x32_bf16 v[70:73], v[154:157], v[188:191], v[70:73]
	v_mfma_f32_16x16x32_bf16 v[126:129], v[150:153], v[166:169], v[126:129]
	v_mfma_f32_16x16x32_bf16 v[118:121], v[158:161], v[166:169], v[118:121]
	v_mfma_f32_16x16x32_bf16 v[110:113], v[150:153], v[174:177], v[110:113]
	v_mfma_f32_16x16x32_bf16 v[102:105], v[158:161], v[174:177], v[102:105]
	v_mfma_f32_16x16x32_bf16 v[94:97], v[150:153], v[184:187], v[94:97]
	v_mfma_f32_16x16x32_bf16 v[86:89], v[158:161], v[184:187], v[86:89]
	v_mfma_f32_16x16x32_bf16 v[78:81], v[150:153], v[192:195], v[78:81]
	v_mfma_f32_16x16x32_bf16 v[70:73], v[158:161], v[192:195], v[70:73]
	s_setprio 0
	s_barrier
	s_add_i32 s27, 0, 0x14000
	s_add_i32 s26, s26, s25
	v_add_u32_e32 v149, s27, v147
	v_lshl_add_u64 v[208:209], s[14:15], 0, v[134:135]
	s_mov_b32 m0, s26
	ds_read_b128 v[196:199], v149
	ds_read_b128 v[200:203], v149 offset:1024
	ds_read_b128 v[204:207], v149 offset:2048
	ds_read_b128 v[226:229], v149 offset:3072
	global_load_lds_dwordx4 v[208:209], off
	v_lshl_add_u64 v[230:231], s[14:15], 0, v[130:131]
	s_add_i32 m0, s26, 0x2000
	s_nop 0
	global_load_lds_dwordx4 v[230:231], off
	s_waitcnt lgkmcnt(0)
	s_barrier
	s_setprio 1
	v_mfma_f32_16x16x32_bf16 v[122:125], v[196:199], v[162:165], v[122:125]
	v_mfma_f32_16x16x32_bf16 v[114:117], v[204:207], v[162:165], v[114:117]
	v_mfma_f32_16x16x32_bf16 v[106:109], v[196:199], v[170:173], v[106:109]
	v_mfma_f32_16x16x32_bf16 v[98:101], v[204:207], v[170:173], v[98:101]
	v_mfma_f32_16x16x32_bf16 v[90:93], v[196:199], v[180:183], v[90:93]
	v_mfma_f32_16x16x32_bf16 v[82:85], v[204:207], v[180:183], v[82:85]
	v_mfma_f32_16x16x32_bf16 v[74:77], v[196:199], v[188:191], v[74:77]
	v_mfma_f32_16x16x32_bf16 v[66:69], v[204:207], v[188:191], v[66:69]
	v_mfma_f32_16x16x32_bf16 v[122:125], v[200:203], v[166:169], v[122:125]
	v_mfma_f32_16x16x32_bf16 v[114:117], v[226:229], v[166:169], v[114:117]
	v_mfma_f32_16x16x32_bf16 v[106:109], v[200:203], v[174:177], v[106:109]
	v_mfma_f32_16x16x32_bf16 v[98:101], v[226:229], v[174:177], v[98:101]
	v_mfma_f32_16x16x32_bf16 v[90:93], v[200:203], v[184:187], v[90:93]
	v_mfma_f32_16x16x32_bf16 v[82:85], v[226:229], v[184:187], v[82:85]
	v_mfma_f32_16x16x32_bf16 v[74:77], v[200:203], v[192:195], v[74:77]
	v_mfma_f32_16x16x32_bf16 v[66:69], v[226:229], v[192:195], v[66:69]
	s_setprio 0
	s_mov_b32 m0, s11
	v_lshl_add_u64 v[232:233], s[16:17], 0, v[136:137]
	s_barrier
	ds_read_b128 v[162:165], v148 offset:16384
	ds_read_b128 v[166:169], v148 offset:17408
	ds_read_b128 v[170:173], v148 offset:18432
	ds_read_b128 v[174:177], v148 offset:19456
	ds_read_b128 v[180:183], v148 offset:20480
	ds_read_b128 v[184:187], v148 offset:21504
	ds_read_b128 v[188:191], v148 offset:22528
	ds_read_b128 v[192:195], v148 offset:23552
	global_load_lds_dwordx4 v[232:233], off
	v_lshl_add_u64 v[234:235], s[16:17], 0, v[132:133]
	s_mov_b32 m0, s36
	s_nop 0
	global_load_lds_dwordx4 v[234:235], off
	s_waitcnt lgkmcnt(0)
	s_barrier
	s_setprio 1
	v_mfma_f32_16x16x32_bf16 v[62:65], v[142:145], v[162:165], v[62:65]
	v_mfma_f32_16x16x32_bf16 v[54:57], v[154:157], v[162:165], v[54:57]
	v_mfma_f32_16x16x32_bf16 v[46:49], v[142:145], v[170:173], v[46:49]
	v_mfma_f32_16x16x32_bf16 v[38:41], v[154:157], v[170:173], v[38:41]
	v_mfma_f32_16x16x32_bf16 v[30:33], v[142:145], v[180:183], v[30:33]
	v_mfma_f32_16x16x32_bf16 v[22:25], v[154:157], v[180:183], v[22:25]
	v_mfma_f32_16x16x32_bf16 v[14:17], v[142:145], v[188:191], v[14:17]
	v_mfma_f32_16x16x32_bf16 v[6:9], v[154:157], v[188:191], v[6:9]
	v_mfma_f32_16x16x32_bf16 v[62:65], v[150:153], v[166:169], v[62:65]
	v_mfma_f32_16x16x32_bf16 v[54:57], v[158:161], v[166:169], v[54:57]
	v_mfma_f32_16x16x32_bf16 v[46:49], v[150:153], v[174:177], v[46:49]
	v_mfma_f32_16x16x32_bf16 v[38:41], v[158:161], v[174:177], v[38:41]
	v_mfma_f32_16x16x32_bf16 v[30:33], v[150:153], v[184:187], v[30:33]
	v_mfma_f32_16x16x32_bf16 v[22:25], v[158:161], v[184:187], v[22:25]
	v_mfma_f32_16x16x32_bf16 v[14:17], v[150:153], v[192:195], v[14:17]
	v_mfma_f32_16x16x32_bf16 v[6:9], v[158:161], v[192:195], v[6:9]
	s_setprio 0
	s_barrier
; #define PG8_STAGE(bufoff, gbase, voff) do { _Pragma("unroll") for (int _i = 0; _i < 2; ++_i) \
;         __builtin_amdgcn_global_load_lds((const unsigned*)((const char*)(gbase) + (voff)[_i]), (LAS unsigned*)(lds + (bufoff) + ldsw + _i * 8192), 16, 0, 0); } while (0)
; #define PG8_LDA(dst, b, h) do { _Pragma("unroll") for (int m = 0; m < 4; ++m) _Pragma("unroll") for (int k = 0; k < 2; ++k) dst[m][k] = *(const LAS bf16x8*)(lds + PG8_SA(b, h) + aoff + m * 2048 + k * 1024); } while (0)
; #define PG8_LDB(dst, b, h) do { _Pragma("unroll") for (int n = 0; n < 2; ++n) _Pragma("unroll") for (int k = 0; k < 2; ++k) dst[n][k] = *(const LAS bf16x8*)(lds + PG8_SB(b, h) + boff + n * 2048 + k * 1024); } while (0)
; #define PG8_MMA(ai, bj, At, Bt) do { __builtin_amdgcn_s_setprio(1); _Pragma("unroll") for (int m = 0; m < 4; ++m) _Pragma("unroll") for (int n = 0; n < 2; ++n) _Pragma("unroll") for (int k = 0; k < 2; ++k) \
;         acc[ai][bj][m][n] = __builtin_amdgcn_mfma_f32_16x16x32_bf16(Bt[n][k], At[m][k], acc[ai][bj][m][n], 0, 0, 0); __builtin_amdgcn_s_setprio(0); } while (0)
; #define PG8_WAIT_V(n) asm volatile("s_waitcnt vmcnt(" #n ")" ::: "memory")
; #define PG8_WAIT_L(n) asm volatile("s_waitcnt lgkmcnt(" #n ")" ::: "memory")
; #define PG8_BAR __builtin_amdgcn_s_barrier()
; #define PG8_SCHED __builtin_amdgcn_sched_barrier(0)
; template <class Epi>
; __device__ __forceinline__ void gemm_phase(LAS unsigned char* lds, const Gemm g, const Epi& E) {
;     ...
;             PG8_STAGE(PG8_SB(0, 1), b2 + hstepB, voffB);
;             PG8_WAIT_V(6); PG8_BAR; PG8_MMA(1, 1, At, B1); PG8_BAR;
;             PG8_LDB(B0, 1, 0); PG8_SCHED; PG8_LDA(At, 1, 0); PG8_STAGE(PG8_SA(0, 1), a2 + hstepA, voffA);
;             PG8_WAIT_L(8); PG8_BAR; PG8_WAIT_L(0); PG8_MMA(0, 0, At, B0); PG8_BAR; PG8_SCHED;
;             PG8_LDB(B1, 1, 1); PG8_STAGE(PG8_SB(1, 0), b3, voffB);
;             PG8_BAR; PG8_WAIT_L(0); PG8_MMA(0, 1, At, B1); PG8_BAR;
;             PG8_LDA(At, 1, 1); PG8_STAGE(PG8_SA(1, 0), a3, voffA);
	s_add_u32 s68, s14, 0x40000
	s_addc_u32 s69, s15, 0
	s_add_i32 s26, s27, s25
	v_lshl_add_u64 v[142:143], s[68:69], 0, v[134:135]
	s_mov_b32 m0, s26
	s_nop 0
	global_load_lds_dwordx4 v[142:143], off
	v_lshl_add_u64 v[142:143], s[68:69], 0, v[130:131]
	s_add_i32 m0, s26, 0x2000
	s_nop 0
	global_load_lds_dwordx4 v[142:143], off
	s_waitcnt vmcnt(6)
	s_barrier
	s_setprio 1
	v_mfma_f32_16x16x32_bf16 v[58:61], v[196:199], v[162:165], v[58:61]
	v_mfma_f32_16x16x32_bf16 v[50:53], v[204:207], v[162:165], v[50:53]
	v_mfma_f32_16x16x32_bf16 v[42:45], v[196:199], v[170:173], v[42:45]
	v_mfma_f32_16x16x32_bf16 v[34:37], v[204:207], v[170:173], v[34:37]
	v_mfma_f32_16x16x32_bf16 v[26:29], v[196:199], v[180:183], v[26:29]
	v_mfma_f32_16x16x32_bf16 v[18:21], v[204:207], v[180:183], v[18:21]
	v_mfma_f32_16x16x32_bf16 v[10:13], v[196:199], v[188:191], v[10:13]
	v_mfma_f32_16x16x32_bf16 v[2:5], v[204:207], v[188:191], v[2:5]
	v_mfma_f32_16x16x32_bf16 v[58:61], v[200:203], v[166:169], v[58:61]
	v_mfma_f32_16x16x32_bf16 v[50:53], v[226:229], v[166:169], v[50:53]
	v_mfma_f32_16x16x32_bf16 v[42:45], v[200:203], v[174:177], v[42:45]
	v_mfma_f32_16x16x32_bf16 v[34:37], v[226:229], v[174:177], v[34:37]
	v_mfma_f32_16x16x32_bf16 v[26:29], v[200:203], v[184:187], v[26:29]
	v_mfma_f32_16x16x32_bf16 v[18:21], v[226:229], v[184:187], v[18:21]
	v_mfma_f32_16x16x32_bf16 v[10:13], v[200:203], v[192:195], v[10:13]
	v_mfma_f32_16x16x32_bf16 v[2:5], v[226:229], v[192:195], v[2:5]
	s_setprio 0
	s_add_i32 s26, 0, 0x18000
	v_add_u32_e32 v149, s26, v147
	s_barrier
	ds_read_b128 v[142:145], v149
	ds_read_b128 v[150:153], v149 offset:1024
	ds_read_b128 v[154:157], v149 offset:2048
	ds_read_b128 v[158:161], v149 offset:3072
	s_add_u32 s16, s16, 0x40000
	s_addc_u32 s17, s17, 0
	s_mov_b32 m0, s44
	v_lshl_add_u64 v[196:197], s[16:17], 0, v[136:137]
	ds_read_b128 v[162:165], v148 offset:32768
	ds_read_b128 v[166:169], v148 offset:33792
	ds_read_b128 v[170:173], v148 offset:34816
	ds_read_b128 v[174:177], v148 offset:35840
	ds_read_b128 v[180:183], v148 offset:36864
	ds_read_b128 v[184:187], v148 offset:37888
	ds_read_b128 v[188:191], v148 offset:38912
	ds_read_b128 v[192:195], v148 offset:39936
	global_load_lds_dwordx4 v[196:197], off
	v_lshl_add_u64 v[196:197], s[16:17], 0, v[132:133]
	s_mov_b32 m0, s50
	s_nop 0
	global_load_lds_dwordx4 v[196:197], off
	s_waitcnt lgkmcnt(0)
	s_barrier
	s_setprio 1
	v_mfma_f32_16x16x32_bf16 v[126:129], v[142:145], v[162:165], v[126:129]
	v_mfma_f32_16x16x32_bf16 v[118:121], v[154:157], v[162:165], v[118:121]
	v_mfma_f32_16x16x32_bf16 v[110:113], v[142:145], v[170:173], v[110:113]
	v_mfma_f32_16x16x32_bf16 v[102:105], v[154:157], v[170:173], v[102:105]
	v_mfma_f32_16x16x32_bf16 v[94:97], v[142:145], v[180:183], v[94:97]
	v_mfma_f32_16x16x32_bf16 v[86:89], v[154:157], v[180:183], v[86:89]
	v_mfma_f32_16x16x32_bf16 v[78:81], v[142:145], v[188:191], v[78:81]
	v_mfma_f32_16x16x32_bf16 v[70:73], v[154:157], v[188:191], v[70:73]
	v_mfma_f32_16x16x32_bf16 v[126:129], v[150:153], v[166:169], v[126:129]
	v_mfma_f32_16x16x32_bf16 v[118:121], v[158:161], v[166:169], v[118:121]
	v_mfma_f32_16x16x32_bf16 v[110:113], v[150:153], v[174:177], v[110:113]
	v_mfma_f32_16x16x32_bf16 v[102:105], v[158:161], v[174:177], v[102:105]
	v_mfma_f32_16x16x32_bf16 v[94:97], v[150:153], v[184:187], v[94:97]
	v_mfma_f32_16x16x32_bf16 v[86:89], v[158:161], v[184:187], v[86:89]
	v_mfma_f32_16x16x32_bf16 v[78:81], v[150:153], v[192:195], v[78:81]
	v_mfma_f32_16x16x32_bf16 v[70:73], v[158:161], v[192:195], v[70:73]
	s_setprio 0
	s_barrier
	s_add_i32 s16, 0, 0x1c000
	s_add_i32 s17, s26, s25
	v_add_u32_e32 v149, s16, v147
	v_lshl_add_u64 v[208:209], v[208:209], 0, s[86:87]
	s_mov_b32 m0, s17
	ds_read_b128 v[196:199], v149
	ds_read_b128 v[200:203], v149 offset:1024
	ds_read_b128 v[204:207], v149 offset:2048
	ds_read_b128 v[226:229], v149 offset:3072
	global_load_lds_dwordx4 v[208:209], off
	v_lshl_add_u64 v[208:209], v[230:231], 0, s[86:87]
	s_add_i32 m0, s17, 0x2000
	s_nop 0
	global_load_lds_dwordx4 v[208:209], off
	s_waitcnt lgkmcnt(0)
	s_barrier
	s_setprio 1
	v_mfma_f32_16x16x32_bf16 v[122:125], v[196:199], v[162:165], v[122:125]
	v_mfma_f32_16x16x32_bf16 v[114:117], v[204:207], v[162:165], v[114:117]
	v_mfma_f32_16x16x32_bf16 v[106:109], v[196:199], v[170:173], v[106:109]
	v_mfma_f32_16x16x32_bf16 v[98:101], v[204:207], v[170:173], v[98:101]
	v_mfma_f32_16x16x32_bf16 v[90:93], v[196:199], v[180:183], v[90:93]
	v_mfma_f32_16x16x32_bf16 v[82:85], v[204:207], v[180:183], v[82:85]
	v_mfma_f32_16x16x32_bf16 v[74:77], v[196:199], v[188:191], v[74:77]
	v_mfma_f32_16x16x32_bf16 v[66:69], v[204:207], v[188:191], v[66:69]
	v_mfma_f32_16x16x32_bf16 v[122:125], v[200:203], v[166:169], v[122:125]
	v_mfma_f32_16x16x32_bf16 v[114:117], v[226:229], v[166:169], v[114:117]
	v_mfma_f32_16x16x32_bf16 v[106:109], v[200:203], v[174:177], v[106:109]
	v_mfma_f32_16x16x32_bf16 v[98:101], v[226:229], v[174:177], v[98:101]
	v_mfma_f32_16x16x32_bf16 v[90:93], v[200:203], v[184:187], v[90:93]
	v_mfma_f32_16x16x32_bf16 v[82:85], v[226:229], v[184:187], v[82:85]
	v_mfma_f32_16x16x32_bf16 v[74:77], v[200:203], v[192:195], v[74:77]
	v_mfma_f32_16x16x32_bf16 v[66:69], v[226:229], v[192:195], v[66:69]
	s_setprio 0
	s_mov_b32 m0, s58
	v_lshl_add_u64 v[208:209], v[232:233], 0, s[86:87]
	s_barrier
	ds_read_b128 v[162:165], v148 offset:49152
	ds_read_b128 v[166:169], v148 offset:50176
	ds_read_b128 v[170:173], v148 offset:51200
	ds_read_b128 v[174:177], v148 offset:52224
	ds_read_b128 v[180:183], v148 offset:53248
	ds_read_b128 v[184:187], v148 offset:54272
	ds_read_b128 v[188:191], v148 offset:55296
	ds_read_b128 v[192:195], v148 offset:56320
	global_load_lds_dwordx4 v[208:209], off
	v_lshl_add_u64 v[208:209], v[234:235], 0, s[86:87]
	s_mov_b32 m0, s59
	s_nop 0
	global_load_lds_dwordx4 v[208:209], off
	s_waitcnt lgkmcnt(0)
	s_barrier
; __device__ __forceinline__ unsigned cvt_pk_bf16(float lo, float hi) { unsigned r; asm("v_cvt_pk_bf16_f32 %0, %1, %2" : "=v"(r) : "v"(lo), "v"(hi)); return r; }
; #define PG8_STAGE(bufoff, gbase, voff) do { _Pragma("unroll") for (int _i = 0; _i < 2; ++_i) \
;         __builtin_amdgcn_global_load_lds((const unsigned*)((const char*)(gbase) + (voff)[_i]), (LAS unsigned*)(lds + (bufoff) + ldsw + _i * 8192), 16, 0, 0); } while (0)
; #define PG8_MMA(ai, bj, At, Bt) do { __builtin_amdgcn_s_setprio(1); _Pragma("unroll") for (int m = 0; m < 4; ++m) _Pragma("unroll") for (int n = 0; n < 2; ++n) _Pragma("unroll") for (int k = 0; k < 2; ++k) \
;         acc[ai][bj][m][n] = __builtin_amdgcn_mfma_f32_16x16x32_bf16(Bt[n][k], At[m][k], acc[ai][bj][m][n], 0, 0, 0); __builtin_amdgcn_s_setprio(0); } while (0)
; #define PG8_WAIT_V(n) asm volatile("s_waitcnt vmcnt(" #n ")" ::: "memory")
; #define PG8_WAIT_L(n) asm volatile("s_waitcnt lgkmcnt(" #n ")" ::: "memory")
; #define PG8_BAR __builtin_amdgcn_s_barrier()
; #define PG8_SCHED __builtin_amdgcn_sched_barrier(0)
; template <class Epi>
; __device__ __forceinline__ void gemm_phase(LAS unsigned char* lds, const Gemm g, const Epi& E) {
;     ...
;             PG8_BAR; PG8_WAIT_L(0); PG8_MMA(1, 0, At, B0); PG8_BAR; PG8_SCHED;
;             PG8_STAGE(PG8_SB(1, 1), b3 + hstepB, voffB);
;             PG8_WAIT_V(6); PG8_BAR; PG8_MMA(1, 1, At, B1); PG8_BAR;
;     __device__ __forceinline__ void operator()(const AccT& acc, const Unit& u, int wr, int wc, int fr, int fq) const {
;         asm volatile("" : "+v"(fr), "+v"(fq));
;         const int gpm = mapA.src(u.pm);
;         const int row0 = gpm * 256 + wr * 64 + fr, col0 = u.pn * 128 + wc * 32 + 8 * fq;
; #pragma unroll
;         for (int ai = 0; ai < 2; ++ai)
; #pragma unroll
;             for (int m = 0; m < 4; ++m) { bf16_t* rowp = U + (size_t)(row0 + ai * 128 + m * 16) * HID + col0;
;                 const f32x4 s0 = silu4(acc[ai][0][m][0]) * acc[ai][1][m][0], s1 = silu4(acc[ai][0][m][1]) * acc[ai][1][m][1];
;                 u32x4 w; w.x = cvt_pk_bf16(s0[0], s0[1]); w.y = cvt_pk_bf16(s0[2], s0[3]); w.z = cvt_pk_bf16(s1[0], s1[1]); w.w = cvt_pk_bf16(s1[2], s1[3]);
;                 *(u32x4*)rowp = w; }
	s_setprio 1
	v_mfma_f32_16x16x32_bf16 v[62:65], v[142:145], v[162:165], v[62:65]
	v_mfma_f32_16x16x32_bf16 v[54:57], v[154:157], v[162:165], v[54:57]
	v_mfma_f32_16x16x32_bf16 v[46:49], v[142:145], v[170:173], v[46:49]
	v_mfma_f32_16x16x32_bf16 v[38:41], v[154:157], v[170:173], v[38:41]
	v_mfma_f32_16x16x32_bf16 v[30:33], v[142:145], v[180:183], v[30:33]
	v_mfma_f32_16x16x32_bf16 v[22:25], v[154:157], v[180:183], v[22:25]
	v_mfma_f32_16x16x32_bf16 v[14:17], v[142:145], v[188:191], v[14:17]
	v_mfma_f32_16x16x32_bf16 v[6:9], v[154:157], v[188:191], v[6:9]
	v_mfma_f32_16x16x32_bf16 v[62:65], v[150:153], v[166:169], v[62:65]
	v_mfma_f32_16x16x32_bf16 v[54:57], v[158:161], v[166:169], v[54:57]
	v_mfma_f32_16x16x32_bf16 v[46:49], v[150:153], v[174:177], v[46:49]
	v_mfma_f32_16x16x32_bf16 v[38:41], v[158:161], v[174:177], v[38:41]
	v_mfma_f32_16x16x32_bf16 v[30:33], v[150:153], v[184:187], v[30:33]
	v_mfma_f32_16x16x32_bf16 v[22:25], v[158:161], v[184:187], v[22:25]
	v_mfma_f32_16x16x32_bf16 v[14:17], v[150:153], v[192:195], v[14:17]
	v_mfma_f32_16x16x32_bf16 v[6:9], v[158:161], v[192:195], v[6:9]
	s_setprio 0
	s_barrier
	s_add_u32 s14, s14, 0x40080
	s_addc_u32 s15, s15, 0
	s_add_i32 s16, s16, s25
	v_lshl_add_u64 v[142:143], s[14:15], 0, v[134:135]
	s_mov_b32 m0, s16
	s_nop 0
	global_load_lds_dwordx4 v[142:143], off
	v_lshl_add_u64 v[142:143], s[14:15], 0, v[130:131]
	s_add_i32 m0, s16, 0x2000
	s_nop 0
	global_load_lds_dwordx4 v[142:143], off
	s_waitcnt vmcnt(6)
	s_barrier
	s_setprio 1
	v_mfma_f32_16x16x32_bf16 v[58:61], v[196:199], v[162:165], v[58:61]
	v_mfma_f32_16x16x32_bf16 v[50:53], v[204:207], v[162:165], v[50:53]
	v_mfma_f32_16x16x32_bf16 v[42:45], v[196:199], v[170:173], v[42:45]
	v_mfma_f32_16x16x32_bf16 v[34:37], v[204:207], v[170:173], v[34:37]
	v_mfma_f32_16x16x32_bf16 v[26:29], v[196:199], v[180:183], v[26:29]
	v_mfma_f32_16x16x32_bf16 v[18:21], v[204:207], v[180:183], v[18:21]
	v_mfma_f32_16x16x32_bf16 v[10:13], v[196:199], v[188:191], v[10:13]
	v_mfma_f32_16x16x32_bf16 v[2:5], v[204:207], v[188:191], v[2:5]
	v_mfma_f32_16x16x32_bf16 v[58:61], v[200:203], v[166:169], v[58:61]
	v_mfma_f32_16x16x32_bf16 v[50:53], v[226:229], v[166:169], v[50:53]
	v_mfma_f32_16x16x32_bf16 v[42:45], v[200:203], v[174:177], v[42:45]
	v_mfma_f32_16x16x32_bf16 v[34:37], v[226:229], v[174:177], v[34:37]
	v_mfma_f32_16x16x32_bf16 v[26:29], v[200:203], v[184:187], v[26:29]
	v_mfma_f32_16x16x32_bf16 v[18:21], v[226:229], v[184:187], v[18:21]
	v_mfma_f32_16x16x32_bf16 v[10:13], v[200:203], v[192:195], v[10:13]
	v_mfma_f32_16x16x32_bf16 v[2:5], v[226:229], v[192:195], v[2:5]
	s_setprio 0
	s_add_i32 s66, s66, 2
	s_add_u32 s12, s12, 0x100
	s_addc_u32 s13, s13, 0
	s_add_u32 s7, s7, 0x100
	s_addc_u32 s65, s65, 0
	s_cmp_gt_u32 s66, 13
	s_barrier
	s_cbranch_scc0 .LBB0_525
	v_mul_f32_e32 v152, 0xbfb8aa3b, v126
	v_mul_f32_e32 v153, 0xbfb8aa3b, v127
	v_mul_f32_e32 v154, 0xbfb8aa3b, v128
	v_mul_f32_e32 v155, 0xbfb8aa3b, v129
	v_exp_f32_e32 v152, v152
	v_exp_f32_e32 v153, v153
	v_exp_f32_e32 v154, v154
	v_exp_f32_e32 v155, v155
	v_add_f32_e32 v152, 1.0, v152
	v_add_f32_e32 v153, 1.0, v153
	v_add_f32_e32 v154, 1.0, v154
	v_add_f32_e32 v155, 1.0, v155
	v_rcp_f32_e32 v152, v152
	v_rcp_f32_e32 v153, v153
	v_rcp_f32_e32 v154, v154
	v_rcp_f32_e32 v155, v155
	v_readlane_b32 s7, v255, 27
	v_pk_mul_f32 v[126:127], v[126:127], v[152:153]
	s_cmp_ge_i32 s64, s7
	v_pk_mul_f32 v[128:129], v[128:129], v[154:155]
	v_pk_mul_f32 v[122:123], v[126:127], v[122:123]
	v_pk_mul_f32 v[124:125], v[128:129], v[124:125]
	v_mul_f32_e32 v126, 0xbfb8aa3b, v118
	v_mul_f32_e32 v127, 0xbfb8aa3b, v119
	v_mul_f32_e32 v128, 0xbfb8aa3b, v120
	v_mul_f32_e32 v129, 0xbfb8aa3b, v121
	v_exp_f32_e32 v126, v126
	v_exp_f32_e32 v127, v127
	v_exp_f32_e32 v128, v128
	v_exp_f32_e32 v129, v129
	v_add_f32_e32 v126, 1.0, v126
	v_add_f32_e32 v127, 1.0, v127
	v_add_f32_e32 v128, 1.0, v128
	v_add_f32_e32 v129, 1.0, v129
	s_cselect_b32 s7, s31, 0
	v_rcp_f32_e32 v126, v126
	v_rcp_f32_e32 v127, v127
	v_rcp_f32_e32 v128, v128
	v_rcp_f32_e32 v129, v129
	s_add_i32 s7, s64, s7
	s_lshl_b32 s10, s10, 7
	v_mov_b32_e32 v142, v146
	v_mov_b32_e32 v143, v1
	s_lshl_b32 s7, s7, 8
	s_or_b32 s10, s10, s53
	s_add_i32 s7, s7, s52
	v_lshl_add_u32 v144, v143, 3, s10
	v_add_u32_e32 v149, s7, v142
	v_ashrrev_i32_e32 v145, 31, v144
	v_mov_b64_e32 v[142:143], s[34:35]
	s_movk_i32 s7, 0x1600
	v_pk_mul_f32 v[118:119], v[118:119], v[126:127]
	v_pk_mul_f32 v[120:121], v[120:121], v[128:129]
	v_mad_i64_i32 v[150:151], s[12:13], v149, s7, v[142:143]
	v_lshlrev_b64 v[144:145], 1, v[144:145]
	v_pk_mul_f32 v[120:121], v[120:121], v[116:117]
	v_pk_mul_f32 v[116:117], v[118:119], v[114:115]
	v_lshl_add_u64 v[150:151], v[150:151], 0, v[144:145]
	v_cvt_pk_bf16_f32 v116, v116, v117
	v_cvt_pk_bf16_f32 v117, v120, v121
	v_cvt_pk_bf16_f32 v114, v122, v123
	v_cvt_pk_bf16_f32 v115, v124, v125
	global_store_dwordx4 v[150:151], v[114:117], off
	v_mul_f32_e32 v118, 0xbfb8aa3b, v112
	v_mul_f32_e32 v119, 0xbfb8aa3b, v113
	v_mul_f32_e32 v116, 0xbfb8aa3b, v110
	v_mul_f32_e32 v117, 0xbfb8aa3b, v111
	v_exp_f32_e32 v116, v116
	v_exp_f32_e32 v117, v117
	v_exp_f32_e32 v118, v118
	v_exp_f32_e32 v119, v119
	v_add_f32_e32 v116, 1.0, v116
	v_add_f32_e32 v117, 1.0, v117
	v_add_f32_e32 v118, 1.0, v118
	v_add_f32_e32 v119, 1.0, v119
	v_rcp_f32_e32 v116, v116
	v_rcp_f32_e32 v117, v117
	v_rcp_f32_e32 v118, v118
	v_rcp_f32_e32 v119, v119
	v_add_u32_e32 v114, 16, v149
	v_pk_mul_f32 v[110:111], v[110:111], v[116:117]
	v_mad_i64_i32 v[114:115], s[12:13], v114, s7, v[142:143]
	v_pk_mul_f32 v[112:113], v[112:113], v[118:119]
	v_pk_mul_f32 v[106:107], v[110:111], v[106:107]
; __device__ __forceinline__ unsigned cvt_pk_bf16(float lo, float hi) { unsigned r; asm("v_cvt_pk_bf16_f32 %0, %1, %2" : "=v"(r) : "v"(lo), "v"(hi)); return r; }
;     __device__ __forceinline__ void operator()(const AccT& acc, const Unit& u, int wr, int wc, int fr, int fq) const {
;     ...
; #pragma unroll
;         for (int ai = 0; ai < 2; ++ai)
; #pragma unroll
;             for (int m = 0; m < 4; ++m) { bf16_t* rowp = U + (size_t)(row0 + ai * 128 + m * 16) * HID + col0;
;                 const f32x4 s0 = silu4(acc[ai][0][m][0]) * acc[ai][1][m][0], s1 = silu4(acc[ai][0][m][1]) * acc[ai][1][m][1];
;                 u32x4 w; w.x = cvt_pk_bf16(s0[0], s0[1]); w.y = cvt_pk_bf16(s0[2], s0[3]); w.z = cvt_pk_bf16(s1[0], s1[1]); w.w = cvt_pk_bf16(s1[2], s1[3]);
;                 *(u32x4*)rowp = w; }
	v_pk_mul_f32 v[108:109], v[112:113], v[108:109]
	v_mul_f32_e32 v110, 0xbfb8aa3b, v102
	v_mul_f32_e32 v111, 0xbfb8aa3b, v103
	v_mul_f32_e32 v112, 0xbfb8aa3b, v104
	v_mul_f32_e32 v113, 0xbfb8aa3b, v105
	v_exp_f32_e32 v110, v110
	v_exp_f32_e32 v111, v111
	v_exp_f32_e32 v112, v112
	v_exp_f32_e32 v113, v113
	v_add_f32_e32 v110, 1.0, v110
	v_add_f32_e32 v111, 1.0, v111
	v_add_f32_e32 v112, 1.0, v112
	v_add_f32_e32 v113, 1.0, v113
	v_rcp_f32_e32 v110, v110
	v_rcp_f32_e32 v111, v111
	v_rcp_f32_e32 v112, v112
	v_rcp_f32_e32 v113, v113
	v_lshl_add_u64 v[114:115], v[114:115], 0, v[144:145]
	v_pk_mul_f32 v[102:103], v[102:103], v[110:111]
	s_and_b64 vcc, exec, s[2:3]
	v_pk_mul_f32 v[104:105], v[104:105], v[112:113]
	s_mov_b32 s10, s6
	v_pk_mul_f32 v[104:105], v[104:105], v[100:101]
	v_pk_mul_f32 v[100:101], v[102:103], v[98:99]
	v_cvt_pk_bf16_f32 v98, v106, v107
	v_cvt_pk_bf16_f32 v99, v108, v109
	v_mul_f32_e32 v102, 0xbfb8aa3b, v96
	v_cvt_pk_bf16_f32 v100, v100, v101
	v_cvt_pk_bf16_f32 v101, v104, v105
	global_store_dwordx4 v[114:115], v[98:101], off
	v_mul_f32_e32 v103, 0xbfb8aa3b, v97
	v_exp_f32_e32 v102, v102
	v_mul_f32_e32 v100, 0xbfb8aa3b, v94
	v_mul_f32_e32 v101, 0xbfb8aa3b, v95
	v_exp_f32_e32 v100, v100
	v_exp_f32_e32 v101, v101
	v_exp_f32_e32 v103, v103
	v_add_f32_e32 v102, 1.0, v102
	v_add_f32_e32 v100, 1.0, v100
	v_add_f32_e32 v101, 1.0, v101
	v_add_f32_e32 v103, 1.0, v103
	v_rcp_f32_e32 v100, v100
	v_rcp_f32_e32 v101, v101
	v_rcp_f32_e32 v102, v102
	v_rcp_f32_e32 v103, v103
	v_add_u32_e32 v98, 32, v149
	v_pk_mul_f32 v[94:95], v[94:95], v[100:101]
	v_mad_i64_i32 v[98:99], s[12:13], v98, s7, v[142:143]
	v_pk_mul_f32 v[96:97], v[96:97], v[102:103]
	v_pk_mul_f32 v[90:91], v[94:95], v[90:91]
	v_pk_mul_f32 v[92:93], v[96:97], v[92:93]
	v_mul_f32_e32 v94, 0xbfb8aa3b, v86
	v_mul_f32_e32 v95, 0xbfb8aa3b, v87
	v_mul_f32_e32 v96, 0xbfb8aa3b, v88
	v_mul_f32_e32 v97, 0xbfb8aa3b, v89
	v_exp_f32_e32 v94, v94
	v_exp_f32_e32 v95, v95
	v_exp_f32_e32 v96, v96
	v_exp_f32_e32 v97, v97
	v_add_f32_e32 v94, 1.0, v94
	v_add_f32_e32 v95, 1.0, v95
	v_add_f32_e32 v96, 1.0, v96
	v_add_f32_e32 v97, 1.0, v97
	v_rcp_f32_e32 v94, v94
	v_rcp_f32_e32 v95, v95
	v_rcp_f32_e32 v96, v96
	v_rcp_f32_e32 v97, v97
	v_lshl_add_u64 v[98:99], v[98:99], 0, v[144:145]
	v_pk_mul_f32 v[86:87], v[86:87], v[94:95]
	s_mov_b32 s64, s61
	v_pk_mul_f32 v[88:89], v[88:89], v[96:97]
	s_mov_b64 s[14:15], s[4:5]
	v_pk_mul_f32 v[88:89], v[88:89], v[84:85]
	v_pk_mul_f32 v[84:85], v[86:87], v[82:83]
	v_cvt_pk_bf16_f32 v82, v90, v91
	v_cvt_pk_bf16_f32 v83, v92, v93
	v_mul_f32_e32 v86, 0xbfb8aa3b, v80
	v_cvt_pk_bf16_f32 v84, v84, v85
	v_cvt_pk_bf16_f32 v85, v88, v89
	global_store_dwordx4 v[98:99], v[82:85], off
	v_mul_f32_e32 v87, 0xbfb8aa3b, v81
	v_exp_f32_e32 v86, v86
	v_mul_f32_e32 v84, 0xbfb8aa3b, v78
	v_mul_f32_e32 v85, 0xbfb8aa3b, v79
	v_exp_f32_e32 v84, v84
	v_exp_f32_e32 v85, v85
	v_exp_f32_e32 v87, v87
	v_add_f32_e32 v86, 1.0, v86
	v_add_f32_e32 v84, 1.0, v84
	v_add_f32_e32 v85, 1.0, v85
	v_add_f32_e32 v87, 1.0, v87
	v_rcp_f32_e32 v84, v84
	v_rcp_f32_e32 v85, v85
	v_rcp_f32_e32 v86, v86
	v_rcp_f32_e32 v87, v87
	v_add_u32_e32 v82, 48, v149
	v_pk_mul_f32 v[78:79], v[78:79], v[84:85]
	v_mad_i64_i32 v[82:83], s[12:13], v82, s7, v[142:143]
	v_pk_mul_f32 v[80:81], v[80:81], v[86:87]
	v_pk_mul_f32 v[74:75], v[78:79], v[74:75]
	v_pk_mul_f32 v[76:77], v[80:81], v[76:77]
	v_mul_f32_e32 v78, 0xbfb8aa3b, v70
	v_mul_f32_e32 v79, 0xbfb8aa3b, v71
	v_mul_f32_e32 v80, 0xbfb8aa3b, v72
	v_mul_f32_e32 v81, 0xbfb8aa3b, v73
	v_exp_f32_e32 v78, v78
	v_exp_f32_e32 v79, v79
	v_exp_f32_e32 v80, v80
	v_exp_f32_e32 v81, v81
	v_add_f32_e32 v78, 1.0, v78
	v_add_f32_e32 v79, 1.0, v79
	v_add_f32_e32 v80, 1.0, v80
	v_add_f32_e32 v81, 1.0, v81
	v_rcp_f32_e32 v78, v78
	v_rcp_f32_e32 v79, v79
	v_rcp_f32_e32 v80, v80
	v_rcp_f32_e32 v81, v81
	v_lshl_add_u64 v[82:83], v[82:83], 0, v[144:145]
	v_pk_mul_f32 v[70:71], v[70:71], v[78:79]
	s_mov_b64 s[68:69], 0x1000
	v_pk_mul_f32 v[72:73], v[72:73], v[80:81]
	s_nop 0
	v_pk_mul_f32 v[72:73], v[72:73], v[68:69]
	v_pk_mul_f32 v[68:69], v[70:71], v[66:67]
	v_cvt_pk_bf16_f32 v66, v74, v75
	v_cvt_pk_bf16_f32 v67, v76, v77
	v_mul_f32_e32 v70, 0xbfb8aa3b, v64
	v_cvt_pk_bf16_f32 v68, v68, v69
	v_cvt_pk_bf16_f32 v69, v72, v73
	global_store_dwordx4 v[82:83], v[66:69], off
	v_mul_f32_e32 v71, 0xbfb8aa3b, v65
	v_exp_f32_e32 v70, v70
	v_mul_f32_e32 v68, 0xbfb8aa3b, v62
	v_mul_f32_e32 v69, 0xbfb8aa3b, v63
	v_exp_f32_e32 v68, v68
	v_exp_f32_e32 v69, v69
	v_exp_f32_e32 v71, v71
	v_add_f32_e32 v70, 1.0, v70
	v_add_f32_e32 v68, 1.0, v68
	v_add_f32_e32 v69, 1.0, v69
	v_add_f32_e32 v71, 1.0, v71
	v_rcp_f32_e32 v68, v68
	v_rcp_f32_e32 v69, v69
	v_rcp_f32_e32 v70, v70
	v_rcp_f32_e32 v71, v71
	v_add_u32_e32 v66, 0x80, v149
	v_pk_mul_f32 v[62:63], v[62:63], v[68:69]
	v_mad_i64_i32 v[66:67], s[12:13], v66, s7, v[142:143]
	v_pk_mul_f32 v[64:65], v[64:65], v[70:71]
	v_pk_mul_f32 v[58:59], v[62:63], v[58:59]
	v_pk_mul_f32 v[60:61], v[64:65], v[60:61]
	v_mul_f32_e32 v62, 0xbfb8aa3b, v54
	v_mul_f32_e32 v63, 0xbfb8aa3b, v55
	v_mul_f32_e32 v64, 0xbfb8aa3b, v56
	v_mul_f32_e32 v65, 0xbfb8aa3b, v57
	v_exp_f32_e32 v62, v62
	v_exp_f32_e32 v63, v63
	v_exp_f32_e32 v64, v64
	v_exp_f32_e32 v65, v65
	v_add_f32_e32 v62, 1.0, v62
	v_add_f32_e32 v63, 1.0, v63
	v_add_f32_e32 v64, 1.0, v64
	v_add_f32_e32 v65, 1.0, v65
; __device__ __forceinline__ unsigned cvt_pk_bf16(float lo, float hi) { unsigned r; asm("v_cvt_pk_bf16_f32 %0, %1, %2" : "=v"(r) : "v"(lo), "v"(hi)); return r; }
; #define PG8_WAIT_V(n) asm volatile("s_waitcnt vmcnt(" #n ")" ::: "memory")
; #define PG8_BAR __builtin_amdgcn_s_barrier()
; template <class Epi>
; __device__ __forceinline__ void gemm_phase(LAS unsigned char* lds, const Gemm g, const Epi& E) {
;     ...
;         if (!has_next) break;
; #pragma unroll
;         for (int a = 0; a < 2; ++a)
; #pragma unroll
;             for (int b = 0; b < 2; ++b)
; #pragma unroll
;                 for (int m = 0; m < 4; ++m)
; #pragma unroll
;                     for (int n = 0; n < 2; ++n) acc[a][b][m][n] = (f32x4){0.f, 0.f, 0.f, 0.f};
;         cur = nxt; cA = nA; cB = nB; ++ui;
;     }
;     PG8_WAIT_V(0);
;     if (wr == 0) PG8_BAR;
;     __device__ __forceinline__ void operator()(const AccT& acc, const Unit& u, int wr, int wc, int fr, int fq) const {
;     ...
; #pragma unroll
;         for (int ai = 0; ai < 2; ++ai)
; #pragma unroll
;             for (int m = 0; m < 4; ++m) { bf16_t* rowp = U + (size_t)(row0 + ai * 128 + m * 16) * HID + col0;
;                 const f32x4 s0 = silu4(acc[ai][0][m][0]) * acc[ai][1][m][0], s1 = silu4(acc[ai][0][m][1]) * acc[ai][1][m][1];
;                 u32x4 w; w.x = cvt_pk_bf16(s0[0], s0[1]); w.y = cvt_pk_bf16(s0[2], s0[3]); w.z = cvt_pk_bf16(s1[0], s1[1]); w.w = cvt_pk_bf16(s1[2], s1[3]);
;                 *(u32x4*)rowp = w; }
	v_rcp_f32_e32 v62, v62
	v_rcp_f32_e32 v63, v63
	v_rcp_f32_e32 v64, v64
	v_rcp_f32_e32 v65, v65
	v_lshl_add_u64 v[66:67], v[66:67], 0, v[144:145]
	v_pk_mul_f32 v[54:55], v[54:55], v[62:63]
	v_pk_mul_f32 v[56:57], v[56:57], v[64:65]
	s_nop 0
	v_pk_mul_f32 v[56:57], v[56:57], v[52:53]
	v_pk_mul_f32 v[52:53], v[54:55], v[50:51]
	v_cvt_pk_bf16_f32 v50, v58, v59
	v_cvt_pk_bf16_f32 v51, v60, v61
	v_mul_f32_e32 v54, 0xbfb8aa3b, v48
	v_cvt_pk_bf16_f32 v52, v52, v53
	v_cvt_pk_bf16_f32 v53, v56, v57
	global_store_dwordx4 v[66:67], v[50:53], off
	v_mul_f32_e32 v55, 0xbfb8aa3b, v49
	v_exp_f32_e32 v54, v54
	v_mul_f32_e32 v52, 0xbfb8aa3b, v46
	v_mul_f32_e32 v53, 0xbfb8aa3b, v47
	v_exp_f32_e32 v52, v52
	v_exp_f32_e32 v53, v53
	v_exp_f32_e32 v55, v55
	v_add_f32_e32 v54, 1.0, v54
	v_add_f32_e32 v52, 1.0, v52
	v_add_f32_e32 v53, 1.0, v53
	v_add_f32_e32 v55, 1.0, v55
	v_rcp_f32_e32 v52, v52
	v_rcp_f32_e32 v53, v53
	v_rcp_f32_e32 v54, v54
	v_rcp_f32_e32 v55, v55
	v_add_u32_e32 v50, 0x90, v149
	v_pk_mul_f32 v[46:47], v[46:47], v[52:53]
	v_mad_i64_i32 v[50:51], s[12:13], v50, s7, v[142:143]
	v_pk_mul_f32 v[48:49], v[48:49], v[54:55]
	v_pk_mul_f32 v[42:43], v[46:47], v[42:43]
	v_pk_mul_f32 v[44:45], v[48:49], v[44:45]
	v_mul_f32_e32 v46, 0xbfb8aa3b, v38
	v_mul_f32_e32 v47, 0xbfb8aa3b, v39
	v_mul_f32_e32 v48, 0xbfb8aa3b, v40
	v_mul_f32_e32 v49, 0xbfb8aa3b, v41
	v_exp_f32_e32 v46, v46
	v_exp_f32_e32 v47, v47
	v_exp_f32_e32 v48, v48
	v_exp_f32_e32 v49, v49
	v_add_f32_e32 v46, 1.0, v46
	v_add_f32_e32 v47, 1.0, v47
	v_add_f32_e32 v48, 1.0, v48
	v_add_f32_e32 v49, 1.0, v49
	v_rcp_f32_e32 v46, v46
	v_rcp_f32_e32 v47, v47
	v_rcp_f32_e32 v48, v48
	v_rcp_f32_e32 v49, v49
	v_lshl_add_u64 v[50:51], v[50:51], 0, v[144:145]
	v_pk_mul_f32 v[38:39], v[38:39], v[46:47]
	v_pk_mul_f32 v[40:41], v[40:41], v[48:49]
	s_nop 0
	v_pk_mul_f32 v[40:41], v[40:41], v[36:37]
	v_pk_mul_f32 v[36:37], v[38:39], v[34:35]
	v_cvt_pk_bf16_f32 v34, v42, v43
	v_cvt_pk_bf16_f32 v35, v44, v45
	v_mul_f32_e32 v38, 0xbfb8aa3b, v32
	v_cvt_pk_bf16_f32 v36, v36, v37
	v_cvt_pk_bf16_f32 v37, v40, v41
	global_store_dwordx4 v[50:51], v[34:37], off
	v_mul_f32_e32 v39, 0xbfb8aa3b, v33
	v_exp_f32_e32 v38, v38
	v_mul_f32_e32 v36, 0xbfb8aa3b, v30
	v_mul_f32_e32 v37, 0xbfb8aa3b, v31
	v_exp_f32_e32 v36, v36
	v_exp_f32_e32 v37, v37
	v_exp_f32_e32 v39, v39
	v_add_f32_e32 v38, 1.0, v38
	v_add_f32_e32 v36, 1.0, v36
	v_add_f32_e32 v37, 1.0, v37
	v_add_f32_e32 v39, 1.0, v39
	v_rcp_f32_e32 v36, v36
	v_rcp_f32_e32 v37, v37
	v_rcp_f32_e32 v38, v38
	v_rcp_f32_e32 v39, v39
	v_add_u32_e32 v34, 0xa0, v149
	v_pk_mul_f32 v[30:31], v[30:31], v[36:37]
	v_mad_i64_i32 v[34:35], s[12:13], v34, s7, v[142:143]
	v_pk_mul_f32 v[32:33], v[32:33], v[38:39]
	v_pk_mul_f32 v[26:27], v[30:31], v[26:27]
	v_pk_mul_f32 v[28:29], v[32:33], v[28:29]
	v_mul_f32_e32 v30, 0xbfb8aa3b, v22
	v_mul_f32_e32 v31, 0xbfb8aa3b, v23
	v_mul_f32_e32 v32, 0xbfb8aa3b, v24
	v_mul_f32_e32 v33, 0xbfb8aa3b, v25
	v_exp_f32_e32 v30, v30
	v_exp_f32_e32 v31, v31
	v_exp_f32_e32 v32, v32
	v_exp_f32_e32 v33, v33
	v_add_f32_e32 v30, 1.0, v30
	v_add_f32_e32 v31, 1.0, v31
	v_add_f32_e32 v32, 1.0, v32
	v_add_f32_e32 v33, 1.0, v33
	v_rcp_f32_e32 v30, v30
	v_rcp_f32_e32 v31, v31
	v_rcp_f32_e32 v32, v32
	v_rcp_f32_e32 v33, v33
	v_lshl_add_u64 v[34:35], v[34:35], 0, v[144:145]
	v_pk_mul_f32 v[22:23], v[22:23], v[30:31]
	v_pk_mul_f32 v[24:25], v[24:25], v[32:33]
	s_nop 0
	v_pk_mul_f32 v[24:25], v[24:25], v[20:21]
	v_pk_mul_f32 v[20:21], v[22:23], v[18:19]
	v_cvt_pk_bf16_f32 v18, v26, v27
	v_cvt_pk_bf16_f32 v19, v28, v29
	v_mul_f32_e32 v22, 0xbfb8aa3b, v16
	v_cvt_pk_bf16_f32 v20, v20, v21
	v_cvt_pk_bf16_f32 v21, v24, v25
	global_store_dwordx4 v[34:35], v[18:21], off
	v_mul_f32_e32 v23, 0xbfb8aa3b, v17
	v_exp_f32_e32 v22, v22
	v_mul_f32_e32 v20, 0xbfb8aa3b, v14
	v_mul_f32_e32 v21, 0xbfb8aa3b, v15
	v_exp_f32_e32 v20, v20
	v_exp_f32_e32 v21, v21
	v_exp_f32_e32 v23, v23
	v_add_f32_e32 v22, 1.0, v22
	v_add_f32_e32 v20, 1.0, v20
	v_add_f32_e32 v21, 1.0, v21
	v_add_f32_e32 v23, 1.0, v23
	v_rcp_f32_e32 v20, v20
	v_rcp_f32_e32 v21, v21
	v_rcp_f32_e32 v22, v22
	v_rcp_f32_e32 v23, v23
	v_add_u32_e32 v18, 0xb0, v149
	v_pk_mul_f32 v[14:15], v[14:15], v[20:21]
	v_mad_i64_i32 v[18:19], s[12:13], v18, s7, v[142:143]
	v_pk_mul_f32 v[16:17], v[16:17], v[22:23]
	v_pk_mul_f32 v[10:11], v[14:15], v[10:11]
	v_pk_mul_f32 v[12:13], v[16:17], v[12:13]
	v_mul_f32_e32 v14, 0xbfb8aa3b, v6
	v_mul_f32_e32 v15, 0xbfb8aa3b, v7
	v_mul_f32_e32 v16, 0xbfb8aa3b, v8
	v_mul_f32_e32 v17, 0xbfb8aa3b, v9
	v_exp_f32_e32 v14, v14
	v_exp_f32_e32 v15, v15
	v_exp_f32_e32 v16, v16
	v_exp_f32_e32 v17, v17
	v_add_f32_e32 v14, 1.0, v14
	v_add_f32_e32 v15, 1.0, v15
	v_add_f32_e32 v16, 1.0, v16
	v_add_f32_e32 v17, 1.0, v17
	v_rcp_f32_e32 v14, v14
	v_rcp_f32_e32 v15, v15
	v_rcp_f32_e32 v16, v16
	v_rcp_f32_e32 v17, v17
	v_lshl_add_u64 v[18:19], v[18:19], 0, v[144:145]
	v_pk_mul_f32 v[6:7], v[6:7], v[14:15]
	s_mov_b64 s[12:13], s[8:9]
	v_pk_mul_f32 v[8:9], v[8:9], v[16:17]
	s_nop 0
	v_pk_mul_f32 v[8:9], v[8:9], v[4:5]
	v_pk_mul_f32 v[4:5], v[6:7], v[2:3]
	v_cvt_pk_bf16_f32 v2, v10, v11
	v_cvt_pk_bf16_f32 v3, v12, v13
	s_nop 0
	v_cvt_pk_bf16_f32 v4, v4, v5
	v_cvt_pk_bf16_f32 v5, v8, v9
	global_store_dwordx4 v[18:19], v[2:5], off
	s_cbranch_vccz .LBB0_520
	s_waitcnt vmcnt(0)
	s_cmpk_gt_u32 s1, 0xff
	s_cbranch_scc1 .LBB0_529
	s_barrier

; #define PG8_STAGE(bufoff, gbase, voff) do { _Pragma("unroll") for (int _i = 0; _i < 2; ++_i) \
;         __builtin_amdgcn_global_load_lds((const unsigned*)((const char*)(gbase) + (voff)[_i]), (LAS unsigned*)(lds + (bufoff) + ldsw + _i * 8192), 16, 0, 0); } while (0)
; #define PG8_LDA(dst, b, h) do { _Pragma("unroll") for (int m = 0; m < 4; ++m) _Pragma("unroll") for (int k = 0; k < 2; ++k) dst[m][k] = *(const LAS bf16x8*)(lds + PG8_SA(b, h) + aoff + m * 2048 + k * 1024); } while (0)
; #define PG8_LDB(dst, b, h) do { _Pragma("unroll") for (int n = 0; n < 2; ++n) _Pragma("unroll") for (int k = 0; k < 2; ++k) dst[n][k] = *(const LAS bf16x8*)(lds + PG8_SB(b, h) + boff + n * 2048 + k * 1024); } while (0)
; #define PG8_MMA(ai, bj, At, Bt) do { __builtin_amdgcn_s_setprio(1); _Pragma("unroll") for (int m = 0; m < 4; ++m) _Pragma("unroll") for (int n = 0; n < 2; ++n) _Pragma("unroll") for (int k = 0; k < 2; ++k) \
;         acc[ai][bj][m][n] = __builtin_amdgcn_mfma_f32_16x16x32_bf16(Bt[n][k], At[m][k], acc[ai][bj][m][n], 0, 0, 0); __builtin_amdgcn_s_setprio(0); } while (0)
; #define PG8_WAIT_L(n) asm volatile("s_waitcnt lgkmcnt(" #n ")" ::: "memory")
; #define PG8_BAR __builtin_amdgcn_s_barrier()
; #define PG8_SCHED __builtin_amdgcn_sched_barrier(0)
; template <class Epi>
; __device__ __forceinline__ void gemm_phase(LAS unsigned char* lds, const Gemm g, const Epi& E) {
;     ...
;             PG8_LDB(B0, 0, 0); PG8_SCHED; PG8_LDA(At, 0, 0); PG8_STAGE(PG8_SA(1, 1), a1 + hstepA, voffA);
;             PG8_WAIT_L(8); PG8_BAR; PG8_WAIT_L(0); PG8_MMA(0, 0, At, B0); PG8_BAR; PG8_SCHED;
;             PG8_LDB(B1, 0, 1); PG8_STAGE(PG8_SB(0, 0), b2, voffB);
;             PG8_BAR; PG8_WAIT_L(0); PG8_MMA(0, 1, At, B1); PG8_BAR;
;             PG8_LDA(At, 0, 1); PG8_STAGE(PG8_SA(0, 0), a2, voffA);
;             PG8_BAR; PG8_WAIT_L(0); PG8_MMA(1, 0, At, B0); PG8_BAR; PG8_SCHED;
.LBB0_547:
	s_add_u32 s10, s8, 0x100
	s_addc_u32 s11, s9, 0
	s_add_i32 s26, 0, 0x10000
	v_add_u32_e32 v142, s26, v157
	ds_read_b128 v[130:133], v142
	ds_read_b128 v[134:137], v142 offset:1024
	ds_read_b128 v[138:141], v142 offset:2048
	ds_read_b128 v[142:145], v142 offset:3072
	s_cmp_eq_u32 s67, 40
	s_cselect_b32 s15, s5, s11
	s_cselect_b32 s14, s4, s10
	s_cselect_b32 s13, s7, s66
	s_cselect_b32 s12, s6, s65
	v_lshl_add_u64 v[154:155], s[8:9], 0, v[150:151]
	s_add_i32 m0, s29, 0xc000
	ds_read_b128 v[160:163], v158
	ds_read_b128 v[164:167], v158 offset:1024
	ds_read_b128 v[168:171], v158 offset:2048
	ds_read_b128 v[172:175], v158 offset:3072
	ds_read_b128 v[180:183], v158 offset:4096
	ds_read_b128 v[184:187], v158 offset:5120
	ds_read_b128 v[188:191], v158 offset:6144
	ds_read_b128 v[192:195], v158 offset:7168
	global_load_lds_dwordx4 v[154:155], off
	v_lshl_add_u64 v[154:155], s[8:9], 0, v[152:153]
	s_add_i32 m0, s29, 0xe000
	s_nop 0
	global_load_lds_dwordx4 v[154:155], off
	s_waitcnt lgkmcnt(0)
	s_barrier
	s_setprio 1
	v_mfma_f32_16x16x32_bf16 v[126:129], v[130:133], v[160:163], v[126:129]
	v_mfma_f32_16x16x32_bf16 v[122:125], v[138:141], v[160:163], v[122:125]
	v_mfma_f32_16x16x32_bf16 v[118:121], v[130:133], v[168:171], v[118:121]
	v_mfma_f32_16x16x32_bf16 v[110:113], v[138:141], v[168:171], v[110:113]
	v_mfma_f32_16x16x32_bf16 v[102:105], v[130:133], v[180:183], v[102:105]
	v_mfma_f32_16x16x32_bf16 v[94:97], v[138:141], v[180:183], v[94:97]
	v_mfma_f32_16x16x32_bf16 v[86:89], v[130:133], v[188:191], v[86:89]
	v_mfma_f32_16x16x32_bf16 v[78:81], v[138:141], v[188:191], v[78:81]
	v_mfma_f32_16x16x32_bf16 v[126:129], v[134:137], v[164:167], v[126:129]
	v_mfma_f32_16x16x32_bf16 v[122:125], v[142:145], v[164:167], v[122:125]
	v_mfma_f32_16x16x32_bf16 v[118:121], v[134:137], v[172:175], v[118:121]
	v_mfma_f32_16x16x32_bf16 v[110:113], v[142:145], v[172:175], v[110:113]
	v_mfma_f32_16x16x32_bf16 v[102:105], v[134:137], v[184:187], v[102:105]
	v_mfma_f32_16x16x32_bf16 v[94:97], v[142:145], v[184:187], v[94:97]
	v_mfma_f32_16x16x32_bf16 v[86:89], v[134:137], v[192:195], v[86:89]
	v_mfma_f32_16x16x32_bf16 v[78:81], v[142:145], v[192:195], v[78:81]
	s_setprio 0
	s_barrier
	s_add_i32 s27, 0, 0x14000
	v_add_u32_e32 v154, s27, v157
	s_add_i32 s8, s26, s18
	ds_read_b128 v[196:199], v154
	ds_read_b128 v[200:203], v154 offset:1024
	ds_read_b128 v[204:207], v154 offset:2048
	ds_read_b128 v[226:229], v154 offset:3072
	v_lshl_add_u64 v[154:155], s[12:13], 0, v[148:149]
	s_mov_b32 m0, s8
	v_lshl_add_u64 v[176:177], s[12:13], 0, v[146:147]
	global_load_lds_dwordx4 v[154:155], off
	s_add_i32 m0, s8, 0x2000
	s_nop 0
	global_load_lds_dwordx4 v[176:177], off
	s_waitcnt lgkmcnt(0)
	s_barrier
	s_setprio 1
	v_mfma_f32_16x16x32_bf16 v[114:117], v[196:199], v[160:163], v[114:117]
	v_mfma_f32_16x16x32_bf16 v[106:109], v[204:207], v[160:163], v[106:109]
	v_mfma_f32_16x16x32_bf16 v[98:101], v[196:199], v[168:171], v[98:101]
	v_mfma_f32_16x16x32_bf16 v[90:93], v[204:207], v[168:171], v[90:93]
	v_mfma_f32_16x16x32_bf16 v[82:85], v[196:199], v[180:183], v[82:85]
	v_mfma_f32_16x16x32_bf16 v[74:77], v[204:207], v[180:183], v[74:77]
	v_mfma_f32_16x16x32_bf16 v[70:73], v[196:199], v[188:191], v[70:73]
	v_mfma_f32_16x16x32_bf16 v[66:69], v[204:207], v[188:191], v[66:69]
	v_mfma_f32_16x16x32_bf16 v[114:117], v[200:203], v[164:167], v[114:117]
	v_mfma_f32_16x16x32_bf16 v[106:109], v[226:229], v[164:167], v[106:109]
	v_mfma_f32_16x16x32_bf16 v[98:101], v[200:203], v[172:175], v[98:101]
	v_mfma_f32_16x16x32_bf16 v[90:93], v[226:229], v[172:175], v[90:93]
	v_mfma_f32_16x16x32_bf16 v[82:85], v[200:203], v[184:187], v[82:85]
	v_mfma_f32_16x16x32_bf16 v[74:77], v[226:229], v[184:187], v[74:77]
	v_mfma_f32_16x16x32_bf16 v[70:73], v[200:203], v[192:195], v[70:73]
	v_mfma_f32_16x16x32_bf16 v[66:69], v[226:229], v[192:195], v[66:69]
	s_setprio 0
	s_mov_b32 m0, s29
	v_lshl_add_u64 v[208:209], s[14:15], 0, v[148:149]
	s_barrier
	ds_read_b128 v[160:163], v158 offset:16384
	ds_read_b128 v[164:167], v158 offset:17408
	ds_read_b128 v[168:171], v158 offset:18432
	ds_read_b128 v[172:175], v158 offset:19456
	ds_read_b128 v[180:183], v158 offset:20480
	ds_read_b128 v[184:187], v158 offset:21504
	ds_read_b128 v[188:191], v158 offset:22528
	ds_read_b128 v[192:195], v158 offset:23552
	global_load_lds_dwordx4 v[208:209], off
	v_lshl_add_u64 v[230:231], s[14:15], 0, v[146:147]
	s_mov_b32 m0, s30
	s_nop 0
	global_load_lds_dwordx4 v[230:231], off
	s_waitcnt lgkmcnt(0)
	s_barrier
	s_setprio 1
	v_mfma_f32_16x16x32_bf16 v[62:65], v[130:133], v[160:163], v[62:65]
	v_mfma_f32_16x16x32_bf16 v[58:61], v[138:141], v[160:163], v[58:61]
	v_mfma_f32_16x16x32_bf16 v[54:57], v[130:133], v[168:171], v[54:57]
	v_mfma_f32_16x16x32_bf16 v[46:49], v[138:141], v[168:171], v[46:49]
	v_mfma_f32_16x16x32_bf16 v[38:41], v[130:133], v[180:183], v[38:41]
	v_mfma_f32_16x16x32_bf16 v[30:33], v[138:141], v[180:183], v[30:33]
	v_mfma_f32_16x16x32_bf16 v[22:25], v[130:133], v[188:191], v[22:25]
	v_mfma_f32_16x16x32_bf16 v[14:17], v[138:141], v[188:191], v[14:17]
	v_mfma_f32_16x16x32_bf16 v[62:65], v[134:137], v[164:167], v[62:65]
	v_mfma_f32_16x16x32_bf16 v[58:61], v[142:145], v[164:167], v[58:61]
	v_mfma_f32_16x16x32_bf16 v[54:57], v[134:137], v[172:175], v[54:57]
	v_mfma_f32_16x16x32_bf16 v[46:49], v[142:145], v[172:175], v[46:49]
	v_mfma_f32_16x16x32_bf16 v[38:41], v[134:137], v[184:187], v[38:41]
	v_mfma_f32_16x16x32_bf16 v[30:33], v[142:145], v[184:187], v[30:33]
	v_mfma_f32_16x16x32_bf16 v[22:25], v[134:137], v[192:195], v[22:25]
	v_mfma_f32_16x16x32_bf16 v[14:17], v[142:145], v[192:195], v[14:17]
	s_setprio 0
	s_barrier
; #define PG8_STAGE(bufoff, gbase, voff) do { _Pragma("unroll") for (int _i = 0; _i < 2; ++_i) \
;         __builtin_amdgcn_global_load_lds((const unsigned*)((const char*)(gbase) + (voff)[_i]), (LAS unsigned*)(lds + (bufoff) + ldsw + _i * 8192), 16, 0, 0); } while (0)
; #define PG8_LDA(dst, b, h) do { _Pragma("unroll") for (int m = 0; m < 4; ++m) _Pragma("unroll") for (int k = 0; k < 2; ++k) dst[m][k] = *(const LAS bf16x8*)(lds + PG8_SA(b, h) + aoff + m * 2048 + k * 1024); } while (0)
; #define PG8_LDB(dst, b, h) do { _Pragma("unroll") for (int n = 0; n < 2; ++n) _Pragma("unroll") for (int k = 0; k < 2; ++k) dst[n][k] = *(const LAS bf16x8*)(lds + PG8_SB(b, h) + boff + n * 2048 + k * 1024); } while (0)
; #define PG8_MMA(ai, bj, At, Bt) do { __builtin_amdgcn_s_setprio(1); _Pragma("unroll") for (int m = 0; m < 4; ++m) _Pragma("unroll") for (int n = 0; n < 2; ++n) _Pragma("unroll") for (int k = 0; k < 2; ++k) \
;         acc[ai][bj][m][n] = __builtin_amdgcn_mfma_f32_16x16x32_bf16(Bt[n][k], At[m][k], acc[ai][bj][m][n], 0, 0, 0); __builtin_amdgcn_s_setprio(0); } while (0)
; #define PG8_WAIT_V(n) asm volatile("s_waitcnt vmcnt(" #n ")" ::: "memory")
; #define PG8_WAIT_L(n) asm volatile("s_waitcnt lgkmcnt(" #n ")" ::: "memory")
; #define PG8_BAR __builtin_amdgcn_s_barrier()
; #define PG8_SCHED __builtin_amdgcn_sched_barrier(0)
; template <class Epi>
; __device__ __forceinline__ void gemm_phase(LAS unsigned char* lds, const Gemm g, const Epi& E) {
;     ...
;             PG8_STAGE(PG8_SB(0, 1), b2 + hstepB, voffB);
;             PG8_WAIT_V(6); PG8_BAR; PG8_MMA(1, 1, At, B1); PG8_BAR;
;             PG8_LDB(B0, 1, 0); PG8_SCHED; PG8_LDA(At, 1, 0); PG8_STAGE(PG8_SA(0, 1), a2 + hstepA, voffA);
;             PG8_WAIT_L(8); PG8_BAR; PG8_WAIT_L(0); PG8_MMA(0, 0, At, B0); PG8_BAR; PG8_SCHED;
;             PG8_LDB(B1, 1, 1); PG8_STAGE(PG8_SB(1, 0), b3, voffB);
;             PG8_BAR; PG8_WAIT_L(0); PG8_MMA(0, 1, At, B1); PG8_BAR;
;             PG8_LDA(At, 1, 1); PG8_STAGE(PG8_SA(1, 0), a3, voffA);
	s_add_u32 s8, s12, 0xb0000
	s_addc_u32 s9, s13, 0
	s_add_i32 s26, s27, s18
	v_lshl_add_u64 v[130:131], s[8:9], 0, v[148:149]
	s_mov_b32 m0, s26
	s_nop 0
	global_load_lds_dwordx4 v[130:131], off
	v_lshl_add_u64 v[130:131], s[8:9], 0, v[146:147]
	s_add_i32 m0, s26, 0x2000
	s_nop 0
	global_load_lds_dwordx4 v[130:131], off
	s_waitcnt vmcnt(6)
	s_barrier
	s_setprio 1
	v_mfma_f32_16x16x32_bf16 v[50:53], v[196:199], v[160:163], v[50:53]
	v_mfma_f32_16x16x32_bf16 v[42:45], v[204:207], v[160:163], v[42:45]
	v_mfma_f32_16x16x32_bf16 v[34:37], v[196:199], v[168:171], v[34:37]
	v_mfma_f32_16x16x32_bf16 v[26:29], v[204:207], v[168:171], v[26:29]
	v_mfma_f32_16x16x32_bf16 v[18:21], v[196:199], v[180:183], v[18:21]
	v_mfma_f32_16x16x32_bf16 v[10:13], v[204:207], v[180:183], v[10:13]
	v_mfma_f32_16x16x32_bf16 v[6:9], v[196:199], v[188:191], v[6:9]
	v_mfma_f32_16x16x32_bf16 v[2:5], v[204:207], v[188:191], v[2:5]
	v_mfma_f32_16x16x32_bf16 v[50:53], v[200:203], v[164:167], v[50:53]
	v_mfma_f32_16x16x32_bf16 v[42:45], v[226:229], v[164:167], v[42:45]
	v_mfma_f32_16x16x32_bf16 v[34:37], v[200:203], v[172:175], v[34:37]
	v_mfma_f32_16x16x32_bf16 v[26:29], v[226:229], v[172:175], v[26:29]
	v_mfma_f32_16x16x32_bf16 v[18:21], v[200:203], v[184:187], v[18:21]
	v_mfma_f32_16x16x32_bf16 v[10:13], v[226:229], v[184:187], v[10:13]
	v_mfma_f32_16x16x32_bf16 v[6:9], v[200:203], v[192:195], v[6:9]
	v_mfma_f32_16x16x32_bf16 v[2:5], v[226:229], v[192:195], v[2:5]
	s_setprio 0
	s_add_i32 s26, 0, 0x18000
	v_add_u32_e32 v142, s26, v157
	s_barrier
	ds_read_b128 v[130:133], v142
	ds_read_b128 v[134:137], v142 offset:1024
	ds_read_b128 v[138:141], v142 offset:2048
	ds_read_b128 v[142:145], v142 offset:3072
	s_add_u32 s8, s14, 0xb0000
	s_addc_u32 s9, s15, 0
	s_mov_b32 m0, s31
	v_lshl_add_u64 v[196:197], s[8:9], 0, v[148:149]
	ds_read_b128 v[160:163], v158 offset:32768
	ds_read_b128 v[164:167], v158 offset:33792
	ds_read_b128 v[168:171], v158 offset:34816
	ds_read_b128 v[172:175], v158 offset:35840
	ds_read_b128 v[180:183], v158 offset:36864
	ds_read_b128 v[184:187], v158 offset:37888
	ds_read_b128 v[188:191], v158 offset:38912
	ds_read_b128 v[192:195], v158 offset:39936
	global_load_lds_dwordx4 v[196:197], off
	v_lshl_add_u64 v[196:197], s[8:9], 0, v[146:147]
	s_mov_b32 m0, s36
	s_nop 0
	global_load_lds_dwordx4 v[196:197], off
	s_waitcnt lgkmcnt(0)
	s_barrier
	s_setprio 1
	v_mfma_f32_16x16x32_bf16 v[126:129], v[130:133], v[160:163], v[126:129]
	v_mfma_f32_16x16x32_bf16 v[122:125], v[138:141], v[160:163], v[122:125]
	v_mfma_f32_16x16x32_bf16 v[118:121], v[130:133], v[168:171], v[118:121]
	v_mfma_f32_16x16x32_bf16 v[110:113], v[138:141], v[168:171], v[110:113]
	v_mfma_f32_16x16x32_bf16 v[102:105], v[130:133], v[180:183], v[102:105]
	v_mfma_f32_16x16x32_bf16 v[94:97], v[138:141], v[180:183], v[94:97]
	v_mfma_f32_16x16x32_bf16 v[86:89], v[130:133], v[188:191], v[86:89]
	v_mfma_f32_16x16x32_bf16 v[78:81], v[138:141], v[188:191], v[78:81]
	v_mfma_f32_16x16x32_bf16 v[126:129], v[134:137], v[164:167], v[126:129]
	v_mfma_f32_16x16x32_bf16 v[122:125], v[142:145], v[164:167], v[122:125]
	v_mfma_f32_16x16x32_bf16 v[118:121], v[134:137], v[172:175], v[118:121]
	v_mfma_f32_16x16x32_bf16 v[110:113], v[142:145], v[172:175], v[110:113]
	v_mfma_f32_16x16x32_bf16 v[102:105], v[134:137], v[184:187], v[102:105]
	v_mfma_f32_16x16x32_bf16 v[94:97], v[142:145], v[184:187], v[94:97]
	v_mfma_f32_16x16x32_bf16 v[86:89], v[134:137], v[192:195], v[86:89]
	v_mfma_f32_16x16x32_bf16 v[78:81], v[142:145], v[192:195], v[78:81]
	s_setprio 0
	s_barrier
	s_add_i32 s14, 0, 0x1c000
	s_add_i32 s8, s26, s18
	v_add_u32_e32 v159, s14, v157
	v_lshl_add_u64 v[154:155], v[154:155], 0, s[86:87]
	s_mov_b32 m0, s8
	ds_read_b128 v[196:199], v159
	ds_read_b128 v[200:203], v159 offset:1024
	ds_read_b128 v[204:207], v159 offset:2048
	ds_read_b128 v[226:229], v159 offset:3072
	global_load_lds_dwordx4 v[154:155], off
	v_lshl_add_u64 v[154:155], v[176:177], 0, s[86:87]
	s_add_i32 m0, s8, 0x2000
	s_nop 0
	global_load_lds_dwordx4 v[154:155], off
	s_waitcnt lgkmcnt(0)
	s_barrier
	s_setprio 1
	v_mfma_f32_16x16x32_bf16 v[114:117], v[196:199], v[160:163], v[114:117]
	v_mfma_f32_16x16x32_bf16 v[106:109], v[204:207], v[160:163], v[106:109]
	v_mfma_f32_16x16x32_bf16 v[98:101], v[196:199], v[168:171], v[98:101]
	v_mfma_f32_16x16x32_bf16 v[90:93], v[204:207], v[168:171], v[90:93]
	v_mfma_f32_16x16x32_bf16 v[82:85], v[196:199], v[180:183], v[82:85]
	v_mfma_f32_16x16x32_bf16 v[74:77], v[204:207], v[180:183], v[74:77]
	v_mfma_f32_16x16x32_bf16 v[70:73], v[196:199], v[188:191], v[70:73]
	v_mfma_f32_16x16x32_bf16 v[66:69], v[204:207], v[188:191], v[66:69]
	v_mfma_f32_16x16x32_bf16 v[114:117], v[200:203], v[164:167], v[114:117]
	v_mfma_f32_16x16x32_bf16 v[106:109], v[226:229], v[164:167], v[106:109]
	v_mfma_f32_16x16x32_bf16 v[98:101], v[200:203], v[172:175], v[98:101]
	v_mfma_f32_16x16x32_bf16 v[90:93], v[226:229], v[172:175], v[90:93]
	v_mfma_f32_16x16x32_bf16 v[82:85], v[200:203], v[184:187], v[82:85]
	v_mfma_f32_16x16x32_bf16 v[74:77], v[226:229], v[184:187], v[74:77]
	v_mfma_f32_16x16x32_bf16 v[70:73], v[200:203], v[192:195], v[70:73]
	v_mfma_f32_16x16x32_bf16 v[66:69], v[226:229], v[192:195], v[66:69]
	s_setprio 0
	s_mov_b32 m0, s52
	v_lshl_add_u64 v[154:155], v[208:209], 0, s[86:87]
	s_barrier
	ds_read_b128 v[160:163], v158 offset:49152
	ds_read_b128 v[164:167], v158 offset:50176
	ds_read_b128 v[168:171], v158 offset:51200
	ds_read_b128 v[172:175], v158 offset:52224
	ds_read_b128 v[180:183], v158 offset:53248
	ds_read_b128 v[184:187], v158 offset:54272
	ds_read_b128 v[188:191], v158 offset:55296
	ds_read_b128 v[192:195], v158 offset:56320
	global_load_lds_dwordx4 v[154:155], off
	v_lshl_add_u64 v[154:155], v[230:231], 0, s[86:87]
	s_mov_b32 m0, s53
	s_nop 0
	global_load_lds_dwordx4 v[154:155], off
	s_waitcnt lgkmcnt(0)
	s_barrier
; #define PG8_STAGE(bufoff, gbase, voff) do { _Pragma("unroll") for (int _i = 0; _i < 2; ++_i) \
;         __builtin_amdgcn_global_load_lds((const unsigned*)((const char*)(gbase) + (voff)[_i]), (LAS unsigned*)(lds + (bufoff) + ldsw + _i * 8192), 16, 0, 0); } while (0)
; #define PG8_MMA(ai, bj, At, Bt) do { __builtin_amdgcn_s_setprio(1); _Pragma("unroll") for (int m = 0; m < 4; ++m) _Pragma("unroll") for (int n = 0; n < 2; ++n) _Pragma("unroll") for (int k = 0; k < 2; ++k) \
;         acc[ai][bj][m][n] = __builtin_amdgcn_mfma_f32_16x16x32_bf16(Bt[n][k], At[m][k], acc[ai][bj][m][n], 0, 0, 0); __builtin_amdgcn_s_setprio(0); } while (0)
; #define PG8_WAIT_V(n) asm volatile("s_waitcnt vmcnt(" #n ")" ::: "memory")
; #define PG8_WAIT_L(n) asm volatile("s_waitcnt lgkmcnt(" #n ")" ::: "memory")
; #define PG8_BAR __builtin_amdgcn_s_barrier()
; template <class Epi>
; __device__ __forceinline__ void gemm_phase(LAS unsigned char* lds, const Gemm g, const Epi& E) {
;     ...
;             PG8_BAR; PG8_WAIT_L(0); PG8_MMA(1, 0, At, B0); PG8_BAR; PG8_SCHED;
;             PG8_STAGE(PG8_SB(1, 1), b3 + hstepB, voffB);
;             PG8_WAIT_V(6); PG8_BAR; PG8_MMA(1, 1, At, B1); PG8_BAR;
;     __device__ __forceinline__ void operator()(const AccT& acc, const Unit& u, int wr, int wc, int fr, int fq) const {
;         asm volatile("" : "+v"(fr), "+v"(fq));
;         const int gpm = mapA.src(u.pm);
;         const int mb = gpm < 32 ? 32 : (gpm - 32) >> 3;
;         const int row0 = gpm * 256 + wr * 64 + fr, col0 = u.pn * 256 + wc * 32 + 4 * fq;
;         const float* gp = modl + ((size_t)mb * 6 + gi) * 1024;
;         f32x4 gv[2][2];
; #pragma unroll
;         for (int bj = 0; bj < 2; ++bj)
; #pragma unroll
;             for (int n = 0; n < 2; ++n) { gv[bj][n] = *(const f32x4*)(gp + col0 + bj * 128 + n * 16); if (scale) gv[bj][n] = gv[bj][n] * *(const f32x4*)(scale + col0 + bj * 128 + n * 16); }
;         const float* sbase = (gpm < 32 ? Xc : Xl) + (size_t)row0 * 1024 + col0;
; #pragma unroll
;         for (int ai = 0; ai < 2; ++ai) {
;             f32x4 xo[4][2][2];
; #pragma unroll
;             for (int m = 0; m < 4; ++m)
; #pragma unroll
;                 for (int bj = 0; bj < 2; ++bj)
; #pragma unroll
;                     for (int n = 0; n < 2; ++n) xo[m][bj][n] = *(const f32x4*)(sbase + (size_t)(ai * 128 + m * 16) * 1024 + bj * 128 + n * 16);
	s_setprio 1
	v_mfma_f32_16x16x32_bf16 v[62:65], v[130:133], v[160:163], v[62:65]
	v_mfma_f32_16x16x32_bf16 v[58:61], v[138:141], v[160:163], v[58:61]
	v_mfma_f32_16x16x32_bf16 v[54:57], v[130:133], v[168:171], v[54:57]
	v_mfma_f32_16x16x32_bf16 v[46:49], v[138:141], v[168:171], v[46:49]
	v_mfma_f32_16x16x32_bf16 v[38:41], v[130:133], v[180:183], v[38:41]
	v_mfma_f32_16x16x32_bf16 v[30:33], v[138:141], v[180:183], v[30:33]
	v_mfma_f32_16x16x32_bf16 v[22:25], v[130:133], v[188:191], v[22:25]
	v_mfma_f32_16x16x32_bf16 v[14:17], v[138:141], v[188:191], v[14:17]
	v_mfma_f32_16x16x32_bf16 v[62:65], v[134:137], v[164:167], v[62:65]
	v_mfma_f32_16x16x32_bf16 v[58:61], v[142:145], v[164:167], v[58:61]
	v_mfma_f32_16x16x32_bf16 v[54:57], v[134:137], v[172:175], v[54:57]
	v_mfma_f32_16x16x32_bf16 v[46:49], v[142:145], v[172:175], v[46:49]
	v_mfma_f32_16x16x32_bf16 v[38:41], v[134:137], v[184:187], v[38:41]
	v_mfma_f32_16x16x32_bf16 v[30:33], v[142:145], v[184:187], v[30:33]
	v_mfma_f32_16x16x32_bf16 v[22:25], v[134:137], v[192:195], v[22:25]
	v_mfma_f32_16x16x32_bf16 v[14:17], v[142:145], v[192:195], v[14:17]
	s_setprio 0
	s_barrier
	s_add_u32 s8, s12, 0xb0080
	s_addc_u32 s9, s13, 0
	s_add_i32 s12, s14, s18
	v_lshl_add_u64 v[130:131], s[8:9], 0, v[148:149]
	s_mov_b32 m0, s12
	s_nop 0
	global_load_lds_dwordx4 v[130:131], off
	v_lshl_add_u64 v[130:131], s[8:9], 0, v[146:147]
	s_add_i32 m0, s12, 0x2000
	s_nop 0
	global_load_lds_dwordx4 v[130:131], off
	s_waitcnt vmcnt(6)
	s_barrier
	s_setprio 1
	v_mfma_f32_16x16x32_bf16 v[50:53], v[196:199], v[160:163], v[50:53]
	v_mfma_f32_16x16x32_bf16 v[42:45], v[204:207], v[160:163], v[42:45]
	v_mfma_f32_16x16x32_bf16 v[34:37], v[196:199], v[168:171], v[34:37]
	v_mfma_f32_16x16x32_bf16 v[26:29], v[204:207], v[168:171], v[26:29]
	v_mfma_f32_16x16x32_bf16 v[18:21], v[196:199], v[180:183], v[18:21]
	v_mfma_f32_16x16x32_bf16 v[10:13], v[204:207], v[180:183], v[10:13]
	v_mfma_f32_16x16x32_bf16 v[6:9], v[196:199], v[188:191], v[6:9]
	v_mfma_f32_16x16x32_bf16 v[2:5], v[204:207], v[188:191], v[2:5]
	v_mfma_f32_16x16x32_bf16 v[50:53], v[200:203], v[164:167], v[50:53]
	v_mfma_f32_16x16x32_bf16 v[42:45], v[226:229], v[164:167], v[42:45]
	v_mfma_f32_16x16x32_bf16 v[34:37], v[200:203], v[172:175], v[34:37]
	v_mfma_f32_16x16x32_bf16 v[26:29], v[226:229], v[172:175], v[26:29]
	v_mfma_f32_16x16x32_bf16 v[18:21], v[200:203], v[184:187], v[18:21]
	v_mfma_f32_16x16x32_bf16 v[10:13], v[226:229], v[184:187], v[10:13]
	v_mfma_f32_16x16x32_bf16 v[6:9], v[200:203], v[192:195], v[6:9]
	v_mfma_f32_16x16x32_bf16 v[2:5], v[226:229], v[192:195], v[2:5]
	s_setprio 0
	s_add_i32 s67, s67, 2
	s_add_u32 s65, s65, 0x100
	s_addc_u32 s66, s66, 0
	s_cmp_gt_u32 s67, 41
	s_mov_b64 s[8:9], s[10:11]
	s_barrier
	s_cbranch_scc0 .LBB0_547
	v_readlane_b32 s8, v255, 27
	s_cmp_ge_i32 s64, s8
	s_cselect_b32 s8, s25, 0
	s_add_i32 s10, s64, s8
	s_sub_i32 s8, s10, 32
	s_lshl_b32 s9, s61, 8
	s_ashr_i32 s8, s8, 3
	s_or_b32 s9, s9, s50
	v_mov_b32_e32 v130, v1
	v_mov_b32_e32 v159, v156
	s_mul_i32 s8, s8, 6
	s_cmp_gt_i32 s10, 31
	s_cselect_b32 s8, s8, 0xc0
	v_lshl_add_u32 v130, v130, 2, s9
	s_ashr_i32 s9, s8, 31
	s_lshl_b64 s[8:9], s[8:9], 12
	v_readlane_b32 s12, v255, 14
	v_readlane_b32 s13, v255, 15
	s_add_u32 s8, s12, s8
	v_ashrrev_i32_e32 v131, 31, v130
	s_addc_u32 s9, s13, s9
	v_lshlrev_b64 v[154:155], 2, v[130:131]
	v_lshl_add_u64 v[130:131], s[8:9], 0, v[154:155]
	s_mov_b64 s[8:9], 0x5000
	v_lshl_add_u64 v[132:133], v[130:131], 0, s[8:9]
	s_movk_i32 s8, 0x5000
	v_add_co_u32_e32 v130, vcc, s8, v130
	s_lshl_b32 s8, s10, 8
	s_add_i32 s8, s8, s44
	v_add_u32_e32 v160, s8, v159
	v_ashrrev_i32_e32 v161, 31, v160
	v_readlane_b32 s8, v254, 0
	v_lshlrev_b64 v[160:161], 12, v[160:161]
	v_readlane_b32 s9, v254, 1
	v_addc_co_u32_e32 v131, vcc, 0, v131, vcc
	s_nop 0
	v_lshl_add_u64 v[160:161], s[8:9], 0, v[160:161]
	v_lshl_add_u64 v[154:155], v[160:161], 0, v[154:155]
	v_add_co_u32_e32 v176, vcc, s45, v154
	global_load_dwordx4 v[138:141], v[132:133], off offset:64
	global_load_dwordx4 v[134:137], v[132:133], off offset:512
	global_load_dwordx4 v[142:145], v[130:131], off
	s_nop 0
	global_load_dwordx4 v[130:133], v[132:133], off offset:576
	v_addc_co_u32_e32 v177, vcc, 0, v155, vcc
	v_add_co_u32_e32 v208, vcc, s19, v154
	global_load_dwordx4 v[160:163], v[154:155], off
	global_load_dwordx4 v[164:167], v[154:155], off offset:64
	global_load_dwordx4 v[168:171], v[154:155], off offset:512
	global_load_dwordx4 v[172:175], v[154:155], off offset:576
	v_addc_co_u32_e32 v209, vcc, 0, v155, vcc
	v_add_co_u32_e32 v246, vcc, s88, v154
	global_load_dwordx4 v[180:183], v[176:177], off
	global_load_dwordx4 v[184:187], v[176:177], off offset:64
	global_load_dwordx4 v[188:191], v[176:177], off offset:512
	global_load_dwordx4 v[192:195], v[176:177], off offset:576
	v_addc_co_u32_e32 v247, vcc, 0, v155, vcc
	global_load_dwordx4 v[196:199], v[208:209], off
	global_load_dwordx4 v[200:203], v[208:209], off offset:64
	global_load_dwordx4 v[204:207], v[208:209], off offset:512
	global_load_dwordx4 v[226:229], v[208:209], off offset:576
	global_load_dwordx4 v[230:233], v[246:247], off
	global_load_dwordx4 v[234:237], v[246:247], off offset:64
	global_load_dwordx4 v[238:241], v[246:247], off offset:512
	global_load_dwordx4 v[242:245], v[246:247], off offset:576
	s_mov_b64 s[8:9], 0x30000
	v_lshl_add_u64 v[248:249], v[154:155], 0, s[84:85]
	v_lshl_add_u64 v[250:251], v[154:155], 0, s[82:83]
	v_lshl_add_u64 v[252:253], v[154:155], 0, s[8:9]
	s_waitcnt vmcnt(0)
;     __device__ __forceinline__ void operator()(const AccT& acc, const Unit& u, int wr, int wc, int fr, int fq) const {
;     ...
;         for (int ai = 0; ai < 2; ++ai) {
;             f32x4 xo[4][2][2];
; #pragma unroll
;             for (int m = 0; m < 4; ++m)
; #pragma unroll
;                 for (int bj = 0; bj < 2; ++bj)
; #pragma unroll
;                     for (int n = 0; n < 2; ++n) xo[m][bj][n] = *(const f32x4*)(sbase + (size_t)(ai * 128 + m * 16) * 1024 + bj * 128 + n * 16);
;             __builtin_amdgcn_sched_barrier(0);
; #pragma unroll
;             for (int m = 0; m < 4; ++m) { float* rowp = X + (size_t)(row0 + ai * 128 + m * 16) * 1024 + col0;
; #pragma unroll
;                 for (int bj = 0; bj < 2; ++bj)
; #pragma unroll
;                     for (int n = 0; n < 2; ++n) *(f32x4*)(rowp + bj * 128 + n * 16) = xo[m][bj][n] + gv[bj][n] * acc[ai][bj][m][n]; }
	v_pk_fma_f32 v[108:109], v[108:109], v[132:133], v[174:175]
	v_pk_fma_f32 v[106:107], v[106:107], v[130:131], v[172:173]
	v_pk_fma_f32 v[92:93], v[92:93], v[132:133], v[194:195]
	v_pk_fma_f32 v[90:91], v[90:91], v[130:131], v[192:193]
	v_pk_fma_f32 v[76:77], v[76:77], v[132:133], v[228:229]
	v_pk_fma_f32 v[74:75], v[74:75], v[130:131], v[226:227]
	global_store_dwordx4 v[154:155], v[106:109], off offset:576
	global_store_dwordx4 v[248:249], v[90:93], off offset:576
	global_store_dwordx4 v[250:251], v[74:77], off offset:576
	v_pk_fma_f32 v[108:109], v[120:121], v[144:145], v[182:183]
	v_pk_fma_f32 v[106:107], v[118:119], v[142:143], v[180:181]
	v_pk_fma_f32 v[92:93], v[104:105], v[144:145], v[198:199]
	v_pk_fma_f32 v[90:91], v[102:103], v[142:143], v[196:197]
	v_pk_fma_f32 v[76:77], v[88:89], v[144:145], v[232:233]
	v_pk_fma_f32 v[74:75], v[86:87], v[142:143], v[230:231]
	v_pk_fma_f32 v[128:129], v[128:129], v[144:145], v[162:163]
	v_pk_fma_f32 v[126:127], v[126:127], v[142:143], v[160:161]
	v_pk_fma_f32 v[124:125], v[124:125], v[140:141], v[166:167]
	v_pk_fma_f32 v[122:123], v[122:123], v[138:139], v[164:165]
	v_pk_fma_f32 v[116:117], v[116:117], v[136:137], v[170:171]
	v_pk_fma_f32 v[114:115], v[114:115], v[134:135], v[168:169]
	global_store_dwordx4 v[176:177], v[106:109], off
	v_pk_fma_f32 v[100:101], v[100:101], v[136:137], v[190:191]
	v_pk_fma_f32 v[98:99], v[98:99], v[134:135], v[188:189]
	v_pk_fma_f32 v[108:109], v[112:113], v[140:141], v[186:187]
	v_pk_fma_f32 v[106:107], v[110:111], v[138:139], v[184:185]
	global_store_dwordx4 v[208:209], v[90:93], off
	v_pk_fma_f32 v[84:85], v[84:85], v[136:137], v[206:207]
	v_pk_fma_f32 v[82:83], v[82:83], v[134:135], v[204:205]
	v_pk_fma_f32 v[92:93], v[96:97], v[140:141], v[202:203]
	v_pk_fma_f32 v[90:91], v[94:95], v[138:139], v[200:201]
	global_store_dwordx4 v[246:247], v[74:77], off
	v_pk_fma_f32 v[72:73], v[72:73], v[136:137], v[240:241]
	v_pk_fma_f32 v[70:71], v[70:71], v[134:135], v[238:239]
	v_pk_fma_f32 v[76:77], v[80:81], v[140:141], v[236:237]
	v_pk_fma_f32 v[74:75], v[78:79], v[138:139], v[234:235]
	v_pk_fma_f32 v[68:69], v[68:69], v[132:133], v[244:245]
	v_pk_fma_f32 v[66:67], v[66:67], v[130:131], v[242:243]
	global_store_dwordx4 v[154:155], v[126:129], off
	global_store_dwordx4 v[154:155], v[122:125], off offset:64
	global_store_dwordx4 v[154:155], v[114:117], off offset:512
	global_store_dwordx4 v[248:249], v[106:109], off offset:64
	global_store_dwordx4 v[248:249], v[98:101], off offset:512
	global_store_dwordx4 v[250:251], v[90:93], off offset:64
	global_store_dwordx4 v[250:251], v[82:85], off offset:512
	global_store_dwordx4 v[252:253], v[74:77], off offset:64
	global_store_dwordx4 v[252:253], v[70:73], off offset:512
	global_store_dwordx4 v[252:253], v[66:69], off offset:576
	s_mov_b64 s[8:9], 0x80000
	v_lshl_add_u64 v[160:161], v[154:155], 0, s[8:9]
	s_mov_b32 s8, 0x80000
	v_add_co_u32_e32 v162, vcc, s8, v154
	s_mov_b64 s[8:9], 0x90000
	s_nop 0
	v_addc_co_u32_e32 v163, vcc, 0, v155, vcc
	v_lshl_add_u64 v[164:165], v[154:155], 0, s[8:9]
	s_mov_b32 s8, 0x90000
	v_add_co_u32_e32 v166, vcc, s8, v154
	s_mov_b64 s[8:9], 0xa0000
	s_nop 0
	v_addc_co_u32_e32 v167, vcc, 0, v155, vcc
	v_lshl_add_u64 v[168:169], v[154:155], 0, s[8:9]
	s_mov_b32 s8, 0xa0000
	v_add_co_u32_e32 v170, vcc, s8, v154
	s_mov_b64 s[8:9], 0xb0000
	s_nop 0
	v_addc_co_u32_e32 v171, vcc, 0, v155, vcc
	v_lshl_add_u64 v[172:173], v[154:155], 0, s[8:9]
	s_mov_b32 s8, 0xb0000
	v_add_co_u32_e32 v154, vcc, s8, v154
	global_load_dwordx4 v[66:69], v[162:163], off
	global_load_dwordx4 v[70:73], v[162:163], off offset:64
	global_load_dwordx4 v[74:77], v[162:163], off offset:512
	global_load_dwordx4 v[78:81], v[162:163], off offset:576
	v_addc_co_u32_e32 v155, vcc, 0, v155, vcc
	global_load_dwordx4 v[82:85], v[166:167], off
	global_load_dwordx4 v[86:89], v[166:167], off offset:64
	global_load_dwordx4 v[90:93], v[166:167], off offset:512
	global_load_dwordx4 v[94:97], v[166:167], off offset:576
	global_load_dwordx4 v[98:101], v[170:171], off
	global_load_dwordx4 v[102:105], v[170:171], off offset:64
	global_load_dwordx4 v[106:109], v[170:171], off offset:512
	global_load_dwordx4 v[110:113], v[170:171], off offset:576
	global_load_dwordx4 v[114:117], v[154:155], off
	global_load_dwordx4 v[118:121], v[154:155], off offset:64
	global_load_dwordx4 v[122:125], v[154:155], off offset:512
	global_load_dwordx4 v[126:129], v[154:155], off offset:576
	s_waitcnt vmcnt(0)
; #define PG8_WAIT_V(n) asm volatile("s_waitcnt vmcnt(" #n ")" ::: "memory")
; #define PG8_BAR __builtin_amdgcn_s_barrier()
; template <class Epi>
; __device__ __forceinline__ void gemm_phase(LAS unsigned char* lds, const Gemm g, const Epi& E) {
;     ...
;         if (!has_next) break;
; #pragma unroll
;         for (int a = 0; a < 2; ++a)
; #pragma unroll
;             for (int b = 0; b < 2; ++b)
; #pragma unroll
;                 for (int m = 0; m < 4; ++m)
; #pragma unroll
;                     for (int n = 0; n < 2; ++n) acc[a][b][m][n] = (f32x4){0.f, 0.f, 0.f, 0.f};
;         cur = nxt; cA = nA; cB = nB; ++ui;
;     }
;     PG8_WAIT_V(0);
;     if (wr == 0) PG8_BAR;
;     __device__ __forceinline__ void operator()(const AccT& acc, const Unit& u, int wr, int wc, int fr, int fq) const {
;     ...
;                     for (int n = 0; n < 2; ++n) xo[m][bj][n] = *(const f32x4*)(sbase + (size_t)(ai * 128 + m * 16) * 1024 + bj * 128 + n * 16);
;             __builtin_amdgcn_sched_barrier(0);
; #pragma unroll
;             for (int m = 0; m < 4; ++m) { float* rowp = X + (size_t)(row0 + ai * 128 + m * 16) * 1024 + col0;
; #pragma unroll
;                 for (int bj = 0; bj < 2; ++bj)
; #pragma unroll
;                     for (int n = 0; n < 2; ++n) *(f32x4*)(rowp + bj * 128 + n * 16) = xo[m][bj][n] + gv[bj][n] * acc[ai][bj][m][n]; }
	v_pk_fma_f32 v[44:45], v[44:45], v[132:133], v[80:81]
	v_pk_fma_f32 v[42:43], v[42:43], v[130:131], v[78:79]
	v_pk_fma_f32 v[28:29], v[28:29], v[132:133], v[96:97]
	v_pk_fma_f32 v[26:27], v[26:27], v[130:131], v[94:95]
	v_pk_fma_f32 v[12:13], v[12:13], v[132:133], v[112:113]
	v_pk_fma_f32 v[10:11], v[10:11], v[130:131], v[110:111]
	global_store_dwordx4 v[160:161], v[42:45], off offset:576
	global_store_dwordx4 v[164:165], v[26:29], off offset:576
	global_store_dwordx4 v[168:169], v[10:13], off offset:576
	v_pk_fma_f32 v[44:45], v[56:57], v[144:145], v[84:85]
	v_pk_fma_f32 v[42:43], v[54:55], v[142:143], v[82:83]
	v_pk_fma_f32 v[28:29], v[40:41], v[144:145], v[100:101]
	v_pk_fma_f32 v[26:27], v[38:39], v[142:143], v[98:99]
	v_pk_fma_f32 v[12:13], v[24:25], v[144:145], v[116:117]
	v_pk_fma_f32 v[10:11], v[22:23], v[142:143], v[114:115]
	v_pk_fma_f32 v[64:65], v[64:65], v[144:145], v[68:69]
	v_pk_fma_f32 v[62:63], v[62:63], v[142:143], v[66:67]
	v_pk_fma_f32 v[60:61], v[60:61], v[140:141], v[72:73]
	v_pk_fma_f32 v[58:59], v[58:59], v[138:139], v[70:71]
	v_pk_fma_f32 v[52:53], v[52:53], v[136:137], v[76:77]
	v_pk_fma_f32 v[50:51], v[50:51], v[134:135], v[74:75]
	global_store_dwordx4 v[166:167], v[42:45], off
	v_pk_fma_f32 v[36:37], v[36:37], v[136:137], v[92:93]
	v_pk_fma_f32 v[34:35], v[34:35], v[134:135], v[90:91]
	v_pk_fma_f32 v[44:45], v[48:49], v[140:141], v[88:89]
	v_pk_fma_f32 v[42:43], v[46:47], v[138:139], v[86:87]
	global_store_dwordx4 v[170:171], v[26:29], off
	v_pk_fma_f32 v[20:21], v[20:21], v[136:137], v[108:109]
	v_pk_fma_f32 v[18:19], v[18:19], v[134:135], v[106:107]
	v_pk_fma_f32 v[28:29], v[32:33], v[140:141], v[104:105]
	v_pk_fma_f32 v[26:27], v[30:31], v[138:139], v[102:103]
	global_store_dwordx4 v[154:155], v[10:13], off
	v_pk_fma_f32 v[8:9], v[8:9], v[136:137], v[124:125]
	v_pk_fma_f32 v[6:7], v[6:7], v[134:135], v[122:123]
	v_pk_fma_f32 v[12:13], v[16:17], v[140:141], v[120:121]
	v_pk_fma_f32 v[10:11], v[14:15], v[138:139], v[118:119]
	v_pk_fma_f32 v[4:5], v[4:5], v[132:133], v[128:129]
	v_pk_fma_f32 v[2:3], v[2:3], v[130:131], v[126:127]
	global_store_dwordx4 v[162:163], v[62:65], off
	global_store_dwordx4 v[160:161], v[58:61], off offset:64
	global_store_dwordx4 v[160:161], v[50:53], off offset:512
	global_store_dwordx4 v[164:165], v[42:45], off offset:64
	global_store_dwordx4 v[164:165], v[34:37], off offset:512
	global_store_dwordx4 v[168:169], v[26:29], off offset:64
	global_store_dwordx4 v[168:169], v[18:21], off offset:512
	global_store_dwordx4 v[172:173], v[10:13], off offset:64
	global_store_dwordx4 v[172:173], v[6:9], off offset:512
	global_store_dwordx4 v[172:173], v[2:5], off offset:576
	s_and_b64 vcc, exec, s[2:3]
	s_mov_b32 s61, s59
	s_mov_b32 s64, s60
	s_mov_b64 s[10:11], s[6:7]
	s_mov_b64 s[8:9], s[4:5]
	s_cbranch_vccz .LBB0_540
	s_waitcnt vmcnt(0)
	s_cmpk_gt_u32 s1, 0xff
	s_movk_i32 s36, 0xf000
	s_cbranch_scc1 .LBB0_551
	s_barrier
